# epilogues: f32 division expansion (div_scale/div_fmas/div_fixup chains) replaced by v_rcp_f32 + mul (650 sites), hazards re-padded
# speedup vs baseline: 1.0403x; 1.0084x over previous
.LBB0_14:
	s_andn2_saveexec_b64 s[4:5], s[4:5]
	s_cbranch_execz .LBB0_26
	v_add_u32_e32 v19, 0xffffff40, v1
	v_lshl_or_b32 v2, v19, 8, v5
	v_lshrrev_b32_e32 v21, 3, v19
	v_bfe_u32 v23, v2, 5, 6
	v_cndmask_b32_e64 v21, v23, v21, s[0:1]
	v_cvt_f32_u32_e32 v21, v21
	v_cmp_gt_u32_e32 vcc, 8, v19
	v_mul_f32_e32 v21, v50, v21
	v_cvt_f64_f32_e32 v[36:37], v21
	v_mul_f64 v[38:39], v[36:37], s[22:23]
	v_rndne_f64_e32 v[38:39], v[38:39]
	v_fmac_f64_e32 v[36:37], s[24:25], v[38:39]
	v_cvt_f32_f64_e32 v21, v[36:37]
	v_mul_f32_e32 v21, 0.15915494, v21
	v_cos_f32_e32 v36, v21
	v_sin_f32_e32 v37, v21
	v_lshl_add_u64 v[38:39], v[2:3], 3, s[16:17]
	global_store_dwordx2 v[38:39], v[36:37], off
	s_and_saveexec_b64 s[6:7], vcc
	s_cbranch_execz .LBB0_17
	v_lshlrev_b32_e32 v19, 12, v19
	v_and_b32_e32 v36, 0x4000, v19
	v_mov_b32_e32 v37, v3
	v_and_b32_e32 v19, 0x3ff, v2
	v_lshl_add_u64 v[36:37], s[90:91], 0, v[36:37]
	v_lshlrev_b32_e32 v38, 2, v19
	v_mov_b32_e32 v39, v3
	v_lshl_add_u64 v[36:37], v[36:37], 0, v[38:39]
	v_add_co_u32_e32 v38, vcc, 0x1000, v36
	s_nop 1
	v_addc_co_u32_e32 v39, vcc, 0, v37, vcc
	v_add_co_u32_e32 v40, vcc, 0x2000, v36
	s_nop 1
	v_addc_co_u32_e32 v41, vcc, 0, v37, vcc
	v_add_co_u32_e32 v42, vcc, 0x3000, v36
	s_nop 1
	v_addc_co_u32_e32 v43, vcc, 0, v37, vcc
	global_load_dword v19, v[40:41], off
	global_load_dword v21, v[42:43], off
	global_load_dword v23, v[36:37], off
	global_load_dword v25, v[38:39], off
	s_waitcnt vmcnt(3)
	v_max_f32_e32 v27, v19, v19
	s_waitcnt vmcnt(2)
	v_max_f32_e32 v29, v21, v21
	v_max_f32_e32 v27, v27, v29
	s_waitcnt vmcnt(0)
	v_max3_f32 v27, v23, v25, v27
	v_sub_f32_e32 v23, v23, v27
	v_sub_f32_e32 v25, v25, v27
	v_sub_f32_e32 v19, v19, v27
	v_sub_f32_e32 v21, v21, v27
	v_mul_f32_e32 v27, 0x3fb8aa3b, v23
	v_mul_f32_e32 v29, 0x3fb8aa3b, v25
	v_fma_f32 v35, v23, s39, -v27
	v_rndne_f32_e32 v36, v27
	v_mul_f32_e32 v31, 0x3fb8aa3b, v19
	v_fma_f32 v37, v25, s39, -v29
	v_rndne_f32_e32 v38, v29
	v_fmac_f32_e32 v35, 0x32a5705f, v23
	v_sub_f32_e32 v27, v27, v36
	v_mul_f32_e32 v33, 0x3fb8aa3b, v21
	v_fma_f32 v39, v19, s39, -v31
	v_rndne_f32_e32 v40, v31
	v_fmac_f32_e32 v37, 0x32a5705f, v25
	v_sub_f32_e32 v29, v29, v38
	v_add_f32_e32 v27, v27, v35
	v_fma_f32 v41, v21, s39, -v33
	v_rndne_f32_e32 v42, v33
	v_cvt_i32_f32_e32 v36, v36
	v_fmac_f32_e32 v39, 0x32a5705f, v19
	v_sub_f32_e32 v31, v31, v40
	v_add_f32_e32 v29, v29, v37
	v_exp_f32_e32 v27, v27
	v_cvt_i32_f32_e32 v38, v38
	v_fmac_f32_e32 v41, 0x32a5705f, v21
	v_sub_f32_e32 v33, v33, v42
	v_add_f32_e32 v31, v31, v39
	v_exp_f32_e32 v29, v29
	v_cvt_i32_f32_e32 v40, v40
	v_add_f32_e32 v33, v33, v41
	v_exp_f32_e32 v31, v31
	v_cvt_i32_f32_e32 v42, v42
	v_exp_f32_e32 v33, v33
	v_ldexp_f32 v27, v27, v36
	v_cmp_ngt_f32_e32 vcc, s40, v23
	v_ldexp_f32 v29, v29, v38
	v_ldexp_f32 v31, v31, v40
	v_cndmask_b32_e32 v27, 0, v27, vcc
	v_cmp_ngt_f32_e32 vcc, s40, v25
	v_ldexp_f32 v33, v33, v42
	s_nop 0
	v_cndmask_b32_e32 v29, 0, v29, vcc
	v_cmp_ngt_f32_e32 vcc, s40, v19
	s_nop 1
	v_cndmask_b32_e32 v31, 0, v31, vcc
	v_cmp_ngt_f32_e32 vcc, s40, v21
	s_nop 1
	v_cndmask_b32_e32 v33, 0, v33, vcc
	v_cmp_nlt_f32_e32 vcc, s41, v23
	s_nop 1
	v_cndmask_b32_e32 v23, v64, v27, vcc
	v_cmp_nlt_f32_e32 vcc, s41, v25
	s_nop 1
	v_cndmask_b32_e32 v36, v64, v29, vcc
	v_cmp_nlt_f32_e32 vcc, s41, v19
	v_add_f32_e32 v19, v23, v36
	s_nop 0
	v_cndmask_b32_e32 v38, v64, v31, vcc
	v_cmp_nlt_f32_e32 vcc, s41, v21
	v_add_f32_e32 v39, v38, v19
	s_nop 0
	v_cndmask_b32_e32 v37, v64, v33, vcc
	v_pk_add_f32 v[36:37], v[36:37], v[38:39]
	s_nop 0
	v_rcp_f32_e32 v19, v37
	s_nop 0
	v_mul_f32_e32 v19, v36, v19
	v_lshl_add_u64 v[36:37], v[2:3], 2, s[18:19]
	global_store_dword v[36:37], v19, off

.LBB0_19:
	global_load_dword v2, v[10:11], off
	global_load_dword v21, v[10:11], off offset:1024
	global_load_dword v23, v[10:11], off offset:2048
	global_load_dword v25, v[12:13], off
	v_readlane_b32 s52, v241, 18
	s_mov_b64 s[30:31], 0
	v_mov_b32_e32 v19, v56
	v_readlane_b32 s64, v241, 30
	v_readlane_b32 s65, v241, 31
	v_readlane_b32 s53, v241, 19
	v_readlane_b32 s54, v241, 20
	v_readlane_b32 s55, v241, 21
	v_readlane_b32 s56, v241, 22
	v_readlane_b32 s57, v241, 23
	v_readlane_b32 s58, v241, 24
	v_readlane_b32 s59, v241, 25
	v_readlane_b32 s60, v241, 26
	v_readlane_b32 s61, v241, 27
	v_readlane_b32 s62, v241, 28
	v_readlane_b32 s63, v241, 29
	v_readlane_b32 s66, v241, 32
	v_readlane_b32 s67, v241, 33
	s_waitcnt vmcnt(3)
	v_mul_f32_e32 v27, 0xbfb8aa3b, v2
	s_waitcnt vmcnt(2)
	v_mul_f32_e32 v29, 0xbfb8aa3b, v21
	v_exp_f32_e32 v27, v27
	s_waitcnt vmcnt(1)
	v_mul_f32_e32 v31, 0xbfb8aa3b, v23
	v_exp_f32_e32 v29, v29
	s_waitcnt vmcnt(0)
	v_mul_f32_e32 v33, 0xbfb8aa3b, v25
	v_exp_f32_e32 v31, v31
	v_exp_f32_e32 v33, v33
	v_add_f32_e32 v27, 1.0, v27
	v_add_f32_e32 v29, 1.0, v29
	v_add_f32_e32 v31, 1.0, v31
	v_add_f32_e32 v33, 1.0, v33
	s_mov_b64 vcc, s[2:3]
	v_rcp_f32_e32 v35, v27
	s_nop 0
	v_mul_f32_e32 v2, v2, v35
	s_mov_b64 vcc, s[4:5]
	v_rcp_f32_e32 v27, v29
	s_nop 0
	v_mul_f32_e32 v21, v21, v27
	s_mov_b64 vcc, s[6:7]
	ds_write2st64_b32 v51, v2, v21 offset1:4
	v_rcp_f32_e32 v27, v31
	s_nop 0
	v_mul_f32_e32 v2, v23, v27
	ds_write_b32 v51, v2 offset:2048
	v_rcp_f32_e32 v21, v33
	s_nop 0
	v_mul_f32_e32 v2, v25, v21
	v_mov_b32_e32 v21, v55
	ds_write_b32 v52, v2
.LBB0_20:
	v_add_u32_e32 v2, 0x200, v19
	v_and_b32_e32 v2, 0x3fff, v2
	v_add_u32_e32 v2, 0xfffffc00, v2
	v_lshl_add_u64 v[36:37], v[2:3], 2, s[64:65]
	global_load_dword v2, v[36:37], off
	v_add_u32_e32 v19, 0x100, v19
	v_cmp_lt_u32_e32 vcc, s42, v19
	s_or_b64 s[30:31], vcc, s[30:31]
	s_waitcnt vmcnt(0)
	v_mul_f32_e32 v23, 0xbfb8aa3b, v2
	v_exp_f32_e32 v23, v23
	s_nop 0
	v_add_f32_e32 v23, 1.0, v23
	v_rcp_f32_e32 v25, v23
	s_nop 0
	v_mul_f32_e32 v2, v2, v25
	ds_write_b32 v21, v2
	v_add_u32_e32 v21, 0x400, v21
	s_andn2_b64 exec, exec, s[30:31]
	s_cbranch_execnz .LBB0_20
	s_or_b64 exec, exec, s[30:31]
	v_mul_hi_i32 v2, v1, s43
	v_lshrrev_b32_e32 v19, 31, v2
	v_ashrrev_i32_e32 v2, 3, v2
	v_add_u32_e32 v2, v2, v19
	v_mul_lo_u32 v19, v2, 48
	v_sub_u32_e32 v19, v1, v19
	v_lshlrev_b32_e32 v38, 6, v19
	v_ashrrev_i32_e32 v39, 31, v38
	v_lshlrev_b64 v[36:37], 2, v[38:39]
	v_mad_i64_i32 v[40:41], s[2:3], v2, s44, v[36:37]
	v_mov_b32_e32 v42, 0
	v_lshl_add_u64 v[40:41], v[14:15], 0, v[40:41]
	s_mov_b64 s[2:3], 0
	v_mov_b32_e32 v19, v57
	v_mov_b32_e32 v43, v42
	v_mov_b32_e32 v44, v42
	v_mov_b32_e32 v45, v42
	v_mov_b32_e32 v46, v42
	v_mov_b32_e32 v47, v42
	v_mov_b32_e32 v48, v42
	v_mov_b32_e32 v49, v42
	v_mov_b32_e32 v21, v42
	s_waitcnt lgkmcnt(0)
	s_barrier

.LBB0_78:
	v_add_u32_e32 v128, s16, v157
	v_or_b32_e32 v144, v128, v154
	v_ashrrev_i32_e32 v145, 31, v144
	v_or_b32_e32 v142, s58, v159
	v_lshlrev_b64 v[146:147], 11, v[144:145]
	v_cmp_gt_i32_e64 s[10:11], s34, v144
	v_cmp_lt_i32_e64 s[12:13], s35, v144
	v_cmp_lt_i32_e64 s[2:3], s87, v142
	s_and_saveexec_b64 s[4:5], s[2:3]
	s_xor_b64 s[4:5], exec, s[4:5]
	s_cbranch_execz .LBB0_80
	v_mul_f32_e32 v139, 0xbfb8aa3b, v124
	v_exp_f32_e32 v148, v139
	v_mul_f32_e32 v139, 0xbfb8aa3b, v125
	v_exp_f32_e32 v149, v139
	s_nop 0
	v_pk_add_f32 v[148:149], v[148:149], 1.0 op_sel_hi:[1,0]
	s_nop 0
	s_nop 0
	v_rcp_f32_e32 v139, v149
	s_nop 0
	v_mul_f32_e32 v125, v125, v139
	s_nop 0
	v_rcp_f32_e32 v139, v148
	s_nop 0
	v_mul_f32_e32 v124, v124, v139
	v_cvt_pk_bf16_f32 v124, v124, v125
	v_mul_f32_e32 v125, 0xbfb8aa3b, v126
	v_exp_f32_e32 v148, v125
	v_mul_f32_e32 v125, 0xbfb8aa3b, v127
	v_exp_f32_e32 v149, v125
	s_nop 0
	v_pk_add_f32 v[148:149], v[148:149], 1.0 op_sel_hi:[1,0]
	s_nop 0
	s_nop 0
	v_rcp_f32_e32 v125, v149
	s_nop 0
	v_mul_f32_e32 v125, v127, v125
	s_nop 0
	v_rcp_f32_e32 v127, v148
	s_nop 0
	v_mul_f32_e32 v126, v126, v127
	v_cvt_pk_bf16_f32 v125, v126, v125
	v_lshl_add_u64 v[126:127], s[68:69], 0, v[146:147]
	v_mov_b32_e32 v143, v129
	v_lshl_add_u64 v[126:127], v[142:143], 1, v[126:127]
	v_add_co_u32_e32 v126, vcc, 0x9ffe000, v126
	s_nop 1
	v_addc_co_u32_e32 v127, vcc, 0, v127, vcc
	global_store_dwordx2 v[126:127], v[124:125], off offset:2048

.LBB0_92:
	s_or_b64 exec, exec, s[4:5]
	v_mul_hi_u32_u24_e32 v125, 0xa00, v139
	v_mul_u32_u24_e32 v124, 0xa00, v139
	v_or_b32_e32 v139, 16, v142
	v_cmp_lt_i32_e64 s[8:9], s87, v139
	s_and_saveexec_b64 s[4:5], s[8:9]
	s_xor_b64 s[4:5], exec, s[4:5]
	s_cbranch_execz .LBB0_94
	v_mul_f32_e32 v126, 0xbfb8aa3b, v120
	v_mul_f32_e32 v127, 0xbfb8aa3b, v121
	v_exp_f32_e32 v126, v126
	v_exp_f32_e32 v127, v127
	s_nop 0
	v_pk_add_f32 v[126:127], v[126:127], 1.0 op_sel_hi:[1,0]
	s_nop 0
	s_nop 0
	v_rcp_f32_e32 v128, v127
	s_nop 0
	v_mul_f32_e32 v121, v121, v128
	s_nop 0
	v_rcp_f32_e32 v127, v126
	s_nop 0
	v_mul_f32_e32 v120, v120, v127
	v_cvt_pk_bf16_f32 v120, v120, v121
	v_mul_f32_e32 v121, 0xbfb8aa3b, v122
	v_exp_f32_e32 v126, v121
	v_mul_f32_e32 v121, 0xbfb8aa3b, v123
	v_exp_f32_e32 v127, v121
	s_nop 0
	v_pk_add_f32 v[126:127], v[126:127], 1.0 op_sel_hi:[1,0]
	s_nop 0
	s_nop 0
	v_rcp_f32_e32 v121, v127
	s_nop 0
	v_mul_f32_e32 v121, v123, v121
	s_nop 0
	v_rcp_f32_e32 v123, v126
	s_nop 0
	v_mul_f32_e32 v122, v122, v123
	v_cvt_pk_bf16_f32 v121, v122, v121
	v_lshl_add_u64 v[122:123], s[68:69], 0, v[146:147]
	v_mov_b32_e32 v143, v129
	v_lshl_add_u64 v[122:123], v[142:143], 1, v[122:123]
	v_add_co_u32_e32 v122, vcc, 0x9ffe000, v122
	s_nop 1
	v_addc_co_u32_e32 v123, vcc, 0, v123, vcc
	global_store_dwordx2 v[122:123], v[120:121], off offset:2080

.LBB0_106:
	s_or_b64 exec, exec, s[4:5]
	v_or_b32_e32 v122, 32, v142
	v_cmp_lt_i32_e64 s[6:7], s87, v122
	s_and_saveexec_b64 s[4:5], s[6:7]
	s_xor_b64 s[4:5], exec, s[4:5]
	s_cbranch_execz .LBB0_108
	v_mul_f32_e32 v120, 0xbfb8aa3b, v116
	v_mul_f32_e32 v121, 0xbfb8aa3b, v117
	v_exp_f32_e32 v120, v120
	v_exp_f32_e32 v121, v121
	s_nop 0
	v_pk_add_f32 v[120:121], v[120:121], 1.0 op_sel_hi:[1,0]
	s_nop 0
	s_nop 0
	v_rcp_f32_e32 v123, v121
	s_nop 0
	v_mul_f32_e32 v117, v117, v123
	v_mov_b32_e32 v143, v129
	v_rcp_f32_e32 v121, v120
	s_nop 0
	v_mul_f32_e32 v116, v116, v121
	v_cvt_pk_bf16_f32 v116, v116, v117
	v_mul_f32_e32 v117, 0xbfb8aa3b, v118
	v_exp_f32_e32 v120, v117
	v_mul_f32_e32 v117, 0xbfb8aa3b, v119
	v_exp_f32_e32 v121, v117
	s_nop 0
	v_pk_add_f32 v[120:121], v[120:121], 1.0 op_sel_hi:[1,0]
	s_nop 0
	s_nop 0
	v_rcp_f32_e32 v117, v121
	s_nop 0
	v_mul_f32_e32 v117, v119, v117
	s_nop 0
	v_rcp_f32_e32 v119, v120
	s_nop 0
	v_mul_f32_e32 v118, v118, v119
	v_cvt_pk_bf16_f32 v117, v118, v117
	v_lshl_add_u64 v[118:119], s[68:69], 0, v[146:147]
	v_lshl_add_u64 v[118:119], v[142:143], 1, v[118:119]
	v_add_co_u32_e32 v118, vcc, 0x9ffe000, v118
	s_nop 1
	v_addc_co_u32_e32 v119, vcc, 0, v119, vcc
	global_store_dwordx2 v[118:119], v[116:117], off offset:2112

.LBB0_120:
	s_or_b64 exec, exec, s[4:5]
	v_or_b32_e32 v120, 48, v142
	v_cmp_lt_i32_e64 s[4:5], s87, v120
	s_and_saveexec_b64 s[30:31], s[4:5]
	s_xor_b64 s[72:73], exec, s[30:31]
	s_cbranch_execz .LBB0_122
	v_mul_f32_e32 v116, 0xbfb8aa3b, v112
	v_mul_f32_e32 v117, 0xbfb8aa3b, v113
	v_exp_f32_e32 v116, v116
	v_exp_f32_e32 v117, v117
	v_mov_b32_e32 v143, v129
	v_pk_add_f32 v[116:117], v[116:117], 1.0 op_sel_hi:[1,0]
	s_nop 0
	s_nop 0
	v_rcp_f32_e32 v118, v117
	s_nop 0
	v_mul_f32_e32 v113, v113, v118
	s_nop 0
	v_rcp_f32_e32 v117, v116
	s_nop 0
	v_mul_f32_e32 v112, v112, v117
	v_cvt_pk_bf16_f32 v112, v112, v113
	v_mul_f32_e32 v113, 0xbfb8aa3b, v114
	v_exp_f32_e32 v116, v113
	v_mul_f32_e32 v113, 0xbfb8aa3b, v115
	v_exp_f32_e32 v117, v113
	s_nop 0
	v_pk_add_f32 v[116:117], v[116:117], 1.0 op_sel_hi:[1,0]
	s_nop 0
	s_nop 0
	v_rcp_f32_e32 v113, v117
	s_nop 0
	v_mul_f32_e32 v113, v115, v113
	s_nop 0
	v_rcp_f32_e32 v115, v116
	s_nop 0
	v_mul_f32_e32 v114, v114, v115
	v_cvt_pk_bf16_f32 v113, v114, v113
	v_lshl_add_u64 v[114:115], s[68:69], 0, v[146:147]
	v_lshl_add_u64 v[114:115], v[142:143], 1, v[114:115]
	v_add_co_u32_e32 v114, vcc, 0x9ffe000, v114
	s_nop 1
	v_addc_co_u32_e32 v115, vcc, 0, v115, vcc
	global_store_dwordx2 v[114:115], v[112:113], off offset:2144

.LBB0_134:
	s_or_b64 exec, exec, s[72:73]
	v_or_b32_e32 v114, 16, v144
	v_ashrrev_i32_e32 v115, 31, v114
	v_lshlrev_b64 v[112:113], 11, v[114:115]
	v_cmp_gt_i32_e64 s[10:11], s34, v114
	v_cmp_lt_i32_e64 s[12:13], s35, v114
	s_and_saveexec_b64 s[30:31], s[2:3]
	s_xor_b64 s[72:73], exec, s[30:31]
	s_cbranch_execz .LBB0_136
	v_mul_f32_e32 v114, 0xbfb8aa3b, v108
	v_mul_f32_e32 v115, 0xbfb8aa3b, v109
	v_exp_f32_e32 v114, v114
	v_exp_f32_e32 v115, v115
	v_mov_b32_e32 v143, v129
	v_pk_add_f32 v[114:115], v[114:115], 1.0 op_sel_hi:[1,0]
	s_nop 0
	s_nop 0
	v_rcp_f32_e32 v116, v115
	s_nop 0
	v_mul_f32_e32 v109, v109, v116
	s_nop 0
	v_rcp_f32_e32 v115, v114
	s_nop 0
	v_mul_f32_e32 v108, v108, v115
	v_cvt_pk_bf16_f32 v108, v108, v109
	v_mul_f32_e32 v109, 0xbfb8aa3b, v110
	v_exp_f32_e32 v114, v109
	v_mul_f32_e32 v109, 0xbfb8aa3b, v111
	v_exp_f32_e32 v115, v109
	s_nop 0
	v_pk_add_f32 v[114:115], v[114:115], 1.0 op_sel_hi:[1,0]
	s_nop 0
	s_nop 0
	v_rcp_f32_e32 v109, v115
	s_nop 0
	v_mul_f32_e32 v109, v111, v109
	s_nop 0
	v_rcp_f32_e32 v111, v114
	s_nop 0
	v_mul_f32_e32 v110, v110, v111
	v_cvt_pk_bf16_f32 v109, v110, v109
	v_lshl_add_u64 v[110:111], s[68:69], 0, v[112:113]
	v_lshl_add_u64 v[110:111], v[142:143], 1, v[110:111]
	v_add_co_u32_e32 v110, vcc, 0x9ffe000, v110
	s_nop 1
	v_addc_co_u32_e32 v111, vcc, 0, v111, vcc
	global_store_dwordx2 v[110:111], v[108:109], off offset:2048

.LBB0_154:
	v_mul_f32_e32 v108, 0xbfb8aa3b, v104
	v_mul_f32_e32 v109, 0xbfb8aa3b, v105
	v_exp_f32_e32 v108, v108
	v_exp_f32_e32 v109, v109
	v_mov_b32_e32 v143, v129
	v_pk_add_f32 v[108:109], v[108:109], 1.0 op_sel_hi:[1,0]
	s_nop 0
	s_nop 0
	v_rcp_f32_e32 v110, v109
	s_nop 0
	v_mul_f32_e32 v105, v105, v110
	s_nop 0
	v_rcp_f32_e32 v109, v108
	s_nop 0
	v_mul_f32_e32 v104, v104, v109
	v_cvt_pk_bf16_f32 v104, v104, v105
	v_mul_f32_e32 v105, 0xbfb8aa3b, v106
	v_exp_f32_e32 v108, v105
	v_mul_f32_e32 v105, 0xbfb8aa3b, v107
	v_exp_f32_e32 v109, v105
	s_nop 0
	v_pk_add_f32 v[108:109], v[108:109], 1.0 op_sel_hi:[1,0]
	s_nop 0
	s_nop 0
	v_rcp_f32_e32 v105, v109
	s_nop 0
	v_mul_f32_e32 v105, v107, v105
	s_nop 0
	v_rcp_f32_e32 v107, v108
	s_nop 0
	v_mul_f32_e32 v106, v106, v107
	v_cvt_pk_bf16_f32 v105, v106, v105
	v_lshl_add_u64 v[106:107], s[68:69], 0, v[112:113]
	v_lshl_add_u64 v[106:107], v[142:143], 1, v[106:107]
	v_add_co_u32_e32 v106, vcc, 0x9ffe000, v106
	s_nop 1
	v_addc_co_u32_e32 v107, vcc, 0, v107, vcc
	global_store_dwordx2 v[106:107], v[104:105], off offset:2080
	s_andn2_saveexec_b64 s[72:73], s[72:73]
	s_cbranch_execz .LBB0_139

.LBB0_166:
	v_mul_f32_e32 v104, 0xbfb8aa3b, v100
	v_mul_f32_e32 v105, 0xbfb8aa3b, v101
	v_exp_f32_e32 v104, v104
	v_exp_f32_e32 v105, v105
	v_mov_b32_e32 v143, v129
	v_pk_add_f32 v[104:105], v[104:105], 1.0 op_sel_hi:[1,0]
	s_nop 0
	s_nop 0
	v_rcp_f32_e32 v106, v105
	s_nop 0
	v_mul_f32_e32 v101, v101, v106
	s_nop 0
	v_rcp_f32_e32 v105, v104
	s_nop 0
	v_mul_f32_e32 v100, v100, v105
	v_cvt_pk_bf16_f32 v100, v100, v101
	v_mul_f32_e32 v101, 0xbfb8aa3b, v102
	v_exp_f32_e32 v104, v101
	v_mul_f32_e32 v101, 0xbfb8aa3b, v103
	v_exp_f32_e32 v105, v101
	s_nop 0
	v_pk_add_f32 v[104:105], v[104:105], 1.0 op_sel_hi:[1,0]
	s_nop 0
	s_nop 0
	v_rcp_f32_e32 v101, v105
	s_nop 0
	v_mul_f32_e32 v101, v103, v101
	s_nop 0
	v_rcp_f32_e32 v103, v104
	s_nop 0
	v_mul_f32_e32 v102, v102, v103
	v_cvt_pk_bf16_f32 v101, v102, v101
	v_lshl_add_u64 v[102:103], s[68:69], 0, v[112:113]
	v_lshl_add_u64 v[102:103], v[142:143], 1, v[102:103]
	v_add_co_u32_e32 v102, vcc, 0x9ffe000, v102
	s_nop 1
	v_addc_co_u32_e32 v103, vcc, 0, v103, vcc
	global_store_dwordx2 v[102:103], v[100:101], off offset:2112
	s_andn2_saveexec_b64 s[72:73], s[72:73]
	s_cbranch_execz .LBB0_141

.LBB0_178:
	v_mul_f32_e32 v100, 0xbfb8aa3b, v96
	v_mul_f32_e32 v101, 0xbfb8aa3b, v97
	v_exp_f32_e32 v100, v100
	v_exp_f32_e32 v101, v101
	v_mov_b32_e32 v143, v129
	v_pk_add_f32 v[100:101], v[100:101], 1.0 op_sel_hi:[1,0]
	s_nop 0
	s_nop 0
	v_rcp_f32_e32 v102, v101
	s_nop 0
	v_mul_f32_e32 v97, v97, v102
	s_nop 0
	v_rcp_f32_e32 v101, v100
	s_nop 0
	v_mul_f32_e32 v96, v96, v101
	v_cvt_pk_bf16_f32 v96, v96, v97
	v_mul_f32_e32 v97, 0xbfb8aa3b, v98
	v_exp_f32_e32 v100, v97
	v_mul_f32_e32 v97, 0xbfb8aa3b, v99
	v_exp_f32_e32 v101, v97
	s_nop 0
	v_pk_add_f32 v[100:101], v[100:101], 1.0 op_sel_hi:[1,0]
	s_nop 0
	s_nop 0
	v_rcp_f32_e32 v97, v101
	s_nop 0
	v_mul_f32_e32 v97, v99, v97
	s_nop 0
	v_rcp_f32_e32 v99, v100
	s_nop 0
	v_mul_f32_e32 v98, v98, v99
	v_cvt_pk_bf16_f32 v97, v98, v97
	v_lshl_add_u64 v[98:99], s[68:69], 0, v[112:113]
	v_lshl_add_u64 v[98:99], v[142:143], 1, v[98:99]
	v_add_co_u32_e32 v98, vcc, 0x9ffe000, v98
	s_nop 1
	v_addc_co_u32_e32 v99, vcc, 0, v99, vcc
	global_store_dwordx2 v[98:99], v[96:97], off offset:2144
	s_andn2_saveexec_b64 s[72:73], s[72:73]
	s_cbranch_execz .LBB0_190

.LBB0_190:
	s_or_b64 exec, exec, s[72:73]
	v_or_b32_e32 v98, 32, v144
	v_ashrrev_i32_e32 v99, 31, v98
	v_lshlrev_b64 v[96:97], 11, v[98:99]
	v_cmp_gt_i32_e64 s[10:11], s34, v98
	v_cmp_lt_i32_e64 s[12:13], s35, v98
	s_and_saveexec_b64 s[0:1], s[2:3]
	s_xor_b64 s[72:73], exec, s[0:1]
	s_cbranch_execz .LBB0_192
	v_mul_f32_e32 v98, 0xbfb8aa3b, v92
	v_mul_f32_e32 v99, 0xbfb8aa3b, v93
	v_exp_f32_e32 v98, v98
	v_exp_f32_e32 v99, v99
	v_mov_b32_e32 v143, v129
	v_pk_add_f32 v[98:99], v[98:99], 1.0 op_sel_hi:[1,0]
	s_nop 0
	s_nop 0
	v_rcp_f32_e32 v100, v99
	s_nop 0
	v_mul_f32_e32 v93, v93, v100
	s_nop 0
	v_rcp_f32_e32 v99, v98
	s_nop 0
	v_mul_f32_e32 v92, v92, v99
	v_cvt_pk_bf16_f32 v92, v92, v93
	v_mul_f32_e32 v93, 0xbfb8aa3b, v94
	v_exp_f32_e32 v98, v93
	v_mul_f32_e32 v93, 0xbfb8aa3b, v95
	v_exp_f32_e32 v99, v93
	s_nop 0
	v_pk_add_f32 v[98:99], v[98:99], 1.0 op_sel_hi:[1,0]
	s_nop 0
	s_nop 0
	v_rcp_f32_e32 v93, v99
	s_nop 0
	v_mul_f32_e32 v93, v95, v93
	s_nop 0
	v_rcp_f32_e32 v95, v98
	s_nop 0
	v_mul_f32_e32 v94, v94, v95
	v_cvt_pk_bf16_f32 v93, v94, v93
	v_lshl_add_u64 v[94:95], s[68:69], 0, v[96:97]
	v_lshl_add_u64 v[94:95], v[142:143], 1, v[94:95]
	v_add_co_u32_e32 v94, vcc, 0x9ffe000, v94
	s_nop 1
	v_addc_co_u32_e32 v95, vcc, 0, v95, vcc
	global_store_dwordx2 v[94:95], v[92:93], off offset:2048

.LBB0_210:
	v_mul_f32_e32 v92, 0xbfb8aa3b, v88
	v_mul_f32_e32 v93, 0xbfb8aa3b, v89
	v_exp_f32_e32 v92, v92
	v_exp_f32_e32 v93, v93
	v_mov_b32_e32 v143, v129
	v_pk_add_f32 v[92:93], v[92:93], 1.0 op_sel_hi:[1,0]
	s_nop 0
	s_nop 0
	v_rcp_f32_e32 v94, v93
	s_nop 0
	v_mul_f32_e32 v89, v89, v94
	s_nop 0
	v_rcp_f32_e32 v93, v92
	s_nop 0
	v_mul_f32_e32 v88, v88, v93
	v_cvt_pk_bf16_f32 v88, v88, v89
	v_mul_f32_e32 v89, 0xbfb8aa3b, v90
	v_exp_f32_e32 v92, v89
	v_mul_f32_e32 v89, 0xbfb8aa3b, v91
	v_exp_f32_e32 v93, v89
	s_nop 0
	v_pk_add_f32 v[92:93], v[92:93], 1.0 op_sel_hi:[1,0]
	s_nop 0
	s_nop 0
	v_rcp_f32_e32 v89, v93
	s_nop 0
	v_mul_f32_e32 v89, v91, v89
	s_nop 0
	v_rcp_f32_e32 v91, v92
	s_nop 0
	v_mul_f32_e32 v90, v90, v91
	v_cvt_pk_bf16_f32 v89, v90, v89
	v_lshl_add_u64 v[90:91], s[68:69], 0, v[96:97]
	v_lshl_add_u64 v[90:91], v[142:143], 1, v[90:91]
	v_add_co_u32_e32 v90, vcc, 0x9ffe000, v90
	s_nop 1
	v_addc_co_u32_e32 v91, vcc, 0, v91, vcc
	global_store_dwordx2 v[90:91], v[88:89], off offset:2080
	s_andn2_saveexec_b64 s[72:73], s[72:73]
	s_cbranch_execz .LBB0_195

.LBB0_222:
	v_mul_f32_e32 v88, 0xbfb8aa3b, v84
	v_mul_f32_e32 v89, 0xbfb8aa3b, v85
	v_exp_f32_e32 v88, v88
	v_exp_f32_e32 v89, v89
	v_mov_b32_e32 v143, v129
	v_pk_add_f32 v[88:89], v[88:89], 1.0 op_sel_hi:[1,0]
	s_nop 0
	s_nop 0
	v_rcp_f32_e32 v90, v89
	s_nop 0
	v_mul_f32_e32 v85, v85, v90
	s_nop 0
	v_rcp_f32_e32 v89, v88
	s_nop 0
	v_mul_f32_e32 v84, v84, v89
	v_cvt_pk_bf16_f32 v84, v84, v85
	v_mul_f32_e32 v85, 0xbfb8aa3b, v86
	v_exp_f32_e32 v88, v85
	v_mul_f32_e32 v85, 0xbfb8aa3b, v87
	v_exp_f32_e32 v89, v85
	s_nop 0
	v_pk_add_f32 v[88:89], v[88:89], 1.0 op_sel_hi:[1,0]
	s_nop 0
	s_nop 0
	v_rcp_f32_e32 v85, v89
	s_nop 0
	v_mul_f32_e32 v85, v87, v85
	s_nop 0
	v_rcp_f32_e32 v87, v88
	s_nop 0
	v_mul_f32_e32 v86, v86, v87
	v_cvt_pk_bf16_f32 v85, v86, v85
	v_lshl_add_u64 v[86:87], s[68:69], 0, v[96:97]
	v_lshl_add_u64 v[86:87], v[142:143], 1, v[86:87]
	v_add_co_u32_e32 v86, vcc, 0x9ffe000, v86
	s_nop 1
	v_addc_co_u32_e32 v87, vcc, 0, v87, vcc
	global_store_dwordx2 v[86:87], v[84:85], off offset:2112
	s_andn2_saveexec_b64 s[72:73], s[72:73]
	s_cbranch_execz .LBB0_197

.LBB0_234:
	v_mul_f32_e32 v84, 0xbfb8aa3b, v80
	v_mul_f32_e32 v85, 0xbfb8aa3b, v81
	v_exp_f32_e32 v84, v84
	v_exp_f32_e32 v85, v85
	v_mov_b32_e32 v143, v129
	v_pk_add_f32 v[84:85], v[84:85], 1.0 op_sel_hi:[1,0]
	s_nop 0
	s_nop 0
	v_rcp_f32_e32 v86, v85
	s_nop 0
	v_mul_f32_e32 v81, v81, v86
	s_nop 0
	v_rcp_f32_e32 v85, v84
	s_nop 0
	v_mul_f32_e32 v80, v80, v85
	v_cvt_pk_bf16_f32 v80, v80, v81
	v_mul_f32_e32 v81, 0xbfb8aa3b, v82
	v_exp_f32_e32 v84, v81
	v_mul_f32_e32 v81, 0xbfb8aa3b, v83
	v_exp_f32_e32 v85, v81
	s_nop 0
	v_pk_add_f32 v[84:85], v[84:85], 1.0 op_sel_hi:[1,0]
	s_nop 0
	s_nop 0
	v_rcp_f32_e32 v81, v85
	s_nop 0
	v_mul_f32_e32 v81, v83, v81
	s_nop 0
	v_rcp_f32_e32 v83, v84
	s_nop 0
	v_mul_f32_e32 v82, v82, v83
	v_cvt_pk_bf16_f32 v81, v82, v81
	v_lshl_add_u64 v[82:83], s[68:69], 0, v[96:97]
	v_lshl_add_u64 v[82:83], v[142:143], 1, v[82:83]
	v_add_co_u32_e32 v82, vcc, 0x9ffe000, v82
	s_nop 1
	v_addc_co_u32_e32 v83, vcc, 0, v83, vcc
	global_store_dwordx2 v[82:83], v[80:81], off offset:2144
	s_andn2_saveexec_b64 s[72:73], s[72:73]
	s_cbranch_execz .LBB0_246

.LBB0_246:
	s_or_b64 exec, exec, s[72:73]
	v_or_b32_e32 v82, 48, v144
	v_ashrrev_i32_e32 v83, 31, v82
	v_lshlrev_b64 v[80:81], 11, v[82:83]
	v_cmp_gt_i32_e64 s[10:11], s34, v82
	v_cmp_lt_i32_e64 s[12:13], s35, v82
	s_and_saveexec_b64 s[0:1], s[2:3]
	s_xor_b64 s[72:73], exec, s[0:1]
	s_cbranch_execz .LBB0_248
	v_mul_f32_e32 v82, 0xbfb8aa3b, v76
	v_mul_f32_e32 v83, 0xbfb8aa3b, v77
	v_exp_f32_e32 v82, v82
	v_exp_f32_e32 v83, v83
	v_mov_b32_e32 v143, v129
	v_pk_add_f32 v[82:83], v[82:83], 1.0 op_sel_hi:[1,0]
	s_nop 0
	s_nop 0
	v_rcp_f32_e32 v84, v83
	s_nop 0
	v_mul_f32_e32 v77, v77, v84
	s_nop 0
	v_rcp_f32_e32 v83, v82
	s_nop 0
	v_mul_f32_e32 v76, v76, v83
	v_cvt_pk_bf16_f32 v76, v76, v77
	v_mul_f32_e32 v77, 0xbfb8aa3b, v78
	v_exp_f32_e32 v82, v77
	v_mul_f32_e32 v77, 0xbfb8aa3b, v79
	v_exp_f32_e32 v83, v77
	s_nop 0
	v_pk_add_f32 v[82:83], v[82:83], 1.0 op_sel_hi:[1,0]
	s_nop 0
	s_nop 0
	v_rcp_f32_e32 v77, v83
	s_nop 0
	v_mul_f32_e32 v77, v79, v77
	s_nop 0
	v_rcp_f32_e32 v79, v82
	s_nop 0
	v_mul_f32_e32 v78, v78, v79
	v_cvt_pk_bf16_f32 v77, v78, v77
	v_lshl_add_u64 v[78:79], s[68:69], 0, v[80:81]
	v_lshl_add_u64 v[78:79], v[142:143], 1, v[78:79]
	v_add_co_u32_e32 v78, vcc, 0x9ffe000, v78
	s_nop 1
	v_addc_co_u32_e32 v79, vcc, 0, v79, vcc
	global_store_dwordx2 v[78:79], v[76:77], off offset:2048

.LBB0_266:
	v_mul_f32_e32 v76, 0xbfb8aa3b, v72
	v_mul_f32_e32 v77, 0xbfb8aa3b, v73
	v_exp_f32_e32 v76, v76
	v_exp_f32_e32 v77, v77
	v_mov_b32_e32 v143, v129
	v_pk_add_f32 v[76:77], v[76:77], 1.0 op_sel_hi:[1,0]
	s_nop 0
	s_nop 0
	v_rcp_f32_e32 v78, v77
	s_nop 0
	v_mul_f32_e32 v73, v73, v78
	s_nop 0
	v_rcp_f32_e32 v77, v76
	s_nop 0
	v_mul_f32_e32 v72, v72, v77
	v_cvt_pk_bf16_f32 v72, v72, v73
	v_mul_f32_e32 v73, 0xbfb8aa3b, v74
	v_exp_f32_e32 v76, v73
	v_mul_f32_e32 v73, 0xbfb8aa3b, v75
	v_exp_f32_e32 v77, v73
	s_nop 0
	v_pk_add_f32 v[76:77], v[76:77], 1.0 op_sel_hi:[1,0]
	s_nop 0
	s_nop 0
	v_rcp_f32_e32 v73, v77
	s_nop 0
	v_mul_f32_e32 v73, v75, v73
	s_nop 0
	v_rcp_f32_e32 v75, v76
	s_nop 0
	v_mul_f32_e32 v74, v74, v75
	v_cvt_pk_bf16_f32 v73, v74, v73
	v_lshl_add_u64 v[74:75], s[68:69], 0, v[80:81]
	v_lshl_add_u64 v[74:75], v[142:143], 1, v[74:75]
	v_add_co_u32_e32 v74, vcc, 0x9ffe000, v74
	s_nop 1
	v_addc_co_u32_e32 v75, vcc, 0, v75, vcc
	global_store_dwordx2 v[74:75], v[72:73], off offset:2080
	s_andn2_saveexec_b64 s[72:73], s[72:73]
	s_cbranch_execz .LBB0_251

.LBB0_278:
	v_mul_f32_e32 v72, 0xbfb8aa3b, v68
	v_mul_f32_e32 v73, 0xbfb8aa3b, v69
	v_exp_f32_e32 v72, v72
	v_exp_f32_e32 v73, v73
	v_mov_b32_e32 v143, v129
	v_pk_add_f32 v[72:73], v[72:73], 1.0 op_sel_hi:[1,0]
	s_nop 0
	s_nop 0
	v_rcp_f32_e32 v74, v73
	s_nop 0
	v_mul_f32_e32 v69, v69, v74
	s_nop 0
	v_rcp_f32_e32 v73, v72
	s_nop 0
	v_mul_f32_e32 v68, v68, v73
	v_cvt_pk_bf16_f32 v68, v68, v69
	v_mul_f32_e32 v69, 0xbfb8aa3b, v70
	v_exp_f32_e32 v72, v69
	v_mul_f32_e32 v69, 0xbfb8aa3b, v71
	v_exp_f32_e32 v73, v69
	s_nop 0
	v_pk_add_f32 v[72:73], v[72:73], 1.0 op_sel_hi:[1,0]
	s_nop 0
	s_nop 0
	v_rcp_f32_e32 v69, v73
	s_nop 0
	v_mul_f32_e32 v69, v71, v69
	s_nop 0
	v_rcp_f32_e32 v71, v72
	s_nop 0
	v_mul_f32_e32 v70, v70, v71
	v_cvt_pk_bf16_f32 v69, v70, v69
	v_lshl_add_u64 v[70:71], s[68:69], 0, v[80:81]
	v_lshl_add_u64 v[70:71], v[142:143], 1, v[70:71]
	v_add_co_u32_e32 v70, vcc, 0x9ffe000, v70
	s_nop 1
	v_addc_co_u32_e32 v71, vcc, 0, v71, vcc
	global_store_dwordx2 v[70:71], v[68:69], off offset:2112
	s_andn2_saveexec_b64 s[72:73], s[72:73]
	s_cbranch_execz .LBB0_253

.LBB0_290:
	v_mul_f32_e32 v68, 0xbfb8aa3b, v64
	v_mul_f32_e32 v69, 0xbfb8aa3b, v65
	v_exp_f32_e32 v68, v68
	v_exp_f32_e32 v69, v69
	v_mov_b32_e32 v143, v129
	v_pk_add_f32 v[68:69], v[68:69], 1.0 op_sel_hi:[1,0]
	s_nop 0
	s_nop 0
	v_rcp_f32_e32 v70, v69
	s_nop 0
	v_mul_f32_e32 v65, v65, v70
	s_nop 0
	v_rcp_f32_e32 v69, v68
	s_nop 0
	v_mul_f32_e32 v64, v64, v69
	v_cvt_pk_bf16_f32 v64, v64, v65
	v_mul_f32_e32 v65, 0xbfb8aa3b, v66
	v_exp_f32_e32 v68, v65
	v_mul_f32_e32 v65, 0xbfb8aa3b, v67
	v_exp_f32_e32 v69, v65
	s_nop 0
	v_pk_add_f32 v[68:69], v[68:69], 1.0 op_sel_hi:[1,0]
	s_nop 0
	s_nop 0
	v_rcp_f32_e32 v65, v69
	s_nop 0
	v_mul_f32_e32 v65, v67, v65
	s_nop 0
	v_rcp_f32_e32 v67, v68
	s_nop 0
	v_mul_f32_e32 v66, v66, v67
	v_cvt_pk_bf16_f32 v65, v66, v65
	v_lshl_add_u64 v[66:67], s[68:69], 0, v[80:81]
	v_lshl_add_u64 v[66:67], v[142:143], 1, v[66:67]
	v_add_co_u32_e32 v66, vcc, 0x9ffe000, v66
	s_nop 1
	v_addc_co_u32_e32 v67, vcc, 0, v67, vcc
	global_store_dwordx2 v[66:67], v[64:65], off offset:2144
	s_andn2_saveexec_b64 s[72:73], s[72:73]
	s_cbranch_execz .LBB0_302

.LBB0_302:
	s_or_b64 exec, exec, s[72:73]
	v_or_b32_e32 v66, 64, v144
	v_ashrrev_i32_e32 v67, 31, v66
	v_lshlrev_b64 v[64:65], 11, v[66:67]
	v_cmp_gt_i32_e64 s[10:11], s34, v66
	v_cmp_lt_i32_e64 s[12:13], s35, v66
	s_and_saveexec_b64 s[0:1], s[2:3]
	s_xor_b64 s[72:73], exec, s[0:1]
	s_cbranch_execz .LBB0_304
	v_mul_f32_e32 v66, 0xbfb8aa3b, v60
	v_mul_f32_e32 v67, 0xbfb8aa3b, v61
	v_exp_f32_e32 v66, v66
	v_exp_f32_e32 v67, v67
	v_mov_b32_e32 v143, v129
	v_pk_add_f32 v[66:67], v[66:67], 1.0 op_sel_hi:[1,0]
	s_nop 0
	s_nop 0
	v_rcp_f32_e32 v68, v67
	s_nop 0
	v_mul_f32_e32 v61, v61, v68
	s_nop 0
	v_rcp_f32_e32 v67, v66
	s_nop 0
	v_mul_f32_e32 v60, v60, v67
	v_cvt_pk_bf16_f32 v60, v60, v61
	v_mul_f32_e32 v61, 0xbfb8aa3b, v62
	v_exp_f32_e32 v66, v61
	v_mul_f32_e32 v61, 0xbfb8aa3b, v63
	v_exp_f32_e32 v67, v61
	s_nop 0
	v_pk_add_f32 v[66:67], v[66:67], 1.0 op_sel_hi:[1,0]
	s_nop 0
	s_nop 0
	v_rcp_f32_e32 v61, v67
	s_nop 0
	v_mul_f32_e32 v61, v63, v61
	s_nop 0
	v_rcp_f32_e32 v63, v66
	s_nop 0
	v_mul_f32_e32 v62, v62, v63
	v_cvt_pk_bf16_f32 v61, v62, v61
	v_lshl_add_u64 v[62:63], s[68:69], 0, v[64:65]
	v_lshl_add_u64 v[62:63], v[142:143], 1, v[62:63]
	v_add_co_u32_e32 v62, vcc, 0x9ffe000, v62
	s_nop 1
	v_addc_co_u32_e32 v63, vcc, 0, v63, vcc
	global_store_dwordx2 v[62:63], v[60:61], off offset:2048

.LBB0_322:
	v_mul_f32_e32 v60, 0xbfb8aa3b, v56
	v_mul_f32_e32 v61, 0xbfb8aa3b, v57
	v_exp_f32_e32 v60, v60
	v_exp_f32_e32 v61, v61
	v_mov_b32_e32 v143, v129
	v_pk_add_f32 v[60:61], v[60:61], 1.0 op_sel_hi:[1,0]
	s_nop 0
	s_nop 0
	v_rcp_f32_e32 v62, v61
	s_nop 0
	v_mul_f32_e32 v57, v57, v62
	s_nop 0
	v_rcp_f32_e32 v61, v60
	s_nop 0
	v_mul_f32_e32 v56, v56, v61
	v_cvt_pk_bf16_f32 v56, v56, v57
	v_mul_f32_e32 v57, 0xbfb8aa3b, v58
	v_exp_f32_e32 v60, v57
	v_mul_f32_e32 v57, 0xbfb8aa3b, v59
	v_exp_f32_e32 v61, v57
	s_nop 0
	v_pk_add_f32 v[60:61], v[60:61], 1.0 op_sel_hi:[1,0]
	s_nop 0
	s_nop 0
	v_rcp_f32_e32 v57, v61
	s_nop 0
	v_mul_f32_e32 v57, v59, v57
	s_nop 0
	v_rcp_f32_e32 v59, v60
	s_nop 0
	v_mul_f32_e32 v58, v58, v59
	v_cvt_pk_bf16_f32 v57, v58, v57
	v_lshl_add_u64 v[58:59], s[68:69], 0, v[64:65]
	v_lshl_add_u64 v[58:59], v[142:143], 1, v[58:59]
	v_add_co_u32_e32 v58, vcc, 0x9ffe000, v58
	s_nop 1
	v_addc_co_u32_e32 v59, vcc, 0, v59, vcc
	global_store_dwordx2 v[58:59], v[56:57], off offset:2080
	s_andn2_saveexec_b64 s[72:73], s[72:73]
	s_cbranch_execz .LBB0_307

.LBB0_334:
	v_mul_f32_e32 v56, 0xbfb8aa3b, v52
	v_mul_f32_e32 v57, 0xbfb8aa3b, v53
	v_exp_f32_e32 v56, v56
	v_exp_f32_e32 v57, v57
	v_mov_b32_e32 v143, v129
	v_pk_add_f32 v[56:57], v[56:57], 1.0 op_sel_hi:[1,0]
	s_nop 0
	s_nop 0
	v_rcp_f32_e32 v58, v57
	s_nop 0
	v_mul_f32_e32 v53, v53, v58
	s_nop 0
	v_rcp_f32_e32 v57, v56
	s_nop 0
	v_mul_f32_e32 v52, v52, v57
	v_cvt_pk_bf16_f32 v52, v52, v53
	v_mul_f32_e32 v53, 0xbfb8aa3b, v54
	v_exp_f32_e32 v56, v53
	v_mul_f32_e32 v53, 0xbfb8aa3b, v55
	v_exp_f32_e32 v57, v53
	s_nop 0
	v_pk_add_f32 v[56:57], v[56:57], 1.0 op_sel_hi:[1,0]
	s_nop 0
	s_nop 0
	v_rcp_f32_e32 v53, v57
	s_nop 0
	v_mul_f32_e32 v53, v55, v53
	s_nop 0
	v_rcp_f32_e32 v55, v56
	s_nop 0
	v_mul_f32_e32 v54, v54, v55
	v_cvt_pk_bf16_f32 v53, v54, v53
	v_lshl_add_u64 v[54:55], s[68:69], 0, v[64:65]
	v_lshl_add_u64 v[54:55], v[142:143], 1, v[54:55]
	v_add_co_u32_e32 v54, vcc, 0x9ffe000, v54
	s_nop 1
	v_addc_co_u32_e32 v55, vcc, 0, v55, vcc
	global_store_dwordx2 v[54:55], v[52:53], off offset:2112
	s_andn2_saveexec_b64 s[72:73], s[72:73]
	s_cbranch_execz .LBB0_309

.LBB0_346:
	v_mul_f32_e32 v52, 0xbfb8aa3b, v48
	v_mul_f32_e32 v53, 0xbfb8aa3b, v49
	v_exp_f32_e32 v52, v52
	v_exp_f32_e32 v53, v53
	v_mov_b32_e32 v143, v129
	v_pk_add_f32 v[52:53], v[52:53], 1.0 op_sel_hi:[1,0]
	s_nop 0
	s_nop 0
	v_rcp_f32_e32 v54, v53
	s_nop 0
	v_mul_f32_e32 v49, v49, v54
	s_nop 0
	v_rcp_f32_e32 v53, v52
	s_nop 0
	v_mul_f32_e32 v48, v48, v53
	v_cvt_pk_bf16_f32 v48, v48, v49
	v_mul_f32_e32 v49, 0xbfb8aa3b, v50
	v_exp_f32_e32 v52, v49
	v_mul_f32_e32 v49, 0xbfb8aa3b, v51
	v_exp_f32_e32 v53, v49
	s_nop 0
	v_pk_add_f32 v[52:53], v[52:53], 1.0 op_sel_hi:[1,0]
	s_nop 0
	s_nop 0
	v_rcp_f32_e32 v49, v53
	s_nop 0
	v_mul_f32_e32 v49, v51, v49
	s_nop 0
	v_rcp_f32_e32 v51, v52
	s_nop 0
	v_mul_f32_e32 v50, v50, v51
	v_cvt_pk_bf16_f32 v49, v50, v49
	v_lshl_add_u64 v[50:51], s[68:69], 0, v[64:65]
	v_lshl_add_u64 v[50:51], v[142:143], 1, v[50:51]
	v_add_co_u32_e32 v50, vcc, 0x9ffe000, v50
	s_nop 1
	v_addc_co_u32_e32 v51, vcc, 0, v51, vcc
	global_store_dwordx2 v[50:51], v[48:49], off offset:2144
	s_andn2_saveexec_b64 s[72:73], s[72:73]
	s_cbranch_execz .LBB0_358

.LBB0_358:
	s_or_b64 exec, exec, s[72:73]
	v_or_b32_e32 v50, 0x50, v144
	v_ashrrev_i32_e32 v51, 31, v50
	v_lshlrev_b64 v[48:49], 11, v[50:51]
	v_cmp_gt_i32_e64 s[10:11], s34, v50
	v_cmp_lt_i32_e64 s[12:13], s35, v50
	s_and_saveexec_b64 s[0:1], s[2:3]
	s_xor_b64 s[72:73], exec, s[0:1]
	s_cbranch_execz .LBB0_360
	v_mul_f32_e32 v50, 0xbfb8aa3b, v44
	v_mul_f32_e32 v51, 0xbfb8aa3b, v45
	v_exp_f32_e32 v50, v50
	v_exp_f32_e32 v51, v51
	v_mov_b32_e32 v143, v129
	v_pk_add_f32 v[50:51], v[50:51], 1.0 op_sel_hi:[1,0]
	s_nop 0
	s_nop 0
	v_rcp_f32_e32 v52, v51
	s_nop 0
	v_mul_f32_e32 v45, v45, v52
	s_nop 0
	v_rcp_f32_e32 v51, v50
	s_nop 0
	v_mul_f32_e32 v44, v44, v51
	v_cvt_pk_bf16_f32 v44, v44, v45
	v_mul_f32_e32 v45, 0xbfb8aa3b, v46
	v_exp_f32_e32 v50, v45
	v_mul_f32_e32 v45, 0xbfb8aa3b, v47
	v_exp_f32_e32 v51, v45
	s_nop 0
	v_pk_add_f32 v[50:51], v[50:51], 1.0 op_sel_hi:[1,0]
	s_nop 0
	s_nop 0
	v_rcp_f32_e32 v45, v51
	s_nop 0
	v_mul_f32_e32 v45, v47, v45
	s_nop 0
	v_rcp_f32_e32 v47, v50
	s_nop 0
	v_mul_f32_e32 v46, v46, v47
	v_cvt_pk_bf16_f32 v45, v46, v45
	v_lshl_add_u64 v[46:47], s[68:69], 0, v[48:49]
	v_lshl_add_u64 v[46:47], v[142:143], 1, v[46:47]
	v_add_co_u32_e32 v46, vcc, 0x9ffe000, v46
	s_nop 1
	v_addc_co_u32_e32 v47, vcc, 0, v47, vcc
	global_store_dwordx2 v[46:47], v[44:45], off offset:2048

.LBB0_378:
	v_mul_f32_e32 v44, 0xbfb8aa3b, v40
	v_mul_f32_e32 v45, 0xbfb8aa3b, v41
	v_exp_f32_e32 v44, v44
	v_exp_f32_e32 v45, v45
	v_mov_b32_e32 v143, v129
	v_pk_add_f32 v[44:45], v[44:45], 1.0 op_sel_hi:[1,0]
	s_nop 0
	s_nop 0
	v_rcp_f32_e32 v46, v45
	s_nop 0
	v_mul_f32_e32 v41, v41, v46
	s_nop 0
	v_rcp_f32_e32 v45, v44
	s_nop 0
	v_mul_f32_e32 v40, v40, v45
	v_cvt_pk_bf16_f32 v40, v40, v41
	v_mul_f32_e32 v41, 0xbfb8aa3b, v42
	v_exp_f32_e32 v44, v41
	v_mul_f32_e32 v41, 0xbfb8aa3b, v43
	v_exp_f32_e32 v45, v41
	s_nop 0
	v_pk_add_f32 v[44:45], v[44:45], 1.0 op_sel_hi:[1,0]
	s_nop 0
	s_nop 0
	v_rcp_f32_e32 v41, v45
	s_nop 0
	v_mul_f32_e32 v41, v43, v41
	s_nop 0
	v_rcp_f32_e32 v43, v44
	s_nop 0
	v_mul_f32_e32 v42, v42, v43
	v_cvt_pk_bf16_f32 v41, v42, v41
	v_lshl_add_u64 v[42:43], s[68:69], 0, v[48:49]
	v_lshl_add_u64 v[42:43], v[142:143], 1, v[42:43]
	v_add_co_u32_e32 v42, vcc, 0x9ffe000, v42
	s_nop 1
	v_addc_co_u32_e32 v43, vcc, 0, v43, vcc
	global_store_dwordx2 v[42:43], v[40:41], off offset:2080
	s_andn2_saveexec_b64 s[72:73], s[72:73]
	s_cbranch_execz .LBB0_363

.LBB0_390:
	v_mul_f32_e32 v40, 0xbfb8aa3b, v36
	v_mul_f32_e32 v41, 0xbfb8aa3b, v37
	v_exp_f32_e32 v40, v40
	v_exp_f32_e32 v41, v41
	v_mov_b32_e32 v143, v129
	v_pk_add_f32 v[40:41], v[40:41], 1.0 op_sel_hi:[1,0]
	s_nop 0
	s_nop 0
	v_rcp_f32_e32 v42, v41
	s_nop 0
	v_mul_f32_e32 v37, v37, v42
	s_nop 0
	v_rcp_f32_e32 v41, v40
	s_nop 0
	v_mul_f32_e32 v36, v36, v41
	v_cvt_pk_bf16_f32 v36, v36, v37
	v_mul_f32_e32 v37, 0xbfb8aa3b, v38
	v_exp_f32_e32 v40, v37
	v_mul_f32_e32 v37, 0xbfb8aa3b, v39
	v_exp_f32_e32 v41, v37
	s_nop 0
	v_pk_add_f32 v[40:41], v[40:41], 1.0 op_sel_hi:[1,0]
	s_nop 0
	s_nop 0
	v_rcp_f32_e32 v37, v41
	s_nop 0
	v_mul_f32_e32 v37, v39, v37
	s_nop 0
	v_rcp_f32_e32 v39, v40
	s_nop 0
	v_mul_f32_e32 v38, v38, v39
	v_cvt_pk_bf16_f32 v37, v38, v37
	v_lshl_add_u64 v[38:39], s[68:69], 0, v[48:49]
	v_lshl_add_u64 v[38:39], v[142:143], 1, v[38:39]
	v_add_co_u32_e32 v38, vcc, 0x9ffe000, v38
	s_nop 1
	v_addc_co_u32_e32 v39, vcc, 0, v39, vcc
	global_store_dwordx2 v[38:39], v[36:37], off offset:2112
	s_andn2_saveexec_b64 s[72:73], s[72:73]
	s_cbranch_execz .LBB0_365

.LBB0_402:
	v_mul_f32_e32 v36, 0xbfb8aa3b, v32
	v_mul_f32_e32 v37, 0xbfb8aa3b, v33
	v_exp_f32_e32 v36, v36
	v_exp_f32_e32 v37, v37
	v_mov_b32_e32 v143, v129
	v_pk_add_f32 v[36:37], v[36:37], 1.0 op_sel_hi:[1,0]
	s_nop 0
	s_nop 0
	v_rcp_f32_e32 v38, v37
	s_nop 0
	v_mul_f32_e32 v33, v33, v38
	s_nop 0
	v_rcp_f32_e32 v37, v36
	s_nop 0
	v_mul_f32_e32 v32, v32, v37
	v_cvt_pk_bf16_f32 v32, v32, v33
	v_mul_f32_e32 v33, 0xbfb8aa3b, v34
	v_exp_f32_e32 v36, v33
	v_mul_f32_e32 v33, 0xbfb8aa3b, v35
	v_exp_f32_e32 v37, v33
	s_nop 0
	v_pk_add_f32 v[36:37], v[36:37], 1.0 op_sel_hi:[1,0]
	s_nop 0
	s_nop 0
	v_rcp_f32_e32 v33, v37
	s_nop 0
	v_mul_f32_e32 v33, v35, v33
	s_nop 0
	v_rcp_f32_e32 v35, v36
	s_nop 0
	v_mul_f32_e32 v34, v34, v35
	v_cvt_pk_bf16_f32 v33, v34, v33
	v_lshl_add_u64 v[34:35], s[68:69], 0, v[48:49]
	v_lshl_add_u64 v[34:35], v[142:143], 1, v[34:35]
	v_add_co_u32_e32 v34, vcc, 0x9ffe000, v34
	s_nop 1
	v_addc_co_u32_e32 v35, vcc, 0, v35, vcc
	global_store_dwordx2 v[34:35], v[32:33], off offset:2144
	s_andn2_saveexec_b64 s[72:73], s[72:73]
	s_cbranch_execz .LBB0_414

.LBB0_414:
	s_or_b64 exec, exec, s[72:73]
	v_or_b32_e32 v34, 0x60, v144
	v_ashrrev_i32_e32 v35, 31, v34
	v_lshlrev_b64 v[32:33], 11, v[34:35]
	v_cmp_gt_i32_e64 s[10:11], s34, v34
	v_cmp_lt_i32_e64 s[12:13], s35, v34
	s_and_saveexec_b64 s[0:1], s[2:3]
	s_xor_b64 s[72:73], exec, s[0:1]
	s_cbranch_execz .LBB0_416
	v_mul_f32_e32 v34, 0xbfb8aa3b, v28
	v_mul_f32_e32 v35, 0xbfb8aa3b, v29
	v_exp_f32_e32 v34, v34
	v_exp_f32_e32 v35, v35
	v_mov_b32_e32 v143, v129
	v_pk_add_f32 v[34:35], v[34:35], 1.0 op_sel_hi:[1,0]
	s_nop 0
	s_nop 0
	v_rcp_f32_e32 v36, v35
	s_nop 0
	v_mul_f32_e32 v29, v29, v36
	s_nop 0
	v_rcp_f32_e32 v35, v34
	s_nop 0
	v_mul_f32_e32 v28, v28, v35
	v_cvt_pk_bf16_f32 v28, v28, v29
	v_mul_f32_e32 v29, 0xbfb8aa3b, v30
	v_exp_f32_e32 v34, v29
	v_mul_f32_e32 v29, 0xbfb8aa3b, v31
	v_exp_f32_e32 v35, v29
	s_nop 0
	v_pk_add_f32 v[34:35], v[34:35], 1.0 op_sel_hi:[1,0]
	s_nop 0
	s_nop 0
	v_rcp_f32_e32 v29, v35
	s_nop 0
	v_mul_f32_e32 v29, v31, v29
	s_nop 0
	v_rcp_f32_e32 v31, v34
	s_nop 0
	v_mul_f32_e32 v30, v30, v31
	v_cvt_pk_bf16_f32 v29, v30, v29
	v_lshl_add_u64 v[30:31], s[68:69], 0, v[32:33]
	v_lshl_add_u64 v[30:31], v[142:143], 1, v[30:31]
	v_add_co_u32_e32 v30, vcc, 0x9ffe000, v30
	s_nop 1
	v_addc_co_u32_e32 v31, vcc, 0, v31, vcc
	global_store_dwordx2 v[30:31], v[28:29], off offset:2048

.LBB0_434:
	v_mul_f32_e32 v28, 0xbfb8aa3b, v24
	v_mul_f32_e32 v29, 0xbfb8aa3b, v25
	v_exp_f32_e32 v28, v28
	v_exp_f32_e32 v29, v29
	v_mov_b32_e32 v143, v129
	v_pk_add_f32 v[28:29], v[28:29], 1.0 op_sel_hi:[1,0]
	s_nop 0
	s_nop 0
	v_rcp_f32_e32 v30, v29
	s_nop 0
	v_mul_f32_e32 v25, v25, v30
	s_nop 0
	v_rcp_f32_e32 v29, v28
	s_nop 0
	v_mul_f32_e32 v24, v24, v29
	v_cvt_pk_bf16_f32 v24, v24, v25
	v_mul_f32_e32 v25, 0xbfb8aa3b, v26
	v_exp_f32_e32 v28, v25
	v_mul_f32_e32 v25, 0xbfb8aa3b, v27
	v_exp_f32_e32 v29, v25
	s_nop 0
	v_pk_add_f32 v[28:29], v[28:29], 1.0 op_sel_hi:[1,0]
	s_nop 0
	s_nop 0
	v_rcp_f32_e32 v25, v29
	s_nop 0
	v_mul_f32_e32 v25, v27, v25
	s_nop 0
	v_rcp_f32_e32 v27, v28
	s_nop 0
	v_mul_f32_e32 v26, v26, v27
	v_cvt_pk_bf16_f32 v25, v26, v25
	v_lshl_add_u64 v[26:27], s[68:69], 0, v[32:33]
	v_lshl_add_u64 v[26:27], v[142:143], 1, v[26:27]
	v_add_co_u32_e32 v26, vcc, 0x9ffe000, v26
	s_nop 1
	v_addc_co_u32_e32 v27, vcc, 0, v27, vcc
	global_store_dwordx2 v[26:27], v[24:25], off offset:2080
	s_andn2_saveexec_b64 s[72:73], s[72:73]
	s_cbranch_execz .LBB0_419

.LBB0_446:
	v_mul_f32_e32 v24, 0xbfb8aa3b, v20
	v_mul_f32_e32 v25, 0xbfb8aa3b, v21
	v_exp_f32_e32 v24, v24
	v_exp_f32_e32 v25, v25
	v_mov_b32_e32 v143, v129
	v_pk_add_f32 v[24:25], v[24:25], 1.0 op_sel_hi:[1,0]
	s_nop 0
	s_nop 0
	v_rcp_f32_e32 v26, v25
	s_nop 0
	v_mul_f32_e32 v21, v21, v26
	s_nop 0
	v_rcp_f32_e32 v25, v24
	s_nop 0
	v_mul_f32_e32 v20, v20, v25
	v_cvt_pk_bf16_f32 v20, v20, v21
	v_mul_f32_e32 v21, 0xbfb8aa3b, v22
	v_exp_f32_e32 v24, v21
	v_mul_f32_e32 v21, 0xbfb8aa3b, v23
	v_exp_f32_e32 v25, v21
	s_nop 0
	v_pk_add_f32 v[24:25], v[24:25], 1.0 op_sel_hi:[1,0]
	s_nop 0
	s_nop 0
	v_rcp_f32_e32 v21, v25
	s_nop 0
	v_mul_f32_e32 v21, v23, v21
	s_nop 0
	v_rcp_f32_e32 v23, v24
	s_nop 0
	v_mul_f32_e32 v22, v22, v23
	v_cvt_pk_bf16_f32 v21, v22, v21
	v_lshl_add_u64 v[22:23], s[68:69], 0, v[32:33]
	v_lshl_add_u64 v[22:23], v[142:143], 1, v[22:23]
	v_add_co_u32_e32 v22, vcc, 0x9ffe000, v22
	s_nop 1
	v_addc_co_u32_e32 v23, vcc, 0, v23, vcc
	global_store_dwordx2 v[22:23], v[20:21], off offset:2112
	s_andn2_saveexec_b64 s[72:73], s[72:73]
	s_cbranch_execz .LBB0_421

.LBB0_458:
	v_mul_f32_e32 v20, 0xbfb8aa3b, v16
	v_mul_f32_e32 v21, 0xbfb8aa3b, v17
	v_exp_f32_e32 v20, v20
	v_exp_f32_e32 v21, v21
	v_mov_b32_e32 v143, v129
	v_pk_add_f32 v[20:21], v[20:21], 1.0 op_sel_hi:[1,0]
	s_nop 0
	s_nop 0
	v_rcp_f32_e32 v22, v21
	s_nop 0
	v_mul_f32_e32 v17, v17, v22
	s_nop 0
	v_rcp_f32_e32 v21, v20
	s_nop 0
	v_mul_f32_e32 v16, v16, v21
	v_cvt_pk_bf16_f32 v16, v16, v17
	v_mul_f32_e32 v17, 0xbfb8aa3b, v18
	v_exp_f32_e32 v20, v17
	v_mul_f32_e32 v17, 0xbfb8aa3b, v19
	v_exp_f32_e32 v21, v17
	s_nop 0
	v_pk_add_f32 v[20:21], v[20:21], 1.0 op_sel_hi:[1,0]
	s_nop 0
	s_nop 0
	v_rcp_f32_e32 v17, v21
	s_nop 0
	v_mul_f32_e32 v17, v19, v17
	s_nop 0
	v_rcp_f32_e32 v19, v20
	s_nop 0
	v_mul_f32_e32 v18, v18, v19
	v_cvt_pk_bf16_f32 v17, v18, v17
	v_lshl_add_u64 v[18:19], s[68:69], 0, v[32:33]
	v_lshl_add_u64 v[18:19], v[142:143], 1, v[18:19]
	v_add_co_u32_e32 v18, vcc, 0x9ffe000, v18
	s_nop 1
	v_addc_co_u32_e32 v19, vcc, 0, v19, vcc
	global_store_dwordx2 v[18:19], v[16:17], off offset:2144
	s_andn2_saveexec_b64 s[72:73], s[72:73]
	s_cbranch_execz .LBB0_470

.LBB0_470:
	s_or_b64 exec, exec, s[72:73]
	v_or_b32_e32 v18, 0x70, v144
	v_ashrrev_i32_e32 v19, 31, v18
	v_lshlrev_b64 v[16:17], 11, v[18:19]
	v_cmp_gt_i32_e64 s[10:11], s34, v18
	v_cmp_lt_i32_e64 s[12:13], s35, v18
	s_and_saveexec_b64 s[0:1], s[2:3]
	s_xor_b64 s[2:3], exec, s[0:1]
	s_cbranch_execz .LBB0_472
	v_mul_f32_e32 v18, 0xbfb8aa3b, v12
	v_mul_f32_e32 v19, 0xbfb8aa3b, v13
	v_exp_f32_e32 v18, v18
	v_exp_f32_e32 v19, v19
	v_mov_b32_e32 v143, v129
	v_pk_add_f32 v[18:19], v[18:19], 1.0 op_sel_hi:[1,0]
	s_nop 0
	s_nop 0
	v_rcp_f32_e32 v20, v19
	s_nop 0
	v_mul_f32_e32 v13, v13, v20
	s_nop 0
	v_rcp_f32_e32 v19, v18
	s_nop 0
	v_mul_f32_e32 v12, v12, v19
	v_cvt_pk_bf16_f32 v12, v12, v13
	v_mul_f32_e32 v13, 0xbfb8aa3b, v14
	v_exp_f32_e32 v18, v13
	v_mul_f32_e32 v13, 0xbfb8aa3b, v15
	v_exp_f32_e32 v19, v13
	s_nop 0
	v_pk_add_f32 v[18:19], v[18:19], 1.0 op_sel_hi:[1,0]
	s_nop 0
	s_nop 0
	v_rcp_f32_e32 v13, v19
	s_nop 0
	v_mul_f32_e32 v13, v15, v13
	s_nop 0
	v_rcp_f32_e32 v15, v18
	s_nop 0
	v_mul_f32_e32 v14, v14, v15
	v_cvt_pk_bf16_f32 v13, v14, v13
	v_lshl_add_u64 v[14:15], s[68:69], 0, v[16:17]
	v_lshl_add_u64 v[14:15], v[142:143], 1, v[14:15]
	v_add_co_u32_e32 v14, vcc, 0x9ffe000, v14
	s_nop 1
	v_addc_co_u32_e32 v15, vcc, 0, v15, vcc
	global_store_dwordx2 v[14:15], v[12:13], off offset:2048

.LBB0_490:
	v_mul_f32_e32 v12, 0xbfb8aa3b, v8
	v_mul_f32_e32 v13, 0xbfb8aa3b, v9
	v_exp_f32_e32 v12, v12
	v_exp_f32_e32 v13, v13
	v_mov_b32_e32 v143, v129
	v_pk_add_f32 v[12:13], v[12:13], 1.0 op_sel_hi:[1,0]
	s_nop 0
	s_nop 0
	v_rcp_f32_e32 v14, v13
	s_nop 0
	v_mul_f32_e32 v9, v9, v14
	s_nop 0
	v_rcp_f32_e32 v13, v12
	s_nop 0
	v_mul_f32_e32 v8, v8, v13
	v_cvt_pk_bf16_f32 v8, v8, v9
	v_mul_f32_e32 v9, 0xbfb8aa3b, v10
	v_exp_f32_e32 v12, v9
	v_mul_f32_e32 v9, 0xbfb8aa3b, v11
	v_exp_f32_e32 v13, v9
	s_nop 0
	v_pk_add_f32 v[12:13], v[12:13], 1.0 op_sel_hi:[1,0]
	s_nop 0
	s_nop 0
	v_rcp_f32_e32 v9, v13
	s_nop 0
	v_mul_f32_e32 v9, v11, v9
	s_nop 0
	v_rcp_f32_e32 v11, v12
	s_nop 0
	v_mul_f32_e32 v10, v10, v11
	v_cvt_pk_bf16_f32 v9, v10, v9
	v_lshl_add_u64 v[10:11], s[68:69], 0, v[16:17]
	v_lshl_add_u64 v[10:11], v[142:143], 1, v[10:11]
	v_add_co_u32_e32 v10, vcc, 0x9ffe000, v10
	s_nop 1
	v_addc_co_u32_e32 v11, vcc, 0, v11, vcc
	global_store_dwordx2 v[10:11], v[8:9], off offset:2080
	s_andn2_saveexec_b64 s[2:3], s[2:3]
	s_cbranch_execz .LBB0_475

.LBB0_502:
	v_mul_f32_e32 v8, 0xbfb8aa3b, v4
	v_mul_f32_e32 v9, 0xbfb8aa3b, v5
	v_exp_f32_e32 v8, v8
	v_exp_f32_e32 v9, v9
	v_mov_b32_e32 v143, v129
	v_pk_add_f32 v[8:9], v[8:9], 1.0 op_sel_hi:[1,0]
	s_nop 0
	s_nop 0
	v_rcp_f32_e32 v10, v9
	s_nop 0
	v_mul_f32_e32 v5, v5, v10
	s_nop 0
	v_rcp_f32_e32 v9, v8
	s_nop 0
	v_mul_f32_e32 v4, v4, v9
	v_cvt_pk_bf16_f32 v4, v4, v5
	v_mul_f32_e32 v5, 0xbfb8aa3b, v6
	v_exp_f32_e32 v8, v5
	v_mul_f32_e32 v5, 0xbfb8aa3b, v7
	v_exp_f32_e32 v9, v5
	s_nop 0
	v_pk_add_f32 v[8:9], v[8:9], 1.0 op_sel_hi:[1,0]
	s_nop 0
	s_nop 0
	v_rcp_f32_e32 v5, v9
	s_nop 0
	v_mul_f32_e32 v5, v7, v5
	s_nop 0
	v_rcp_f32_e32 v7, v8
	s_nop 0
	v_mul_f32_e32 v6, v6, v7
	v_cvt_pk_bf16_f32 v5, v6, v5
	v_lshl_add_u64 v[6:7], s[68:69], 0, v[16:17]
	v_lshl_add_u64 v[6:7], v[142:143], 1, v[6:7]
	v_add_co_u32_e32 v6, vcc, 0x9ffe000, v6
	s_nop 1
	v_addc_co_u32_e32 v7, vcc, 0, v7, vcc
	global_store_dwordx2 v[6:7], v[4:5], off offset:2112
	s_andn2_saveexec_b64 s[2:3], s[2:3]
	s_cbranch_execz .LBB0_477

.LBB0_514:
	v_mul_f32_e32 v4, 0xbfb8aa3b, v0
	v_mul_f32_e32 v5, 0xbfb8aa3b, v1
	v_exp_f32_e32 v4, v4
	v_exp_f32_e32 v5, v5
	v_mov_b32_e32 v143, v129
	v_pk_add_f32 v[4:5], v[4:5], 1.0 op_sel_hi:[1,0]
	s_nop 0
	s_nop 0
	v_rcp_f32_e32 v6, v5
	s_nop 0
	v_mul_f32_e32 v1, v1, v6
	s_nop 0
	v_rcp_f32_e32 v5, v4
	s_nop 0
	v_mul_f32_e32 v0, v0, v5
	v_cvt_pk_bf16_f32 v0, v0, v1
	v_mul_f32_e32 v1, 0xbfb8aa3b, v2
	v_exp_f32_e32 v4, v1
	v_mul_f32_e32 v1, 0xbfb8aa3b, v3
	v_exp_f32_e32 v5, v1
	s_nop 0
	v_pk_add_f32 v[4:5], v[4:5], 1.0 op_sel_hi:[1,0]
	s_nop 0
	s_nop 0
	v_rcp_f32_e32 v1, v5
	s_nop 0
	v_mul_f32_e32 v1, v3, v1
	s_nop 0
	v_rcp_f32_e32 v3, v4
	s_nop 0
	v_mul_f32_e32 v2, v2, v3
	v_cvt_pk_bf16_f32 v1, v2, v1
	v_lshl_add_u64 v[2:3], s[68:69], 0, v[16:17]
	v_lshl_add_u64 v[2:3], v[142:143], 1, v[2:3]
	v_add_co_u32_e32 v2, vcc, 0x9ffe000, v2
	s_nop 1
	v_addc_co_u32_e32 v3, vcc, 0, v3, vcc
	global_store_dwordx2 v[2:3], v[0:1], off offset:2144
	s_andn2_saveexec_b64 s[2:3], s[2:3]
	s_cbranch_execz .LBB0_526

.LBB0_685:
	ds_bpermute_b32 v0, v188, v175
	ds_bpermute_b32 v1, v188, v174
	s_lshl_b32 s2, s15, 1
	v_mov_b32_e32 v149, v145
	s_add_i32 s28, s28, s78
	s_waitcnt lgkmcnt(1)
	v_add_f32_e32 v0, v175, v0
	ds_bpermute_b32 v2, v187, v0
	s_waitcnt lgkmcnt(1)
	v_add_f32_e32 v1, v174, v1
	ds_bpermute_b32 v3, v187, v1
	s_cmpk_gt_i32 s28, 0x5ff
	s_waitcnt lgkmcnt(1)
	v_add_f32_e32 v0, v0, v2
	s_waitcnt lgkmcnt(0)
	v_add_f32_e32 v1, v1, v3
	v_rcp_f32_e32 v10, v0
	v_rcp_f32_e32 v0, v1
	s_nop 0
	v_mul_f32_e32 v12, v190, v0
	v_pk_mul_f32 v[2:3], v[78:79], v[12:13] op_sel_hi:[1,0]
	v_pk_mul_f32 v[6:7], v[70:71], v[12:13] op_sel_hi:[1,0]
	v_pk_fma_f32 v[4:5], v[74:75], v[10:11], v[2:3] op_sel_hi:[1,0,1] neg_lo:[0,0,1] neg_hi:[0,0,1]
	v_lshl_add_u64 v[2:3], s[4:5], 0, v[152:153]
	v_lshl_add_u64 v[2:3], v[2:3], 0, s[2:3]
	v_lshl_add_u64 v[2:3], v[2:3], 0, v[148:149]
	global_load_dwordx2 v[74:75], v[2:3], off
	v_pk_fma_f32 v[66:67], v[66:67], v[10:11], v[6:7] op_sel_hi:[1,0,1] neg_lo:[0,0,1] neg_hi:[0,0,1]
	global_load_dwordx4 v[6:9], v[146:147], off
	v_pk_mul_f32 v[68:69], v[68:69], v[12:13] op_sel_hi:[1,0]
	v_pk_mul_f32 v[0:1], v[76:77], v[12:13] op_sel_hi:[1,0]
	v_pk_fma_f32 v[64:65], v[64:65], v[10:11], v[68:69] op_sel_hi:[1,0,1] neg_lo:[0,0,1] neg_hi:[0,0,1]
	v_pk_mul_f32 v[62:63], v[62:63], v[12:13] op_sel_hi:[1,0]
	v_pk_mul_f32 v[68:69], v[64:65], v[64:65]
	v_pk_mul_f32 v[60:61], v[60:61], v[12:13] op_sel_hi:[1,0]
	v_pk_mul_f32 v[54:55], v[54:55], v[12:13] op_sel_hi:[1,0]
	v_pk_mul_f32 v[52:53], v[52:53], v[12:13] op_sel_hi:[1,0]
	v_pk_mul_f32 v[46:47], v[46:47], v[12:13] op_sel_hi:[1,0]
	v_pk_mul_f32 v[44:45], v[44:45], v[12:13] op_sel_hi:[1,0]
	v_pk_mul_f32 v[38:39], v[38:39], v[12:13] op_sel_hi:[1,0]
	v_pk_mul_f32 v[36:37], v[36:37], v[12:13] op_sel_hi:[1,0]
	v_pk_mul_f32 v[30:31], v[30:31], v[12:13] op_sel_hi:[1,0]
	v_pk_mul_f32 v[28:29], v[28:29], v[12:13] op_sel_hi:[1,0]
	v_pk_mul_f32 v[22:23], v[22:23], v[12:13] op_sel_hi:[1,0]
	v_pk_mul_f32 v[12:13], v[20:21], v[12:13] op_sel_hi:[1,0]
	v_pk_fma_f32 v[0:1], v[72:73], v[10:11], v[0:1] op_sel_hi:[1,0,1] neg_lo:[0,0,1] neg_hi:[0,0,1]
	v_pk_mul_f32 v[70:71], v[66:67], v[66:67]
	v_pk_fma_f32 v[58:59], v[58:59], v[10:11], v[62:63] op_sel_hi:[1,0,1] neg_lo:[0,0,1] neg_hi:[0,0,1]
	v_pk_fma_f32 v[56:57], v[56:57], v[10:11], v[60:61] op_sel_hi:[1,0,1] neg_lo:[0,0,1] neg_hi:[0,0,1]
	v_pk_fma_f32 v[50:51], v[50:51], v[10:11], v[54:55] op_sel_hi:[1,0,1] neg_lo:[0,0,1] neg_hi:[0,0,1]
	v_pk_fma_f32 v[48:49], v[48:49], v[10:11], v[52:53] op_sel_hi:[1,0,1] neg_lo:[0,0,1] neg_hi:[0,0,1]
	v_pk_fma_f32 v[42:43], v[42:43], v[10:11], v[46:47] op_sel_hi:[1,0,1] neg_lo:[0,0,1] neg_hi:[0,0,1]
	v_pk_fma_f32 v[40:41], v[40:41], v[10:11], v[44:45] op_sel_hi:[1,0,1] neg_lo:[0,0,1] neg_hi:[0,0,1]
	v_pk_fma_f32 v[34:35], v[34:35], v[10:11], v[38:39] op_sel_hi:[1,0,1] neg_lo:[0,0,1] neg_hi:[0,0,1]
	v_pk_fma_f32 v[32:33], v[32:33], v[10:11], v[36:37] op_sel_hi:[1,0,1] neg_lo:[0,0,1] neg_hi:[0,0,1]
	v_pk_fma_f32 v[26:27], v[26:27], v[10:11], v[30:31] op_sel_hi:[1,0,1] neg_lo:[0,0,1] neg_hi:[0,0,1]
	v_pk_fma_f32 v[24:25], v[24:25], v[10:11], v[28:29] op_sel_hi:[1,0,1] neg_lo:[0,0,1] neg_hi:[0,0,1]
	v_pk_fma_f32 v[18:19], v[18:19], v[10:11], v[22:23] op_sel_hi:[1,0,1] neg_lo:[0,0,1] neg_hi:[0,0,1]
	v_pk_fma_f32 v[10:11], v[16:17], v[10:11], v[12:13] op_sel_hi:[1,0,1] neg_lo:[0,0,1] neg_hi:[0,0,1]
	v_add_f32_e32 v16, v68, v69
	v_add_f32_e32 v16, v70, v16
	v_pk_mul_f32 v[60:61], v[56:57], v[56:57]
	v_add_f32_e32 v16, v71, v16
	v_add_f32_e32 v16, v60, v16
	v_pk_mul_f32 v[62:63], v[58:59], v[58:59]
	v_add_f32_e32 v16, v61, v16
	v_add_f32_e32 v16, v62, v16
	v_pk_mul_f32 v[52:53], v[48:49], v[48:49]
	v_add_f32_e32 v16, v63, v16
	v_add_f32_e32 v16, v52, v16
	v_pk_mul_f32 v[54:55], v[50:51], v[50:51]
	v_add_f32_e32 v16, v53, v16
	v_add_f32_e32 v16, v54, v16
	v_pk_mul_f32 v[44:45], v[40:41], v[40:41]
	v_add_f32_e32 v16, v55, v16
	v_add_f32_e32 v16, v44, v16
	v_pk_mul_f32 v[46:47], v[42:43], v[42:43]
	v_add_f32_e32 v16, v45, v16
	v_add_f32_e32 v16, v46, v16
	v_pk_mul_f32 v[36:37], v[32:33], v[32:33]
	v_add_f32_e32 v16, v47, v16
	v_add_f32_e32 v16, v36, v16
	v_pk_mul_f32 v[38:39], v[34:35], v[34:35]
	v_add_f32_e32 v16, v37, v16
	v_add_f32_e32 v16, v38, v16
	v_pk_mul_f32 v[28:29], v[24:25], v[24:25]
	v_add_f32_e32 v16, v39, v16
	v_add_f32_e32 v16, v28, v16
	v_pk_mul_f32 v[30:31], v[26:27], v[26:27]
	v_add_f32_e32 v16, v29, v16
	v_add_f32_e32 v16, v30, v16
	v_pk_mul_f32 v[12:13], v[10:11], v[10:11]
	v_add_f32_e32 v16, v31, v16
	v_add_f32_e32 v12, v12, v16
	v_pk_mul_f32 v[22:23], v[18:19], v[18:19]
	v_add_f32_e32 v12, v13, v12
	v_add_f32_e32 v12, v22, v12
	v_pk_mul_f32 v[14:15], v[0:1], v[0:1]
	v_add_f32_e32 v12, v23, v12
	v_add_f32_e32 v12, v14, v12
	v_pk_mul_f32 v[72:73], v[4:5], v[4:5]
	v_add_f32_e32 v12, v15, v12
	v_add_f32_e32 v12, v72, v12
	v_add_f32_e32 v12, v73, v12
	ds_bpermute_b32 v13, v188, v12
	s_waitcnt vmcnt(1)
	v_and_b32_e32 v23, 0xffff0000, v75
	v_lshlrev_b32_e32 v20, 16, v74
	s_waitcnt lgkmcnt(0)
	v_add_f32_e32 v21, v12, v13
	ds_bpermute_b32 v22, v187, v21
	global_load_dwordx2 v[12:13], v[2:3], off offset:32
	global_load_dwordx2 v[14:15], v[2:3], off offset:64
	global_load_dwordx2 v[16:17], v[2:3], off offset:96
	s_waitcnt lgkmcnt(0)
	v_add_f32_e32 v21, v21, v22
	v_fmamk_f32 v21, v21, 0x3c000000, v213
	v_mul_f32_e32 v22, 0x4b800000, v21
	v_cmp_gt_f32_e32 vcc, s27, v21
	s_nop 1
	v_cndmask_b32_e32 v21, v21, v22, vcc
	v_rsq_f32_e32 v28, v21
	v_lshlrev_b32_e32 v22, 16, v75
	v_and_b32_e32 v21, 0xffff0000, v74
	v_mul_f32_e32 v29, 0x45800000, v28
	v_cndmask_b32_e32 v28, v28, v29, vcc
	v_mul_f32_e32 v28, 0x3f4ccccd, v28
	v_pk_mul_f32 v[30:31], v[66:67], v[28:29] op_sel_hi:[1,0]
	v_pk_mul_f32 v[10:11], v[10:11], v[28:29] op_sel_hi:[1,0]
	s_waitcnt vmcnt(3)
	v_pk_mul_f32 v[8:9], v[8:9], v[30:31]
	v_pk_mul_f32 v[4:5], v[4:5], v[28:29] op_sel_hi:[1,0]
	v_pk_mul_f32 v[8:9], v[8:9], v[22:23]
	v_pk_mul_f32 v[22:23], v[64:65], v[28:29] op_sel_hi:[1,0]
	v_pk_mul_f32 v[0:1], v[0:1], v[28:29] op_sel_hi:[1,0]
	v_pk_mul_f32 v[6:7], v[6:7], v[22:23]
	v_pk_mul_f32 v[22:23], v[56:57], v[28:29] op_sel_hi:[1,0]
	v_pk_mul_f32 v[6:7], v[6:7], v[20:21]
	v_pk_mul_f32 v[20:21], v[58:59], v[28:29] op_sel_hi:[1,0]
	v_cvt_pk_bf16_f32 v6, v6, v7
	v_cvt_pk_bf16_f32 v7, v8, v9
	global_store_dwordx2 v[2:3], v[6:7], off
	global_load_dwordx4 v[6:9], v[146:147], off offset:64
	s_waitcnt vmcnt(4)
	v_lshlrev_b32_e32 v30, 16, v12
	v_and_b32_e32 v31, 0xffff0000, v12
	v_lshlrev_b32_e32 v12, 16, v13
	v_and_b32_e32 v13, 0xffff0000, v13
	s_waitcnt vmcnt(0)
	v_pk_mul_f32 v[8:9], v[8:9], v[20:21]
	v_pk_mul_f32 v[6:7], v[6:7], v[22:23]
	v_pk_mul_f32 v[8:9], v[8:9], v[12:13]
	v_pk_mul_f32 v[6:7], v[6:7], v[30:31]
	v_pk_mul_f32 v[12:13], v[50:51], v[28:29] op_sel_hi:[1,0]
	v_cvt_pk_bf16_f32 v6, v6, v7
	v_cvt_pk_bf16_f32 v7, v8, v9
	global_store_dwordx2 v[2:3], v[6:7], off offset:32
	global_load_dwordx4 v[6:9], v[146:147], off offset:128
	v_pk_mul_f32 v[20:21], v[48:49], v[28:29] op_sel_hi:[1,0]
	v_lshlrev_b32_e32 v22, 16, v14
	v_and_b32_e32 v23, 0xffff0000, v14
	v_lshlrev_b32_e32 v14, 16, v15
	v_and_b32_e32 v15, 0xffff0000, v15
	v_pk_mul_f32 v[30:31], v[32:33], v[28:29] op_sel_hi:[1,0]
	s_waitcnt vmcnt(0)
	v_pk_mul_f32 v[8:9], v[8:9], v[12:13]
	v_pk_mul_f32 v[6:7], v[6:7], v[20:21]
	v_pk_mul_f32 v[8:9], v[8:9], v[14:15]
	v_pk_mul_f32 v[6:7], v[6:7], v[22:23]
	v_pk_mul_f32 v[14:15], v[42:43], v[28:29] op_sel_hi:[1,0]
	v_cvt_pk_bf16_f32 v6, v6, v7
	v_cvt_pk_bf16_f32 v7, v8, v9
	global_store_dwordx2 v[2:3], v[6:7], off offset:64
	global_load_dwordx4 v[6:9], v[146:147], off offset:192
	s_nop 0
	global_load_dwordx2 v[12:13], v[2:3], off offset:128
	v_pk_mul_f32 v[20:21], v[40:41], v[28:29] op_sel_hi:[1,0]
	v_lshlrev_b32_e32 v22, 16, v16
	v_and_b32_e32 v23, 0xffff0000, v16
	v_lshlrev_b32_e32 v16, 16, v17
	v_and_b32_e32 v17, 0xffff0000, v17
	s_waitcnt vmcnt(1)
	v_pk_mul_f32 v[8:9], v[8:9], v[14:15]
	v_pk_mul_f32 v[6:7], v[6:7], v[20:21]
	v_pk_mul_f32 v[8:9], v[8:9], v[16:17]
	v_pk_mul_f32 v[6:7], v[6:7], v[22:23]
	v_pk_mul_f32 v[22:23], v[34:35], v[28:29] op_sel_hi:[1,0]
	v_cvt_pk_bf16_f32 v6, v6, v7
	v_cvt_pk_bf16_f32 v7, v8, v9
	global_store_dwordx2 v[2:3], v[6:7], off offset:96
	global_load_dwordx4 v[6:9], v[146:147], off offset:256
	s_nop 0
	global_load_dwordx2 v[14:15], v[2:3], off offset:160
	global_load_dwordx2 v[16:17], v[2:3], off offset:192
	global_load_dwordx2 v[20:21], v[2:3], off offset:224
	s_waitcnt vmcnt(5)
	v_lshlrev_b32_e32 v32, 16, v12
	v_and_b32_e32 v33, 0xffff0000, v12
	v_lshlrev_b32_e32 v12, 16, v13
	v_and_b32_e32 v13, 0xffff0000, v13
	s_waitcnt vmcnt(3)
	v_pk_mul_f32 v[8:9], v[8:9], v[22:23]
	v_pk_mul_f32 v[6:7], v[6:7], v[30:31]
	v_pk_mul_f32 v[8:9], v[8:9], v[12:13]
	v_pk_mul_f32 v[6:7], v[6:7], v[32:33]
	v_pk_mul_f32 v[12:13], v[26:27], v[28:29] op_sel_hi:[1,0]
	v_cvt_pk_bf16_f32 v6, v6, v7
	v_cvt_pk_bf16_f32 v7, v8, v9
	global_store_dwordx2 v[2:3], v[6:7], off offset:128
	global_load_dwordx4 v[6:9], v[146:147], off offset:320
	v_pk_mul_f32 v[22:23], v[24:25], v[28:29] op_sel_hi:[1,0]
	s_waitcnt vmcnt(4)
	v_lshlrev_b32_e32 v24, 16, v14
	v_and_b32_e32 v25, 0xffff0000, v14
	v_lshlrev_b32_e32 v14, 16, v15
	v_and_b32_e32 v15, 0xffff0000, v15
	s_waitcnt vmcnt(0)
	v_pk_mul_f32 v[8:9], v[8:9], v[12:13]
	v_pk_mul_f32 v[6:7], v[6:7], v[22:23]
	v_pk_mul_f32 v[8:9], v[8:9], v[14:15]
	v_pk_mul_f32 v[6:7], v[6:7], v[24:25]
	v_pk_mul_f32 v[12:13], v[18:19], v[28:29] op_sel_hi:[1,0]
	v_cvt_pk_bf16_f32 v6, v6, v7
	v_cvt_pk_bf16_f32 v7, v8, v9
	global_store_dwordx2 v[2:3], v[6:7], off offset:160
	global_load_dwordx4 v[6:9], v[146:147], off offset:384
	v_lshlrev_b32_e32 v14, 16, v16
	v_and_b32_e32 v15, 0xffff0000, v16
	v_lshlrev_b32_e32 v16, 16, v17
	v_and_b32_e32 v17, 0xffff0000, v17
	s_waitcnt vmcnt(0)
	v_pk_mul_f32 v[8:9], v[12:13], v[8:9]
	v_pk_mul_f32 v[6:7], v[10:11], v[6:7]
	v_pk_mul_f32 v[8:9], v[8:9], v[16:17]
	v_pk_mul_f32 v[6:7], v[6:7], v[14:15]
	v_lshlrev_b32_e32 v10, 16, v20
	v_cvt_pk_bf16_f32 v6, v6, v7
	v_cvt_pk_bf16_f32 v7, v8, v9
	global_store_dwordx2 v[2:3], v[6:7], off offset:192
	global_load_dwordx4 v[6:9], v[146:147], off offset:448
	v_and_b32_e32 v11, 0xffff0000, v20
	v_lshlrev_b32_e32 v12, 16, v21
	v_and_b32_e32 v13, 0xffff0000, v21
	s_waitcnt vmcnt(0)
	v_pk_mul_f32 v[4:5], v[4:5], v[8:9]
	v_pk_mul_f32 v[0:1], v[0:1], v[6:7]
	v_pk_mul_f32 v[4:5], v[4:5], v[12:13]
	v_pk_mul_f32 v[0:1], v[0:1], v[10:11]
	s_nop 0
	v_cvt_pk_bf16_f32 v0, v0, v1
	v_cvt_pk_bf16_f32 v1, v4, v5
	global_store_dwordx2 v[2:3], v[0:1], off offset:224
	s_cbranch_scc1 .LBB0_713

.LBB0_1128:
	v_mul_f32_e32 v139, 0xbfb8aa3b, v124
	v_exp_f32_e32 v142, v139
	v_mul_f32_e32 v139, 0xbfb8aa3b, v125
	v_exp_f32_e32 v143, v139
	v_add_u32_e32 v140, s63, v152
	v_ashrrev_i32_e32 v141, 31, v140
	v_lshlrev_b64 v[144:145], 12, v[140:141]
	v_pk_add_f32 v[142:143], v[142:143], 1.0 op_sel_hi:[1,0]
	v_or_b32_e32 v146, s28, v151
	s_mov_b64 s[38:39], -1
	v_mul_f32_e32 v147, 0xbfb8aa3b, v126
	v_exp_f32_e32 v154, v147
	v_mul_f32_e32 v147, 0xbfb8aa3b, v127
	v_rcp_f32_e32 v139, v143
	s_nop 0
	v_mul_f32_e32 v125, v125, v139
	v_exp_f32_e32 v155, v147
	s_nop 0
	v_pk_add_f32 v[154:155], v[154:155], 1.0 op_sel_hi:[1,0]
	v_rcp_f32_e32 v139, v142
	s_nop 0
	v_mul_f32_e32 v124, v124, v139
	v_cvt_pk_bf16_f32 v142, v124, v125
	v_rcp_f32_e32 v124, v155
	s_nop 0
	v_mul_f32_e32 v127, v127, v124
	v_ashrrev_i32_e32 v147, 31, v146
	v_rcp_f32_e32 v124, v154
	s_nop 0
	v_mul_f32_e32 v126, v126, v124
	v_mul_f32_e32 v124, 0xbfb8aa3b, v120
	v_mul_f32_e32 v125, 0xbfb8aa3b, v121
	v_exp_f32_e32 v124, v124
	v_exp_f32_e32 v125, v125
	v_cvt_pk_bf16_f32 v143, v126, v127
	v_lshl_add_u64 v[126:127], s[68:69], 0, v[144:145]
	v_pk_add_f32 v[144:145], v[124:125], 1.0 op_sel_hi:[1,0]
	s_nop 0
	v_lshlrev_b64 v[124:125], 1, v[146:147]
	v_lshl_add_u64 v[126:127], v[126:127], 0, v[124:125]
	global_store_dwordx2 v[126:127], v[142:143], off
	v_mul_f32_e32 v142, 0xbfb8aa3b, v122
	v_mul_f32_e32 v143, 0xbfb8aa3b, v123
	v_exp_f32_e32 v142, v142
	v_exp_f32_e32 v143, v143
	v_rcp_f32_e32 v139, v145
	s_nop 0
	v_mul_f32_e32 v121, v121, v139
	v_pk_add_f32 v[142:143], v[142:143], 1.0 op_sel_hi:[1,0]
	v_rcp_f32_e32 v139, v144
	s_nop 0
	v_mul_f32_e32 v120, v120, v139
	v_cvt_pk_bf16_f32 v120, v120, v121
	v_rcp_f32_e32 v121, v143
	s_nop 0
	v_mul_f32_e32 v121, v123, v121
	v_mul_f32_e32 v143, 0xbfb8aa3b, v116
	v_exp_f32_e32 v144, v143
	v_mul_f32_e32 v143, 0xbfb8aa3b, v117
	v_exp_f32_e32 v145, v143
	v_rcp_f32_e32 v123, v142
	s_nop 0
	v_mul_f32_e32 v122, v122, v123
	v_pk_add_f32 v[144:145], v[144:145], 1.0 op_sel_hi:[1,0]
	v_cvt_pk_bf16_f32 v121, v122, v121
	global_store_dwordx2 v[126:127], v[120:121], off offset:32
	v_rcp_f32_e32 v120, v145
	s_nop 0
	v_mul_f32_e32 v117, v117, v120
	v_mul_f32_e32 v120, 0xbfb8aa3b, v118
	v_mul_f32_e32 v121, 0xbfb8aa3b, v119
	v_exp_f32_e32 v120, v120
	v_exp_f32_e32 v121, v121
	s_nop 0
	v_pk_add_f32 v[120:121], v[120:121], 1.0 op_sel_hi:[1,0]
	v_rcp_f32_e32 v122, v144
	s_nop 0
	v_mul_f32_e32 v116, v116, v122
	v_cvt_pk_bf16_f32 v116, v116, v117
	v_rcp_f32_e32 v117, v121
	s_nop 0
	v_mul_f32_e32 v117, v119, v117
	v_mul_f32_e32 v123, 0xbfb8aa3b, v113
	v_mul_f32_e32 v122, 0xbfb8aa3b, v112
	v_exp_f32_e32 v122, v122
	v_exp_f32_e32 v123, v123
	v_rcp_f32_e32 v119, v120
	s_nop 0
	v_mul_f32_e32 v118, v118, v119
	v_pk_add_f32 v[122:123], v[122:123], 1.0 op_sel_hi:[1,0]
	v_cvt_pk_bf16_f32 v117, v118, v117
	global_store_dwordx2 v[126:127], v[116:117], off offset:64
	v_rcp_f32_e32 v116, v123
	s_nop 0
	v_mul_f32_e32 v113, v113, v116
	v_mul_f32_e32 v116, 0xbfb8aa3b, v114
	v_mul_f32_e32 v117, 0xbfb8aa3b, v115
	v_exp_f32_e32 v116, v116
	v_exp_f32_e32 v117, v117
	s_nop 0
	v_pk_add_f32 v[116:117], v[116:117], 1.0 op_sel_hi:[1,0]
	v_rcp_f32_e32 v118, v122
	s_nop 0
	v_mul_f32_e32 v112, v112, v118
	v_cvt_pk_bf16_f32 v112, v112, v113
	v_rcp_f32_e32 v113, v117
	s_nop 0
	v_mul_f32_e32 v113, v115, v113
	v_mul_f32_e32 v117, 0xbfb8aa3b, v108
	v_exp_f32_e32 v118, v117
	v_mul_f32_e32 v117, 0xbfb8aa3b, v109
	v_exp_f32_e32 v119, v117
	v_rcp_f32_e32 v115, v116
	s_nop 0
	v_mul_f32_e32 v114, v114, v115
	v_cvt_pk_bf16_f32 v113, v114, v113
	global_store_dwordx2 v[126:127], v[112:113], off offset:96
	v_pk_add_f32 v[112:113], v[118:119], 1.0 op_sel_hi:[1,0]
	v_or_b32_e32 v114, 16, v140
	v_ashrrev_i32_e32 v115, 31, v114
	v_lshlrev_b64 v[114:115], 12, v[114:115]
	v_rcp_f32_e32 v116, v113
	s_nop 0
	v_mul_f32_e32 v109, v109, v116
	v_mul_f32_e32 v116, 0xbfb8aa3b, v110
	v_mul_f32_e32 v117, 0xbfb8aa3b, v111
	v_exp_f32_e32 v116, v116
	v_exp_f32_e32 v117, v117
	s_nop 0
	v_pk_add_f32 v[116:117], v[116:117], 1.0 op_sel_hi:[1,0]
	v_rcp_f32_e32 v113, v112
	s_nop 0
	v_mul_f32_e32 v108, v108, v113
	v_cvt_pk_bf16_f32 v112, v108, v109
	v_rcp_f32_e32 v108, v117
	s_nop 0
	v_mul_f32_e32 v111, v111, v108
	v_mul_f32_e32 v108, 0xbfb8aa3b, v104
	v_mul_f32_e32 v109, 0xbfb8aa3b, v105
	v_exp_f32_e32 v108, v108
	v_exp_f32_e32 v109, v109
	v_rcp_f32_e32 v113, v116
	s_nop 0
	v_mul_f32_e32 v110, v110, v113
	v_cvt_pk_bf16_f32 v113, v110, v111
	v_pk_add_f32 v[110:111], v[108:109], 1.0 op_sel_hi:[1,0]
	v_lshl_add_u64 v[108:109], s[68:69], 0, v[114:115]
	v_lshl_add_u64 v[108:109], v[108:109], 0, v[124:125]
	global_store_dwordx2 v[108:109], v[112:113], off
	v_rcp_f32_e32 v112, v111
	s_nop 0
	v_mul_f32_e32 v105, v105, v112
	v_mul_f32_e32 v112, 0xbfb8aa3b, v106
	v_mul_f32_e32 v113, 0xbfb8aa3b, v107
	v_exp_f32_e32 v112, v112
	v_exp_f32_e32 v113, v113
	s_nop 0
	v_pk_add_f32 v[112:113], v[112:113], 1.0 op_sel_hi:[1,0]
	v_rcp_f32_e32 v111, v110
	s_nop 0
	v_mul_f32_e32 v104, v104, v111
	v_cvt_pk_bf16_f32 v104, v104, v105
	v_rcp_f32_e32 v105, v113
	s_nop 0
	v_mul_f32_e32 v105, v107, v105
	v_mul_f32_e32 v111, 0xbfb8aa3b, v101
	v_mul_f32_e32 v110, 0xbfb8aa3b, v100
	v_exp_f32_e32 v110, v110
	v_exp_f32_e32 v111, v111
	v_rcp_f32_e32 v107, v112
	s_nop 0
	v_mul_f32_e32 v106, v106, v107
	v_pk_add_f32 v[110:111], v[110:111], 1.0 op_sel_hi:[1,0]
	v_cvt_pk_bf16_f32 v105, v106, v105
	global_store_dwordx2 v[108:109], v[104:105], off offset:32
	v_rcp_f32_e32 v104, v111
	s_nop 0
	v_mul_f32_e32 v101, v101, v104
	v_mul_f32_e32 v104, 0xbfb8aa3b, v102
	v_mul_f32_e32 v105, 0xbfb8aa3b, v103
	v_exp_f32_e32 v104, v104
	v_exp_f32_e32 v105, v105
	s_nop 0
	v_pk_add_f32 v[104:105], v[104:105], 1.0 op_sel_hi:[1,0]
	v_rcp_f32_e32 v106, v110
	s_nop 0
	v_mul_f32_e32 v100, v100, v106
	v_cvt_pk_bf16_f32 v100, v100, v101
	v_rcp_f32_e32 v101, v105
	s_nop 0
	v_mul_f32_e32 v101, v103, v101
	v_mul_f32_e32 v107, 0xbfb8aa3b, v97
	v_mul_f32_e32 v106, 0xbfb8aa3b, v96
	v_exp_f32_e32 v106, v106
	v_exp_f32_e32 v107, v107
	v_rcp_f32_e32 v103, v104
	s_nop 0
	v_mul_f32_e32 v102, v102, v103
	v_pk_add_f32 v[106:107], v[106:107], 1.0 op_sel_hi:[1,0]
	v_cvt_pk_bf16_f32 v101, v102, v101
	global_store_dwordx2 v[108:109], v[100:101], off offset:64
	v_rcp_f32_e32 v100, v107
	s_nop 0
	v_mul_f32_e32 v97, v97, v100
	v_mul_f32_e32 v100, 0xbfb8aa3b, v98
	v_mul_f32_e32 v101, 0xbfb8aa3b, v99
	v_exp_f32_e32 v100, v100
	v_exp_f32_e32 v101, v101
	s_nop 0
	v_pk_add_f32 v[100:101], v[100:101], 1.0 op_sel_hi:[1,0]
	v_rcp_f32_e32 v102, v106
	s_nop 0
	v_mul_f32_e32 v96, v96, v102
	v_cvt_pk_bf16_f32 v96, v96, v97
	v_rcp_f32_e32 v97, v101
	s_nop 0
	v_mul_f32_e32 v97, v99, v97
	v_mul_f32_e32 v101, 0xbfb8aa3b, v92
	v_exp_f32_e32 v102, v101
	v_mul_f32_e32 v101, 0xbfb8aa3b, v93
	v_exp_f32_e32 v103, v101
	v_rcp_f32_e32 v99, v100
	s_nop 0
	v_mul_f32_e32 v98, v98, v99
	v_cvt_pk_bf16_f32 v97, v98, v97
	global_store_dwordx2 v[108:109], v[96:97], off offset:96
	v_pk_add_f32 v[96:97], v[102:103], 1.0 op_sel_hi:[1,0]
	v_or_b32_e32 v98, 32, v140
	v_ashrrev_i32_e32 v99, 31, v98
	v_lshlrev_b64 v[98:99], 12, v[98:99]
	v_rcp_f32_e32 v100, v97
	s_nop 0
	v_mul_f32_e32 v93, v93, v100
	v_mul_f32_e32 v100, 0xbfb8aa3b, v94
	v_mul_f32_e32 v101, 0xbfb8aa3b, v95
	v_exp_f32_e32 v100, v100
	v_exp_f32_e32 v101, v101
	s_nop 0
	v_pk_add_f32 v[100:101], v[100:101], 1.0 op_sel_hi:[1,0]
	v_rcp_f32_e32 v97, v96
	s_nop 0
	v_mul_f32_e32 v92, v92, v97
	v_cvt_pk_bf16_f32 v96, v92, v93
	v_rcp_f32_e32 v92, v101
	s_nop 0
	v_mul_f32_e32 v95, v95, v92
	v_mul_f32_e32 v92, 0xbfb8aa3b, v88
	v_mul_f32_e32 v93, 0xbfb8aa3b, v89
	v_exp_f32_e32 v92, v92
	v_exp_f32_e32 v93, v93
	v_rcp_f32_e32 v97, v100
	s_nop 0
	v_mul_f32_e32 v94, v94, v97
	v_cvt_pk_bf16_f32 v97, v94, v95
	v_pk_add_f32 v[94:95], v[92:93], 1.0 op_sel_hi:[1,0]
	v_lshl_add_u64 v[92:93], s[68:69], 0, v[98:99]
	v_lshl_add_u64 v[92:93], v[92:93], 0, v[124:125]
	global_store_dwordx2 v[92:93], v[96:97], off
	v_rcp_f32_e32 v96, v95
	s_nop 0
	v_mul_f32_e32 v89, v89, v96
	v_mul_f32_e32 v96, 0xbfb8aa3b, v90
	v_mul_f32_e32 v97, 0xbfb8aa3b, v91
	v_exp_f32_e32 v96, v96
	v_exp_f32_e32 v97, v97
	s_nop 0
	v_pk_add_f32 v[96:97], v[96:97], 1.0 op_sel_hi:[1,0]
	v_rcp_f32_e32 v95, v94
	s_nop 0
	v_mul_f32_e32 v88, v88, v95
	v_cvt_pk_bf16_f32 v88, v88, v89
	v_rcp_f32_e32 v89, v97
	s_nop 0
	v_mul_f32_e32 v89, v91, v89
	v_mul_f32_e32 v95, 0xbfb8aa3b, v85
	v_mul_f32_e32 v94, 0xbfb8aa3b, v84
	v_exp_f32_e32 v94, v94
	v_exp_f32_e32 v95, v95
	v_rcp_f32_e32 v91, v96
	s_nop 0
	v_mul_f32_e32 v90, v90, v91
	v_pk_add_f32 v[94:95], v[94:95], 1.0 op_sel_hi:[1,0]
	v_cvt_pk_bf16_f32 v89, v90, v89
	global_store_dwordx2 v[92:93], v[88:89], off offset:32
	v_rcp_f32_e32 v88, v95
	s_nop 0
	v_mul_f32_e32 v85, v85, v88
	v_mul_f32_e32 v88, 0xbfb8aa3b, v86
	v_mul_f32_e32 v89, 0xbfb8aa3b, v87
	v_exp_f32_e32 v88, v88
	v_exp_f32_e32 v89, v89
	s_nop 0
	v_pk_add_f32 v[88:89], v[88:89], 1.0 op_sel_hi:[1,0]
	v_rcp_f32_e32 v90, v94
	s_nop 0
	v_mul_f32_e32 v84, v84, v90
	v_cvt_pk_bf16_f32 v84, v84, v85
	v_rcp_f32_e32 v85, v89
	s_nop 0
	v_mul_f32_e32 v85, v87, v85
	v_mul_f32_e32 v91, 0xbfb8aa3b, v81
	v_mul_f32_e32 v90, 0xbfb8aa3b, v80
	v_exp_f32_e32 v90, v90
	v_exp_f32_e32 v91, v91
	v_rcp_f32_e32 v87, v88
	s_nop 0
	v_mul_f32_e32 v86, v86, v87
	v_pk_add_f32 v[90:91], v[90:91], 1.0 op_sel_hi:[1,0]
	v_cvt_pk_bf16_f32 v85, v86, v85
	global_store_dwordx2 v[92:93], v[84:85], off offset:64
	v_rcp_f32_e32 v84, v91
	s_nop 0
	v_mul_f32_e32 v81, v81, v84
	v_mul_f32_e32 v84, 0xbfb8aa3b, v82
	v_mul_f32_e32 v85, 0xbfb8aa3b, v83
	v_exp_f32_e32 v84, v84
	v_exp_f32_e32 v85, v85
	s_nop 0
	v_pk_add_f32 v[84:85], v[84:85], 1.0 op_sel_hi:[1,0]
	v_rcp_f32_e32 v86, v90
	s_nop 0
	v_mul_f32_e32 v80, v80, v86
	v_cvt_pk_bf16_f32 v80, v80, v81
	v_rcp_f32_e32 v81, v85
	s_nop 0
	v_mul_f32_e32 v81, v83, v81
	v_mul_f32_e32 v85, 0xbfb8aa3b, v76
	v_exp_f32_e32 v86, v85
	v_mul_f32_e32 v85, 0xbfb8aa3b, v77
	v_exp_f32_e32 v87, v85
	v_rcp_f32_e32 v83, v84
	s_nop 0
	v_mul_f32_e32 v82, v82, v83
	v_cvt_pk_bf16_f32 v81, v82, v81
	global_store_dwordx2 v[92:93], v[80:81], off offset:96
	v_pk_add_f32 v[80:81], v[86:87], 1.0 op_sel_hi:[1,0]
	v_or_b32_e32 v82, 48, v140
	v_ashrrev_i32_e32 v83, 31, v82
	v_lshlrev_b64 v[82:83], 12, v[82:83]
	v_rcp_f32_e32 v84, v81
	s_nop 0
	v_mul_f32_e32 v77, v77, v84
	v_mul_f32_e32 v84, 0xbfb8aa3b, v78
	v_mul_f32_e32 v85, 0xbfb8aa3b, v79
	v_exp_f32_e32 v84, v84
	v_exp_f32_e32 v85, v85
	s_nop 0
	v_pk_add_f32 v[84:85], v[84:85], 1.0 op_sel_hi:[1,0]
	v_rcp_f32_e32 v81, v80
	s_nop 0
	v_mul_f32_e32 v76, v76, v81
	v_cvt_pk_bf16_f32 v80, v76, v77
	v_rcp_f32_e32 v76, v85
	s_nop 0
	v_mul_f32_e32 v79, v79, v76
	v_mul_f32_e32 v76, 0xbfb8aa3b, v72
	v_mul_f32_e32 v77, 0xbfb8aa3b, v73
	v_exp_f32_e32 v76, v76
	v_exp_f32_e32 v77, v77
	v_rcp_f32_e32 v81, v84
	s_nop 0
	v_mul_f32_e32 v78, v78, v81
	v_cvt_pk_bf16_f32 v81, v78, v79
	v_pk_add_f32 v[78:79], v[76:77], 1.0 op_sel_hi:[1,0]
	v_lshl_add_u64 v[76:77], s[68:69], 0, v[82:83]
	v_lshl_add_u64 v[76:77], v[76:77], 0, v[124:125]
	global_store_dwordx2 v[76:77], v[80:81], off
	v_rcp_f32_e32 v80, v79
	s_nop 0
	v_mul_f32_e32 v73, v73, v80
	v_mul_f32_e32 v80, 0xbfb8aa3b, v74
	v_mul_f32_e32 v81, 0xbfb8aa3b, v75
	v_exp_f32_e32 v80, v80
	v_exp_f32_e32 v81, v81
	s_nop 0
	v_pk_add_f32 v[80:81], v[80:81], 1.0 op_sel_hi:[1,0]
	v_rcp_f32_e32 v79, v78
	s_nop 0
	v_mul_f32_e32 v72, v72, v79
	v_cvt_pk_bf16_f32 v72, v72, v73
	v_rcp_f32_e32 v73, v81
	s_nop 0
	v_mul_f32_e32 v73, v75, v73
	v_mul_f32_e32 v79, 0xbfb8aa3b, v69
	v_mul_f32_e32 v78, 0xbfb8aa3b, v68
	v_exp_f32_e32 v78, v78
	v_exp_f32_e32 v79, v79
	v_rcp_f32_e32 v75, v80
	s_nop 0
	v_mul_f32_e32 v74, v74, v75
	v_pk_add_f32 v[78:79], v[78:79], 1.0 op_sel_hi:[1,0]
	v_cvt_pk_bf16_f32 v73, v74, v73
	global_store_dwordx2 v[76:77], v[72:73], off offset:32
	v_rcp_f32_e32 v72, v79
	s_nop 0
	v_mul_f32_e32 v69, v69, v72
	v_mul_f32_e32 v72, 0xbfb8aa3b, v70
	v_mul_f32_e32 v73, 0xbfb8aa3b, v71
	v_exp_f32_e32 v72, v72
	v_exp_f32_e32 v73, v73
	s_nop 0
	v_pk_add_f32 v[72:73], v[72:73], 1.0 op_sel_hi:[1,0]
	v_rcp_f32_e32 v74, v78
	s_nop 0
	v_mul_f32_e32 v68, v68, v74
	v_cvt_pk_bf16_f32 v68, v68, v69
	v_rcp_f32_e32 v69, v73
	s_nop 0
	v_mul_f32_e32 v69, v71, v69
	v_mul_f32_e32 v75, 0xbfb8aa3b, v65
	v_mul_f32_e32 v74, 0xbfb8aa3b, v64
	v_exp_f32_e32 v74, v74
	v_exp_f32_e32 v75, v75
	v_rcp_f32_e32 v71, v72
	s_nop 0
	v_mul_f32_e32 v70, v70, v71
	v_pk_add_f32 v[74:75], v[74:75], 1.0 op_sel_hi:[1,0]
	v_cvt_pk_bf16_f32 v69, v70, v69
	global_store_dwordx2 v[76:77], v[68:69], off offset:64
	v_rcp_f32_e32 v68, v75
	s_nop 0
	v_mul_f32_e32 v65, v65, v68
	v_mul_f32_e32 v68, 0xbfb8aa3b, v66
	v_mul_f32_e32 v69, 0xbfb8aa3b, v67
	v_exp_f32_e32 v68, v68
	v_exp_f32_e32 v69, v69
	s_nop 0
	v_pk_add_f32 v[68:69], v[68:69], 1.0 op_sel_hi:[1,0]
	v_rcp_f32_e32 v70, v74
	s_nop 0
	v_mul_f32_e32 v64, v64, v70
	v_cvt_pk_bf16_f32 v64, v64, v65
	v_rcp_f32_e32 v65, v69
	s_nop 0
	v_mul_f32_e32 v65, v67, v65
	v_mul_f32_e32 v69, 0xbfb8aa3b, v60
	v_exp_f32_e32 v70, v69
	v_mul_f32_e32 v69, 0xbfb8aa3b, v61
	v_exp_f32_e32 v71, v69
	v_rcp_f32_e32 v67, v68
	s_nop 0
	v_mul_f32_e32 v66, v66, v67
	v_cvt_pk_bf16_f32 v65, v66, v65
	global_store_dwordx2 v[76:77], v[64:65], off offset:96
	v_pk_add_f32 v[64:65], v[70:71], 1.0 op_sel_hi:[1,0]
	v_or_b32_e32 v66, 64, v140
	v_ashrrev_i32_e32 v67, 31, v66
	v_lshlrev_b64 v[66:67], 12, v[66:67]
	v_rcp_f32_e32 v68, v65
	s_nop 0
	v_mul_f32_e32 v61, v61, v68
	v_mul_f32_e32 v68, 0xbfb8aa3b, v62
	v_mul_f32_e32 v69, 0xbfb8aa3b, v63
	v_exp_f32_e32 v68, v68
	v_exp_f32_e32 v69, v69
	s_nop 0
	v_pk_add_f32 v[68:69], v[68:69], 1.0 op_sel_hi:[1,0]
	v_rcp_f32_e32 v65, v64
	s_nop 0
	v_mul_f32_e32 v60, v60, v65
	v_cvt_pk_bf16_f32 v64, v60, v61
	v_rcp_f32_e32 v60, v69
	s_nop 0
	v_mul_f32_e32 v63, v63, v60
	v_mul_f32_e32 v60, 0xbfb8aa3b, v56
	v_mul_f32_e32 v61, 0xbfb8aa3b, v57
	v_exp_f32_e32 v60, v60
	v_exp_f32_e32 v61, v61
	v_rcp_f32_e32 v65, v68
	s_nop 0
	v_mul_f32_e32 v62, v62, v65
	v_cvt_pk_bf16_f32 v65, v62, v63
	v_pk_add_f32 v[62:63], v[60:61], 1.0 op_sel_hi:[1,0]
	v_lshl_add_u64 v[60:61], s[68:69], 0, v[66:67]
	v_lshl_add_u64 v[60:61], v[60:61], 0, v[124:125]
	global_store_dwordx2 v[60:61], v[64:65], off
	v_rcp_f32_e32 v64, v63
	s_nop 0
	v_mul_f32_e32 v57, v57, v64
	v_mul_f32_e32 v64, 0xbfb8aa3b, v58
	v_mul_f32_e32 v65, 0xbfb8aa3b, v59
	v_exp_f32_e32 v64, v64
	v_exp_f32_e32 v65, v65
	s_nop 0
	v_pk_add_f32 v[64:65], v[64:65], 1.0 op_sel_hi:[1,0]
	v_rcp_f32_e32 v63, v62
	s_nop 0
	v_mul_f32_e32 v56, v56, v63
	v_cvt_pk_bf16_f32 v56, v56, v57
	v_rcp_f32_e32 v57, v65
	s_nop 0
	v_mul_f32_e32 v57, v59, v57
	v_mul_f32_e32 v63, 0xbfb8aa3b, v53
	v_mul_f32_e32 v62, 0xbfb8aa3b, v52
	v_exp_f32_e32 v62, v62
	v_exp_f32_e32 v63, v63
	v_rcp_f32_e32 v59, v64
	s_nop 0
	v_mul_f32_e32 v58, v58, v59
	v_pk_add_f32 v[62:63], v[62:63], 1.0 op_sel_hi:[1,0]
	v_cvt_pk_bf16_f32 v57, v58, v57
	global_store_dwordx2 v[60:61], v[56:57], off offset:32
	v_rcp_f32_e32 v56, v63
	s_nop 0
	v_mul_f32_e32 v53, v53, v56
	v_mul_f32_e32 v56, 0xbfb8aa3b, v54
	v_mul_f32_e32 v57, 0xbfb8aa3b, v55
	v_exp_f32_e32 v56, v56
	v_exp_f32_e32 v57, v57
	s_nop 0
	v_pk_add_f32 v[56:57], v[56:57], 1.0 op_sel_hi:[1,0]
	v_rcp_f32_e32 v58, v62
	s_nop 0
	v_mul_f32_e32 v52, v52, v58
	v_cvt_pk_bf16_f32 v52, v52, v53
	v_rcp_f32_e32 v53, v57
	s_nop 0
	v_mul_f32_e32 v53, v55, v53
	v_mul_f32_e32 v59, 0xbfb8aa3b, v49
	v_mul_f32_e32 v58, 0xbfb8aa3b, v48
	v_exp_f32_e32 v58, v58
	v_exp_f32_e32 v59, v59
	v_rcp_f32_e32 v55, v56
	s_nop 0
	v_mul_f32_e32 v54, v54, v55
	v_pk_add_f32 v[58:59], v[58:59], 1.0 op_sel_hi:[1,0]
	v_cvt_pk_bf16_f32 v53, v54, v53
	global_store_dwordx2 v[60:61], v[52:53], off offset:64
	v_rcp_f32_e32 v52, v59
	s_nop 0
	v_mul_f32_e32 v49, v49, v52
	v_mul_f32_e32 v52, 0xbfb8aa3b, v50
	v_mul_f32_e32 v53, 0xbfb8aa3b, v51
	v_exp_f32_e32 v52, v52
	v_exp_f32_e32 v53, v53
	s_nop 0
	v_pk_add_f32 v[52:53], v[52:53], 1.0 op_sel_hi:[1,0]
	v_rcp_f32_e32 v54, v58
	s_nop 0
	v_mul_f32_e32 v48, v48, v54
	v_cvt_pk_bf16_f32 v48, v48, v49
	v_rcp_f32_e32 v49, v53
	s_nop 0
	v_mul_f32_e32 v49, v51, v49
	v_mul_f32_e32 v53, 0xbfb8aa3b, v44
	v_exp_f32_e32 v54, v53
	v_mul_f32_e32 v53, 0xbfb8aa3b, v45
	v_exp_f32_e32 v55, v53
	v_rcp_f32_e32 v51, v52
	s_nop 0
	v_mul_f32_e32 v50, v50, v51
	v_cvt_pk_bf16_f32 v49, v50, v49
	global_store_dwordx2 v[60:61], v[48:49], off offset:96
	v_pk_add_f32 v[48:49], v[54:55], 1.0 op_sel_hi:[1,0]
	v_or_b32_e32 v50, 0x50, v140
	v_ashrrev_i32_e32 v51, 31, v50
	v_lshlrev_b64 v[50:51], 12, v[50:51]
	v_rcp_f32_e32 v52, v49
	s_nop 0
	v_mul_f32_e32 v45, v45, v52
	v_mul_f32_e32 v52, 0xbfb8aa3b, v46
	v_mul_f32_e32 v53, 0xbfb8aa3b, v47
	v_exp_f32_e32 v52, v52
	v_exp_f32_e32 v53, v53
	s_nop 0
	v_pk_add_f32 v[52:53], v[52:53], 1.0 op_sel_hi:[1,0]
	v_rcp_f32_e32 v49, v48
	s_nop 0
	v_mul_f32_e32 v44, v44, v49
	v_cvt_pk_bf16_f32 v48, v44, v45
	v_rcp_f32_e32 v44, v53
	s_nop 0
	v_mul_f32_e32 v47, v47, v44
	v_mul_f32_e32 v44, 0xbfb8aa3b, v40
	v_mul_f32_e32 v45, 0xbfb8aa3b, v41
	v_exp_f32_e32 v44, v44
	v_exp_f32_e32 v45, v45
	v_rcp_f32_e32 v49, v52
	s_nop 0
	v_mul_f32_e32 v46, v46, v49
	v_cvt_pk_bf16_f32 v49, v46, v47
	v_pk_add_f32 v[46:47], v[44:45], 1.0 op_sel_hi:[1,0]
	v_lshl_add_u64 v[44:45], s[68:69], 0, v[50:51]
	v_lshl_add_u64 v[44:45], v[44:45], 0, v[124:125]
	global_store_dwordx2 v[44:45], v[48:49], off
	v_rcp_f32_e32 v48, v47
	s_nop 0
	v_mul_f32_e32 v41, v41, v48
	v_mul_f32_e32 v48, 0xbfb8aa3b, v42
	v_mul_f32_e32 v49, 0xbfb8aa3b, v43
	v_exp_f32_e32 v48, v48
	v_exp_f32_e32 v49, v49
	s_nop 0
	v_pk_add_f32 v[48:49], v[48:49], 1.0 op_sel_hi:[1,0]
	v_rcp_f32_e32 v47, v46
	s_nop 0
	v_mul_f32_e32 v40, v40, v47
	v_cvt_pk_bf16_f32 v40, v40, v41
	v_rcp_f32_e32 v41, v49
	s_nop 0
	v_mul_f32_e32 v41, v43, v41
	v_mul_f32_e32 v47, 0xbfb8aa3b, v37
	v_mul_f32_e32 v46, 0xbfb8aa3b, v36
	v_exp_f32_e32 v46, v46
	v_exp_f32_e32 v47, v47
	v_rcp_f32_e32 v43, v48
	s_nop 0
	v_mul_f32_e32 v42, v42, v43
	v_pk_add_f32 v[46:47], v[46:47], 1.0 op_sel_hi:[1,0]
	v_cvt_pk_bf16_f32 v41, v42, v41
	global_store_dwordx2 v[44:45], v[40:41], off offset:32
	v_rcp_f32_e32 v40, v47
	s_nop 0
	v_mul_f32_e32 v37, v37, v40
	v_mul_f32_e32 v40, 0xbfb8aa3b, v38
	v_mul_f32_e32 v41, 0xbfb8aa3b, v39
	v_exp_f32_e32 v40, v40
	v_exp_f32_e32 v41, v41
	s_nop 0
	v_pk_add_f32 v[40:41], v[40:41], 1.0 op_sel_hi:[1,0]
	v_rcp_f32_e32 v42, v46
	s_nop 0
	v_mul_f32_e32 v36, v36, v42
	v_cvt_pk_bf16_f32 v36, v36, v37
	v_rcp_f32_e32 v37, v41
	s_nop 0
	v_mul_f32_e32 v37, v39, v37
	v_mul_f32_e32 v43, 0xbfb8aa3b, v33
	v_mul_f32_e32 v42, 0xbfb8aa3b, v32
	v_exp_f32_e32 v42, v42
	v_exp_f32_e32 v43, v43
	v_rcp_f32_e32 v39, v40
	s_nop 0
	v_mul_f32_e32 v38, v38, v39
	v_pk_add_f32 v[42:43], v[42:43], 1.0 op_sel_hi:[1,0]
	v_cvt_pk_bf16_f32 v37, v38, v37
	global_store_dwordx2 v[44:45], v[36:37], off offset:64
	v_rcp_f32_e32 v36, v43
	s_nop 0
	v_mul_f32_e32 v33, v33, v36
	v_mul_f32_e32 v36, 0xbfb8aa3b, v34
	v_mul_f32_e32 v37, 0xbfb8aa3b, v35
	v_exp_f32_e32 v36, v36
	v_exp_f32_e32 v37, v37
	s_nop 0
	v_pk_add_f32 v[36:37], v[36:37], 1.0 op_sel_hi:[1,0]
	v_rcp_f32_e32 v38, v42
	s_nop 0
	v_mul_f32_e32 v32, v32, v38
	v_cvt_pk_bf16_f32 v32, v32, v33
	v_rcp_f32_e32 v33, v37
	s_nop 0
	v_mul_f32_e32 v33, v35, v33
	v_mul_f32_e32 v37, 0xbfb8aa3b, v28
	v_exp_f32_e32 v38, v37
	v_mul_f32_e32 v37, 0xbfb8aa3b, v29
	v_exp_f32_e32 v39, v37
	v_rcp_f32_e32 v35, v36
	s_nop 0
	v_mul_f32_e32 v34, v34, v35
	v_cvt_pk_bf16_f32 v33, v34, v33
	global_store_dwordx2 v[44:45], v[32:33], off offset:96
	v_pk_add_f32 v[32:33], v[38:39], 1.0 op_sel_hi:[1,0]
	v_or_b32_e32 v34, 0x60, v140
	v_ashrrev_i32_e32 v35, 31, v34
	v_lshlrev_b64 v[34:35], 12, v[34:35]
	v_rcp_f32_e32 v36, v33
	s_nop 0
	v_mul_f32_e32 v29, v29, v36
	v_mul_f32_e32 v36, 0xbfb8aa3b, v30
	v_mul_f32_e32 v37, 0xbfb8aa3b, v31
	v_exp_f32_e32 v36, v36
	v_exp_f32_e32 v37, v37
	s_nop 0
	v_pk_add_f32 v[36:37], v[36:37], 1.0 op_sel_hi:[1,0]
	v_rcp_f32_e32 v33, v32
	s_nop 0
	v_mul_f32_e32 v28, v28, v33
	v_cvt_pk_bf16_f32 v32, v28, v29
	v_rcp_f32_e32 v28, v37
	s_nop 0
	v_mul_f32_e32 v31, v31, v28
	v_mul_f32_e32 v28, 0xbfb8aa3b, v24
	v_mul_f32_e32 v29, 0xbfb8aa3b, v25
	v_exp_f32_e32 v28, v28
	v_exp_f32_e32 v29, v29
	v_rcp_f32_e32 v33, v36
	s_nop 0
	v_mul_f32_e32 v30, v30, v33
	v_cvt_pk_bf16_f32 v33, v30, v31
	v_pk_add_f32 v[30:31], v[28:29], 1.0 op_sel_hi:[1,0]
	v_lshl_add_u64 v[28:29], s[68:69], 0, v[34:35]
	v_lshl_add_u64 v[28:29], v[28:29], 0, v[124:125]
	global_store_dwordx2 v[28:29], v[32:33], off
	v_rcp_f32_e32 v32, v31
	s_nop 0
	v_mul_f32_e32 v25, v25, v32
	v_mul_f32_e32 v32, 0xbfb8aa3b, v26
	v_mul_f32_e32 v33, 0xbfb8aa3b, v27
	v_exp_f32_e32 v32, v32
	v_exp_f32_e32 v33, v33
	s_nop 0
	v_pk_add_f32 v[32:33], v[32:33], 1.0 op_sel_hi:[1,0]
	v_rcp_f32_e32 v31, v30
	s_nop 0
	v_mul_f32_e32 v24, v24, v31
	v_cvt_pk_bf16_f32 v24, v24, v25
	v_rcp_f32_e32 v25, v33
	s_nop 0
	v_mul_f32_e32 v25, v27, v25
	v_mul_f32_e32 v31, 0xbfb8aa3b, v21
	v_mul_f32_e32 v30, 0xbfb8aa3b, v20
	v_exp_f32_e32 v30, v30
	v_exp_f32_e32 v31, v31
	v_rcp_f32_e32 v27, v32
	s_nop 0
	v_mul_f32_e32 v26, v26, v27
	v_pk_add_f32 v[30:31], v[30:31], 1.0 op_sel_hi:[1,0]
	v_cvt_pk_bf16_f32 v25, v26, v25
	global_store_dwordx2 v[28:29], v[24:25], off offset:32
	v_rcp_f32_e32 v24, v31
	s_nop 0
	v_mul_f32_e32 v21, v21, v24
	v_mul_f32_e32 v24, 0xbfb8aa3b, v22
	v_mul_f32_e32 v25, 0xbfb8aa3b, v23
	v_exp_f32_e32 v24, v24
	v_exp_f32_e32 v25, v25
	s_nop 0
	v_pk_add_f32 v[24:25], v[24:25], 1.0 op_sel_hi:[1,0]
	v_rcp_f32_e32 v26, v30
	s_nop 0
	v_mul_f32_e32 v20, v20, v26
	v_cvt_pk_bf16_f32 v20, v20, v21
	v_rcp_f32_e32 v21, v25
	s_nop 0
	v_mul_f32_e32 v21, v23, v21
	v_mul_f32_e32 v27, 0xbfb8aa3b, v17
	v_mul_f32_e32 v26, 0xbfb8aa3b, v16
	v_exp_f32_e32 v26, v26
	v_exp_f32_e32 v27, v27
	v_rcp_f32_e32 v23, v24
	s_nop 0
	v_mul_f32_e32 v22, v22, v23
	v_pk_add_f32 v[26:27], v[26:27], 1.0 op_sel_hi:[1,0]
	v_cvt_pk_bf16_f32 v21, v22, v21
	global_store_dwordx2 v[28:29], v[20:21], off offset:64
	v_rcp_f32_e32 v20, v27
	s_nop 0
	v_mul_f32_e32 v17, v17, v20
	v_mul_f32_e32 v20, 0xbfb8aa3b, v18
	v_mul_f32_e32 v21, 0xbfb8aa3b, v19
	v_exp_f32_e32 v20, v20
	v_exp_f32_e32 v21, v21
	s_nop 0
	v_pk_add_f32 v[20:21], v[20:21], 1.0 op_sel_hi:[1,0]
	v_rcp_f32_e32 v22, v26
	s_nop 0
	v_mul_f32_e32 v16, v16, v22
	v_cvt_pk_bf16_f32 v16, v16, v17
	v_rcp_f32_e32 v17, v21
	s_nop 0
	v_mul_f32_e32 v17, v19, v17
	v_mul_f32_e32 v21, 0xbfb8aa3b, v12
	v_exp_f32_e32 v22, v21
	v_mul_f32_e32 v21, 0xbfb8aa3b, v13
	v_exp_f32_e32 v23, v21
	v_rcp_f32_e32 v19, v20
	s_nop 0
	v_mul_f32_e32 v18, v18, v19
	v_cvt_pk_bf16_f32 v17, v18, v17
	global_store_dwordx2 v[28:29], v[16:17], off offset:96
	v_pk_add_f32 v[16:17], v[22:23], 1.0 op_sel_hi:[1,0]
	v_or_b32_e32 v18, 0x70, v140
	v_ashrrev_i32_e32 v19, 31, v18
	v_lshlrev_b64 v[18:19], 12, v[18:19]
	v_rcp_f32_e32 v20, v17
	s_nop 0
	v_mul_f32_e32 v13, v13, v20
	v_mul_f32_e32 v20, 0xbfb8aa3b, v14
	v_mul_f32_e32 v21, 0xbfb8aa3b, v15
	v_exp_f32_e32 v20, v20
	v_exp_f32_e32 v21, v21
	s_nop 0
	v_pk_add_f32 v[20:21], v[20:21], 1.0 op_sel_hi:[1,0]
	v_rcp_f32_e32 v17, v16
	s_nop 0
	v_mul_f32_e32 v12, v12, v17
	v_cvt_pk_bf16_f32 v16, v12, v13
	v_rcp_f32_e32 v12, v21
	s_nop 0
	v_mul_f32_e32 v15, v15, v12
	v_mul_f32_e32 v12, 0xbfb8aa3b, v8
	v_mul_f32_e32 v13, 0xbfb8aa3b, v9
	v_exp_f32_e32 v12, v12
	v_exp_f32_e32 v13, v13
	v_rcp_f32_e32 v17, v20
	s_nop 0
	v_mul_f32_e32 v14, v14, v17
	v_cvt_pk_bf16_f32 v17, v14, v15
	v_pk_add_f32 v[14:15], v[12:13], 1.0 op_sel_hi:[1,0]
	v_lshl_add_u64 v[12:13], s[68:69], 0, v[18:19]
	v_lshl_add_u64 v[12:13], v[12:13], 0, v[124:125]
	global_store_dwordx2 v[12:13], v[16:17], off
	v_rcp_f32_e32 v16, v15
	s_nop 0
	v_mul_f32_e32 v9, v9, v16
	v_mul_f32_e32 v16, 0xbfb8aa3b, v10
	v_mul_f32_e32 v17, 0xbfb8aa3b, v11
	v_exp_f32_e32 v16, v16
	v_exp_f32_e32 v17, v17
	s_nop 0
	v_pk_add_f32 v[16:17], v[16:17], 1.0 op_sel_hi:[1,0]
	v_rcp_f32_e32 v15, v14
	s_nop 0
	v_mul_f32_e32 v8, v8, v15
	v_cvt_pk_bf16_f32 v8, v8, v9
	v_rcp_f32_e32 v9, v17
	s_nop 0
	v_mul_f32_e32 v9, v11, v9
	v_mul_f32_e32 v15, 0xbfb8aa3b, v5
	v_mul_f32_e32 v14, 0xbfb8aa3b, v4
	v_exp_f32_e32 v14, v14
	v_exp_f32_e32 v15, v15
	v_rcp_f32_e32 v11, v16
	s_nop 0
	v_mul_f32_e32 v10, v10, v11
	v_pk_add_f32 v[14:15], v[14:15], 1.0 op_sel_hi:[1,0]
	v_cvt_pk_bf16_f32 v9, v10, v9
	global_store_dwordx2 v[12:13], v[8:9], off offset:32
	v_rcp_f32_e32 v8, v15
	s_nop 0
	v_mul_f32_e32 v5, v5, v8
	v_mul_f32_e32 v8, 0xbfb8aa3b, v6
	v_mul_f32_e32 v9, 0xbfb8aa3b, v7
	v_exp_f32_e32 v8, v8
	v_exp_f32_e32 v9, v9
	s_nop 0
	v_pk_add_f32 v[8:9], v[8:9], 1.0 op_sel_hi:[1,0]
	v_rcp_f32_e32 v10, v14
	s_nop 0
	v_mul_f32_e32 v4, v4, v10
	v_cvt_pk_bf16_f32 v4, v4, v5
	v_rcp_f32_e32 v5, v9
	s_nop 0
	v_mul_f32_e32 v5, v7, v5
	v_mul_f32_e32 v11, 0xbfb8aa3b, v1
	v_mul_f32_e32 v10, 0xbfb8aa3b, v0
	v_exp_f32_e32 v10, v10
	v_exp_f32_e32 v11, v11
	v_rcp_f32_e32 v7, v8
	s_nop 0
	v_mul_f32_e32 v6, v6, v7
	v_pk_add_f32 v[10:11], v[10:11], 1.0 op_sel_hi:[1,0]
	v_cvt_pk_bf16_f32 v5, v6, v5
	global_store_dwordx2 v[12:13], v[4:5], off offset:64
	v_rcp_f32_e32 v4, v11
	s_nop 0
	v_mul_f32_e32 v1, v1, v4
	v_mul_f32_e32 v4, 0xbfb8aa3b, v2
	v_mul_f32_e32 v5, 0xbfb8aa3b, v3
	v_exp_f32_e32 v4, v4
	v_exp_f32_e32 v5, v5
	s_nop 0
	v_pk_add_f32 v[4:5], v[4:5], 1.0 op_sel_hi:[1,0]
	v_rcp_f32_e32 v6, v10
	s_nop 0
	v_mul_f32_e32 v0, v0, v6
	v_cvt_pk_bf16_f32 v0, v0, v1
	v_rcp_f32_e32 v1, v5
	s_nop 0
	v_mul_f32_e32 v1, v3, v1
	v_rcp_f32_e32 v3, v4
	s_nop 0
	v_mul_f32_e32 v2, v2, v3
	v_cvt_pk_bf16_f32 v1, v2, v1
	s_and_b64 vcc, exec, s[26:27]
	global_store_dwordx2 v[12:13], v[0:1], off offset:96
	s_cbranch_vccnz .LBB0_1143

.LBB0_1246:
	s_add_i32 s4, s38, 0xfffff000
	s_cmp_gt_u32 s4, 0xfffff3ff
	s_cselect_b64 s[8:9], -1, 0
	v_or_b32_e32 v142, s38, v153
	s_mov_b64 s[2:3], -1
	s_and_b64 vcc, exec, s[8:9]
	s_cbranch_vccz .LBB0_1250
	s_cmpk_gt_u32 s38, 0xbff
	v_mov_b32_e32 v143, v127
	v_mov_b32_e32 v141, v126
	v_mov_b32_e32 v139, v125
	v_mov_b32_e32 v128, v124
	s_cbranch_scc1 .LBB0_1249
	v_mov_b32_e32 v143, v129
	v_lshl_add_u64 v[144:145], v[142:143], 2, s[68:69]
	v_add_co_u32_e32 v144, vcc, 0x14103000, v144
	v_mul_f32_e32 v128, 0xbfb8aa3b, v124
	s_nop 0
	v_addc_co_u32_e32 v145, vcc, 0, v145, vcc
	global_load_dwordx4 v[144:147], v[144:145], off
	v_mul_f32_e32 v139, 0xbfb8aa3b, v125
	v_exp_f32_e32 v128, v128
	v_mul_f32_e32 v141, 0xbfb8aa3b, v126
	v_exp_f32_e32 v139, v139
	v_mul_f32_e32 v143, 0xbfb8aa3b, v127
	v_exp_f32_e32 v141, v141
	v_exp_f32_e32 v143, v143
	v_add_f32_e32 v128, 1.0, v128
	v_add_f32_e32 v139, 1.0, v139
	v_add_f32_e32 v141, 1.0, v141
	v_add_f32_e32 v143, 1.0, v143
	s_waitcnt vmcnt(0)
	v_sub_f32_e32 v148, 1.0, v144
	v_sub_f32_e32 v149, 1.0, v145
	v_sub_f32_e32 v155, 1.0, v146
	v_sub_f32_e32 v156, 1.0, v147
	s_mov_b64 vcc, s[2:3]
	v_rcp_f32_e32 v157, v128
	s_nop 0
	v_mul_f32_e32 v128, v148, v157
	s_mov_b64 vcc, s[4:5]
	v_add_f32_e32 v128, v144, v128
	s_mov_b64 vcc, s[6:7]
	v_rcp_f32_e32 v144, v141
	s_nop 0
	v_mul_f32_e32 v141, v155, v144
	v_rcp_f32_e32 v148, v139
	s_nop 0
	v_mul_f32_e32 v139, v149, v148
	v_rcp_f32_e32 v144, v143
	s_nop 0
	v_mul_f32_e32 v143, v156, v144
	v_add_f32_e32 v139, v145, v139
	v_add_f32_e32 v141, v146, v141
	v_add_f32_e32 v143, v147, v143
	v_log_f32_e32 v128, v128
	v_log_f32_e32 v139, v139
	v_log_f32_e32 v141, v141
	v_log_f32_e32 v143, v143

.LBB0_1250:
	s_andn2_b64 vcc, exec, s[2:3]
	s_cbranch_vccnz .LBB0_1252
	v_mul_f32_e32 v128, 0xbfb8aa3b, v124
	v_exp_f32_e32 v144, v128
	v_mul_f32_e32 v128, 0xbfb8aa3b, v125
	v_exp_f32_e32 v145, v128
	v_mul_f32_e32 v128, 0xbfb8aa3b, v126
	v_exp_f32_e32 v146, v128
	v_mul_f32_e32 v128, 0xbfb8aa3b, v127
	v_pk_add_f32 v[144:145], v[144:145], 1.0 op_sel_hi:[1,0]
	v_exp_f32_e32 v147, v128
	s_nop 0
	v_pk_add_f32 v[146:147], v[146:147], 1.0 op_sel_hi:[1,0]
	v_rcp_f32_e32 v128, v144
	s_nop 0
	v_mul_f32_e32 v128, v124, v128
	v_rcp_f32_e32 v124, v145
	s_nop 0
	v_mul_f32_e32 v139, v125, v124
	v_rcp_f32_e32 v124, v146
	s_nop 0
	v_mul_f32_e32 v141, v126, v124
	v_rcp_f32_e32 v124, v147
	s_nop 0
	v_mul_f32_e32 v143, v127, v124
.LBB0_1252:
	s_ashr_i32 s2, s72, 2
	v_add_u32_e32 v124, s67, v154
	s_mul_hi_i32 s3, s2, 0x3000000
	s_mul_i32 s2, s2, 0x3000000
	v_ashrrev_i32_e32 v125, 31, v124
	s_add_u32 s40, s68, s2
	v_lshlrev_b64 v[126:127], 11, v[124:125]
	s_addc_u32 s41, s69, s3
	v_and_b32_e32 v125, 0x3cc, v142
	v_cvt_pk_bf16_f32 v144, v128, v139
	v_lshl_add_u64 v[126:127], s[40:41], 0, v[126:127]
	v_lshlrev_b32_e32 v128, 1, v125
	v_cndmask_b32_e64 v125, 0, 1, s[8:9]
	v_cvt_pk_bf16_f32 v145, v141, v143
	v_lshl_add_u64 v[146:147], v[126:127], 0, v[128:129]
	v_cmp_ne_u32_e64 s[2:3], 1, v125
	s_andn2_b64 vcc, exec, s[8:9]
	s_mov_b64 s[4:5], -1
	global_store_dwordx2 v[146:147], v[144:145], off
	s_cbranch_vccnz .LBB0_1256
	s_cmpk_gt_u32 s38, 0xbff
	v_mov_b32_e32 v143, v123
	v_mov_b32_e32 v141, v122
	v_mov_b32_e32 v139, v121
	v_mov_b32_e32 v125, v120
	s_cbranch_scc1 .LBB0_1255
	v_mov_b32_e32 v143, v129
	v_lshl_add_u64 v[144:145], v[142:143], 2, s[68:69]
	v_add_co_u32_e32 v144, vcc, 0x14103000, v144
	v_mul_f32_e32 v125, 0xbfb8aa3b, v120
	s_nop 0
	v_addc_co_u32_e32 v145, vcc, 0, v145, vcc
	global_load_dwordx4 v[144:147], v[144:145], off offset:64
	v_mul_f32_e32 v139, 0xbfb8aa3b, v121
	v_exp_f32_e32 v125, v125
	v_mul_f32_e32 v141, 0xbfb8aa3b, v122
	v_exp_f32_e32 v139, v139
	v_mul_f32_e32 v143, 0xbfb8aa3b, v123
	v_exp_f32_e32 v141, v141
	v_exp_f32_e32 v143, v143
	v_add_f32_e32 v125, 1.0, v125
	v_add_f32_e32 v139, 1.0, v139
	v_add_f32_e32 v141, 1.0, v141
	v_add_f32_e32 v143, 1.0, v143
	s_waitcnt vmcnt(0)
	v_sub_f32_e32 v148, 1.0, v144
	v_sub_f32_e32 v149, 1.0, v145
	v_sub_f32_e32 v155, 1.0, v146
	v_sub_f32_e32 v156, 1.0, v147
	s_mov_b64 vcc, s[4:5]
	v_rcp_f32_e32 v157, v125
	s_nop 0
	v_mul_f32_e32 v125, v148, v157
	s_mov_b64 vcc, s[6:7]
	v_add_f32_e32 v125, v144, v125
	s_mov_b64 vcc, s[8:9]
	v_rcp_f32_e32 v144, v141
	s_nop 0
	v_mul_f32_e32 v141, v155, v144
	v_rcp_f32_e32 v148, v139
	s_nop 0
	v_mul_f32_e32 v139, v149, v148
	v_rcp_f32_e32 v144, v143
	s_nop 0
	v_mul_f32_e32 v143, v156, v144
	v_add_f32_e32 v139, v145, v139
	v_add_f32_e32 v141, v146, v141
	v_add_f32_e32 v143, v147, v143
	v_log_f32_e32 v125, v125
	v_log_f32_e32 v139, v139
	v_log_f32_e32 v141, v141
	v_log_f32_e32 v143, v143

.LBB0_1256:
	s_andn2_b64 vcc, exec, s[4:5]
	s_cbranch_vccnz .LBB0_1258
	v_mul_f32_e32 v125, 0xbfb8aa3b, v120
	v_exp_f32_e32 v144, v125
	v_mul_f32_e32 v125, 0xbfb8aa3b, v121
	v_exp_f32_e32 v145, v125
	v_mul_f32_e32 v125, 0xbfb8aa3b, v122
	v_exp_f32_e32 v146, v125
	v_mul_f32_e32 v125, 0xbfb8aa3b, v123
	v_pk_add_f32 v[144:145], v[144:145], 1.0 op_sel_hi:[1,0]
	v_exp_f32_e32 v147, v125
	s_nop 0
	v_pk_add_f32 v[146:147], v[146:147], 1.0 op_sel_hi:[1,0]
	v_rcp_f32_e32 v125, v144
	s_nop 0
	v_mul_f32_e32 v125, v120, v125
	v_rcp_f32_e32 v120, v145
	s_nop 0
	v_mul_f32_e32 v139, v121, v120
	v_rcp_f32_e32 v120, v146
	s_nop 0
	v_mul_f32_e32 v141, v122, v120
	v_rcp_f32_e32 v120, v147
	s_nop 0
	v_mul_f32_e32 v143, v123, v120
.LBB0_1258:
	v_bitop3_b32 v120, v142, s64, 16 bitop3:0xc8
	v_lshlrev_b32_e32 v120, 1, v120
	v_mov_b32_e32 v121, v129
	v_cvt_pk_bf16_f32 v122, v125, v139
	v_cvt_pk_bf16_f32 v123, v141, v143
	v_lshl_add_u64 v[144:145], v[126:127], 0, v[120:121]
	s_and_b64 vcc, exec, s[2:3]
	s_mov_b64 s[4:5], -1
	global_store_dwordx2 v[144:145], v[122:123], off
	s_cbranch_vccnz .LBB0_1262
	s_cmpk_gt_u32 s38, 0xbff
	v_mov_b32_e32 v125, v119
	v_mov_b32_e32 v123, v118
	v_mov_b32_e32 v122, v117
	v_mov_b32_e32 v121, v116
	s_cbranch_scc1 .LBB0_1261
	v_mov_b32_e32 v143, v129
	v_lshl_add_u64 v[122:123], v[142:143], 2, s[68:69]
	v_add_co_u32_e32 v122, vcc, 0x14103000, v122
	v_mul_f32_e32 v121, 0xbfb8aa3b, v116
	s_nop 0
	v_addc_co_u32_e32 v123, vcc, 0, v123, vcc
	global_load_dwordx4 v[144:147], v[122:123], off offset:128
	v_mul_f32_e32 v122, 0xbfb8aa3b, v117
	v_exp_f32_e32 v121, v121
	v_mul_f32_e32 v123, 0xbfb8aa3b, v118
	v_exp_f32_e32 v122, v122
	v_mul_f32_e32 v125, 0xbfb8aa3b, v119
	v_exp_f32_e32 v123, v123
	v_exp_f32_e32 v125, v125
	v_add_f32_e32 v121, 1.0, v121
	v_add_f32_e32 v122, 1.0, v122
	v_add_f32_e32 v123, 1.0, v123
	v_add_f32_e32 v125, 1.0, v125
	s_waitcnt vmcnt(0)
	v_sub_f32_e32 v139, 1.0, v144
	v_sub_f32_e32 v141, 1.0, v145
	v_sub_f32_e32 v143, 1.0, v146
	v_sub_f32_e32 v148, 1.0, v147
	s_mov_b64 vcc, s[4:5]
	v_rcp_f32_e32 v149, v121
	s_nop 0
	v_mul_f32_e32 v121, v139, v149
	s_mov_b64 vcc, s[6:7]
	v_rcp_f32_e32 v139, v122
	s_nop 0
	v_mul_f32_e32 v122, v141, v139
	s_mov_b64 vcc, s[8:9]
	v_rcp_f32_e32 v139, v123
	s_nop 0
	v_mul_f32_e32 v123, v143, v139
	v_rcp_f32_e32 v139, v125
	s_nop 0
	v_mul_f32_e32 v125, v148, v139
	v_add_f32_e32 v121, v144, v121
	v_add_f32_e32 v122, v145, v122
	v_add_f32_e32 v123, v146, v123
	v_add_f32_e32 v125, v147, v125
	v_log_f32_e32 v121, v121
	v_log_f32_e32 v122, v122
	v_log_f32_e32 v123, v123
	v_log_f32_e32 v125, v125

.LBB0_1262:
	s_andn2_b64 vcc, exec, s[4:5]
	s_cbranch_vccnz .LBB0_1264
	v_mul_f32_e32 v121, 0xbfb8aa3b, v116
	v_exp_f32_e32 v122, v121
	v_mul_f32_e32 v121, 0xbfb8aa3b, v117
	v_exp_f32_e32 v123, v121
	v_mul_f32_e32 v121, 0xbfb8aa3b, v118
	v_exp_f32_e32 v144, v121
	v_mul_f32_e32 v121, 0xbfb8aa3b, v119
	v_pk_add_f32 v[122:123], v[122:123], 1.0 op_sel_hi:[1,0]
	v_exp_f32_e32 v145, v121
	s_nop 0
	v_pk_add_f32 v[144:145], v[144:145], 1.0 op_sel_hi:[1,0]
	v_rcp_f32_e32 v121, v122
	s_nop 0
	v_mul_f32_e32 v121, v116, v121
	v_rcp_f32_e32 v116, v123
	s_nop 0
	v_mul_f32_e32 v122, v117, v116
	v_rcp_f32_e32 v116, v144
	s_nop 0
	v_mul_f32_e32 v123, v118, v116
	v_rcp_f32_e32 v116, v145
	s_nop 0
	v_mul_f32_e32 v125, v119, v116
.LBB0_1264:
	v_bitop3_b32 v116, v142, s65, 32 bitop3:0xc8
	v_lshlrev_b32_e32 v116, 1, v116
	v_mov_b32_e32 v117, v129
	v_cvt_pk_bf16_f32 v118, v121, v122
	v_cvt_pk_bf16_f32 v119, v123, v125
	v_lshl_add_u64 v[122:123], v[126:127], 0, v[116:117]
	s_and_b64 vcc, exec, s[2:3]
	s_mov_b64 s[4:5], -1
	global_store_dwordx2 v[122:123], v[118:119], off
	s_cbranch_vccnz .LBB0_1268
	s_cmpk_gt_u32 s38, 0xbff
	v_mov_b32_e32 v121, v115
	v_mov_b32_e32 v119, v114
	v_mov_b32_e32 v118, v113
	v_mov_b32_e32 v117, v112
	s_cbranch_scc1 .LBB0_1267
	v_mov_b32_e32 v143, v129
	v_lshl_add_u64 v[118:119], v[142:143], 2, s[68:69]
	v_add_co_u32_e32 v118, vcc, 0x14103000, v118
	v_mul_f32_e32 v117, 0xbfb8aa3b, v112
	s_nop 0
	v_addc_co_u32_e32 v119, vcc, 0, v119, vcc
	global_load_dwordx4 v[144:147], v[118:119], off offset:192
	v_mul_f32_e32 v118, 0xbfb8aa3b, v113
	v_exp_f32_e32 v117, v117
	v_mul_f32_e32 v119, 0xbfb8aa3b, v114
	v_exp_f32_e32 v118, v118
	v_mul_f32_e32 v121, 0xbfb8aa3b, v115
	v_exp_f32_e32 v119, v119
	v_exp_f32_e32 v121, v121
	v_add_f32_e32 v117, 1.0, v117
	v_add_f32_e32 v118, 1.0, v118
	v_add_f32_e32 v119, 1.0, v119
	v_add_f32_e32 v121, 1.0, v121
	s_waitcnt vmcnt(0)
	v_sub_f32_e32 v122, 1.0, v144
	v_sub_f32_e32 v123, 1.0, v145
	v_sub_f32_e32 v125, 1.0, v146
	v_sub_f32_e32 v139, 1.0, v147
	s_mov_b64 vcc, s[4:5]
	v_rcp_f32_e32 v141, v117
	s_nop 0
	v_mul_f32_e32 v117, v122, v141
	s_mov_b64 vcc, s[6:7]
	v_rcp_f32_e32 v122, v118
	s_nop 0
	v_mul_f32_e32 v118, v123, v122
	s_mov_b64 vcc, s[8:9]
	v_rcp_f32_e32 v122, v119
	s_nop 0
	v_mul_f32_e32 v119, v125, v122
	v_rcp_f32_e32 v122, v121
	s_nop 0
	v_mul_f32_e32 v121, v139, v122
	v_add_f32_e32 v117, v144, v117
	v_add_f32_e32 v118, v145, v118
	v_add_f32_e32 v119, v146, v119
	v_add_f32_e32 v121, v147, v121
	v_log_f32_e32 v117, v117
	v_log_f32_e32 v118, v118
	v_log_f32_e32 v119, v119
	v_log_f32_e32 v121, v121

.LBB0_1268:
	s_andn2_b64 vcc, exec, s[4:5]
	s_cbranch_vccnz .LBB0_1270
	v_mul_f32_e32 v117, 0xbfb8aa3b, v112
	v_exp_f32_e32 v118, v117
	v_mul_f32_e32 v117, 0xbfb8aa3b, v113
	v_exp_f32_e32 v119, v117
	v_mul_f32_e32 v117, 0xbfb8aa3b, v114
	v_exp_f32_e32 v122, v117
	v_mul_f32_e32 v117, 0xbfb8aa3b, v115
	v_pk_add_f32 v[118:119], v[118:119], 1.0 op_sel_hi:[1,0]
	v_exp_f32_e32 v123, v117
	s_nop 0
	v_pk_add_f32 v[122:123], v[122:123], 1.0 op_sel_hi:[1,0]
	v_rcp_f32_e32 v117, v118
	s_nop 0
	v_mul_f32_e32 v117, v112, v117
	v_rcp_f32_e32 v112, v119
	s_nop 0
	v_mul_f32_e32 v118, v113, v112
	v_rcp_f32_e32 v112, v122
	s_nop 0
	v_mul_f32_e32 v119, v114, v112
	v_rcp_f32_e32 v112, v123
	s_nop 0
	v_mul_f32_e32 v121, v115, v112
.LBB0_1270:
	v_bitop3_b32 v112, v142, s66, 48 bitop3:0xc8
	v_lshlrev_b32_e32 v112, 1, v112
	v_mov_b32_e32 v113, v129
	v_cvt_pk_bf16_f32 v114, v117, v118
	v_cvt_pk_bf16_f32 v115, v119, v121
	v_lshl_add_u64 v[118:119], v[126:127], 0, v[112:113]
	s_and_b64 vcc, exec, s[2:3]
	s_mov_b64 s[4:5], -1
	global_store_dwordx2 v[118:119], v[114:115], off
	s_cbranch_vccnz .LBB0_1274
	s_cmpk_gt_u32 s38, 0xbff
	v_mov_b32_e32 v117, v111
	v_mov_b32_e32 v115, v110
	v_mov_b32_e32 v114, v109
	v_mov_b32_e32 v113, v108
	s_cbranch_scc1 .LBB0_1273
	v_mov_b32_e32 v143, v129
	v_lshl_add_u64 v[114:115], v[142:143], 2, s[68:69]
	v_add_co_u32_e32 v114, vcc, 0x14103000, v114
	v_mul_f32_e32 v113, 0xbfb8aa3b, v108
	s_nop 0
	v_addc_co_u32_e32 v115, vcc, 0, v115, vcc
	global_load_dwordx4 v[144:147], v[114:115], off
	v_mul_f32_e32 v114, 0xbfb8aa3b, v109
	v_exp_f32_e32 v113, v113
	v_mul_f32_e32 v115, 0xbfb8aa3b, v110
	v_exp_f32_e32 v114, v114
	v_mul_f32_e32 v117, 0xbfb8aa3b, v111
	v_exp_f32_e32 v115, v115
	v_exp_f32_e32 v117, v117
	v_add_f32_e32 v113, 1.0, v113
	v_add_f32_e32 v114, 1.0, v114
	v_add_f32_e32 v115, 1.0, v115
	v_add_f32_e32 v117, 1.0, v117
	s_waitcnt vmcnt(0)
	v_sub_f32_e32 v118, 1.0, v144
	v_sub_f32_e32 v119, 1.0, v145
	v_sub_f32_e32 v121, 1.0, v146
	v_sub_f32_e32 v122, 1.0, v147
	s_mov_b64 vcc, s[4:5]
	v_rcp_f32_e32 v123, v113
	s_nop 0
	v_mul_f32_e32 v113, v118, v123
	s_mov_b64 vcc, s[6:7]
	v_rcp_f32_e32 v118, v114
	s_nop 0
	v_mul_f32_e32 v114, v119, v118
	s_mov_b64 vcc, s[8:9]
	v_rcp_f32_e32 v118, v115
	s_nop 0
	v_mul_f32_e32 v115, v121, v118
	v_rcp_f32_e32 v118, v117
	s_nop 0
	v_mul_f32_e32 v117, v122, v118
	v_add_f32_e32 v113, v144, v113
	v_add_f32_e32 v114, v145, v114
	v_add_f32_e32 v115, v146, v115
	v_add_f32_e32 v117, v147, v117
	v_log_f32_e32 v113, v113
	v_log_f32_e32 v114, v114
	v_log_f32_e32 v115, v115
	v_log_f32_e32 v117, v117

.LBB0_1274:
	s_andn2_b64 vcc, exec, s[4:5]
	s_cbranch_vccnz .LBB0_1276
	v_mul_f32_e32 v113, 0xbfb8aa3b, v108
	v_exp_f32_e32 v114, v113
	v_mul_f32_e32 v113, 0xbfb8aa3b, v109
	v_exp_f32_e32 v115, v113
	v_mul_f32_e32 v113, 0xbfb8aa3b, v110
	v_exp_f32_e32 v118, v113
	v_mul_f32_e32 v113, 0xbfb8aa3b, v111
	v_pk_add_f32 v[114:115], v[114:115], 1.0 op_sel_hi:[1,0]
	v_exp_f32_e32 v119, v113
	s_nop 0
	v_pk_add_f32 v[118:119], v[118:119], 1.0 op_sel_hi:[1,0]
	v_rcp_f32_e32 v113, v114
	s_nop 0
	v_mul_f32_e32 v113, v108, v113
	v_rcp_f32_e32 v108, v115
	s_nop 0
	v_mul_f32_e32 v114, v109, v108
	v_rcp_f32_e32 v108, v118
	s_nop 0
	v_mul_f32_e32 v115, v110, v108
	v_rcp_f32_e32 v108, v119
	s_nop 0
	v_mul_f32_e32 v117, v111, v108
.LBB0_1276:
	v_or_b32_e32 v108, 16, v124
	v_ashrrev_i32_e32 v109, 31, v108
	v_lshlrev_b64 v[108:109], 11, v[108:109]
	v_lshl_add_u64 v[108:109], s[40:41], 0, v[108:109]
	v_cvt_pk_bf16_f32 v110, v113, v114
	v_cvt_pk_bf16_f32 v111, v115, v117
	v_lshl_add_u64 v[114:115], v[108:109], 0, v[128:129]
	s_and_b64 vcc, exec, s[2:3]
	s_mov_b64 s[4:5], -1
	global_store_dwordx2 v[114:115], v[110:111], off
	s_cbranch_vccnz .LBB0_1280
	s_cmpk_gt_u32 s38, 0xbff
	v_mov_b32_e32 v114, v107
	v_mov_b32_e32 v113, v106
	v_mov_b32_e32 v111, v105
	v_mov_b32_e32 v110, v104
	s_cbranch_scc1 .LBB0_1279
	v_mov_b32_e32 v143, v129
	v_lshl_add_u64 v[110:111], v[142:143], 2, s[68:69]
	v_add_co_u32_e32 v110, vcc, 0x14103000, v110
	v_mul_f32_e32 v113, 0xbfb8aa3b, v106
	s_nop 0
	v_addc_co_u32_e32 v111, vcc, 0, v111, vcc
	global_load_dwordx4 v[144:147], v[110:111], off offset:64
	v_mul_f32_e32 v110, 0xbfb8aa3b, v104
	v_mul_f32_e32 v111, 0xbfb8aa3b, v105
	v_exp_f32_e32 v110, v110
	v_exp_f32_e32 v111, v111
	v_mul_f32_e32 v114, 0xbfb8aa3b, v107
	v_exp_f32_e32 v113, v113
	v_exp_f32_e32 v114, v114
	v_add_f32_e32 v110, 1.0, v110
	v_add_f32_e32 v111, 1.0, v111
	v_add_f32_e32 v113, 1.0, v113
	v_add_f32_e32 v114, 1.0, v114
	s_waitcnt vmcnt(0)
	v_sub_f32_e32 v115, 1.0, v144
	v_sub_f32_e32 v117, 1.0, v145
	v_sub_f32_e32 v118, 1.0, v146
	v_sub_f32_e32 v119, 1.0, v147
	s_mov_b64 vcc, s[4:5]
	v_rcp_f32_e32 v121, v110
	s_nop 0
	v_mul_f32_e32 v110, v115, v121
	s_mov_b64 vcc, s[6:7]
	v_rcp_f32_e32 v115, v111
	s_nop 0
	v_mul_f32_e32 v111, v117, v115
	s_mov_b64 vcc, s[8:9]
	v_rcp_f32_e32 v115, v113
	s_nop 0
	v_mul_f32_e32 v113, v118, v115
	v_rcp_f32_e32 v115, v114
	s_nop 0
	v_mul_f32_e32 v114, v119, v115
	v_add_f32_e32 v110, v144, v110
	v_add_f32_e32 v111, v145, v111
	v_add_f32_e32 v113, v146, v113
	v_add_f32_e32 v114, v147, v114
	v_log_f32_e32 v110, v110
	v_log_f32_e32 v111, v111
	v_log_f32_e32 v113, v113
	v_log_f32_e32 v114, v114

.LBB0_1280:
	s_andn2_b64 vcc, exec, s[4:5]
	s_cbranch_vccnz .LBB0_1282
	v_mul_f32_e32 v110, 0xbfb8aa3b, v104
	v_mul_f32_e32 v111, 0xbfb8aa3b, v105
	v_exp_f32_e32 v110, v110
	v_exp_f32_e32 v111, v111
	v_mul_f32_e32 v113, 0xbfb8aa3b, v106
	v_exp_f32_e32 v114, v113
	v_mul_f32_e32 v113, 0xbfb8aa3b, v107
	v_pk_add_f32 v[110:111], v[110:111], 1.0 op_sel_hi:[1,0]
	v_exp_f32_e32 v115, v113
	s_nop 0
	v_pk_add_f32 v[114:115], v[114:115], 1.0 op_sel_hi:[1,0]
	v_rcp_f32_e32 v113, v110
	s_nop 0
	v_mul_f32_e32 v110, v104, v113
	v_rcp_f32_e32 v104, v111
	s_nop 0
	v_mul_f32_e32 v111, v105, v104
	v_rcp_f32_e32 v104, v114
	s_nop 0
	v_mul_f32_e32 v113, v106, v104
	v_rcp_f32_e32 v104, v115
	s_nop 0
	v_mul_f32_e32 v114, v107, v104
.LBB0_1282:
	v_mov_b32_e32 v121, v129
	v_cvt_pk_bf16_f32 v104, v110, v111
	v_cvt_pk_bf16_f32 v105, v113, v114
	v_lshl_add_u64 v[106:107], v[108:109], 0, v[120:121]
	s_and_b64 vcc, exec, s[2:3]
	s_mov_b64 s[4:5], -1
	global_store_dwordx2 v[106:107], v[104:105], off
	s_cbranch_vccnz .LBB0_1286
	s_cmpk_gt_u32 s38, 0xbff
	v_mov_b32_e32 v107, v103
	v_mov_b32_e32 v106, v102
	v_mov_b32_e32 v105, v101
	v_mov_b32_e32 v104, v100
	s_cbranch_scc1 .LBB0_1285
	v_mov_b32_e32 v143, v129
	v_lshl_add_u64 v[104:105], v[142:143], 2, s[68:69]
	v_add_co_u32_e32 v104, vcc, 0x14103000, v104
	v_mul_f32_e32 v110, 0xbfb8aa3b, v100
	s_nop 0
	v_addc_co_u32_e32 v105, vcc, 0, v105, vcc
	global_load_dwordx4 v[104:107], v[104:105], off offset:128
	v_mul_f32_e32 v111, 0xbfb8aa3b, v101
	v_exp_f32_e32 v110, v110
	v_mul_f32_e32 v113, 0xbfb8aa3b, v102
	v_exp_f32_e32 v111, v111
	v_mul_f32_e32 v114, 0xbfb8aa3b, v103
	v_exp_f32_e32 v113, v113
	v_exp_f32_e32 v114, v114
	v_add_f32_e32 v110, 1.0, v110
	v_add_f32_e32 v111, 1.0, v111
	v_add_f32_e32 v113, 1.0, v113
	v_add_f32_e32 v114, 1.0, v114
	s_waitcnt vmcnt(0)
	v_sub_f32_e32 v115, 1.0, v104
	v_sub_f32_e32 v117, 1.0, v105
	v_sub_f32_e32 v118, 1.0, v106
	v_sub_f32_e32 v119, 1.0, v107
	s_mov_b64 vcc, s[4:5]
	v_rcp_f32_e32 v121, v110
	s_nop 0
	v_mul_f32_e32 v110, v115, v121
	s_mov_b64 vcc, s[6:7]
	v_add_f32_e32 v104, v104, v110
	v_rcp_f32_e32 v115, v111
	s_nop 0
	v_mul_f32_e32 v110, v117, v115
	s_mov_b64 vcc, s[8:9]
	v_add_f32_e32 v105, v105, v110
	v_rcp_f32_e32 v111, v113
	s_nop 0
	v_mul_f32_e32 v110, v118, v111
	v_add_f32_e32 v106, v106, v110
	v_rcp_f32_e32 v111, v114
	s_nop 0
	v_mul_f32_e32 v110, v119, v111
	v_add_f32_e32 v107, v107, v110
	v_log_f32_e32 v104, v104
	v_log_f32_e32 v105, v105
	v_log_f32_e32 v106, v106
	v_log_f32_e32 v107, v107

.LBB0_1286:
	s_andn2_b64 vcc, exec, s[4:5]
	s_cbranch_vccnz .LBB0_1288
	v_mul_f32_e32 v104, 0xbfb8aa3b, v100
	v_mul_f32_e32 v105, 0xbfb8aa3b, v101
	v_exp_f32_e32 v104, v104
	v_exp_f32_e32 v105, v105
	v_mul_f32_e32 v106, 0xbfb8aa3b, v102
	v_mul_f32_e32 v107, 0xbfb8aa3b, v103
	v_exp_f32_e32 v106, v106
	v_pk_add_f32 v[104:105], v[104:105], 1.0 op_sel_hi:[1,0]
	v_exp_f32_e32 v107, v107
	s_nop 0
	v_pk_add_f32 v[106:107], v[106:107], 1.0 op_sel_hi:[1,0]
	v_rcp_f32_e32 v110, v104
	s_nop 0
	v_mul_f32_e32 v104, v100, v110
	v_rcp_f32_e32 v100, v105
	s_nop 0
	v_mul_f32_e32 v105, v101, v100
	v_rcp_f32_e32 v100, v106
	s_nop 0
	v_mul_f32_e32 v106, v102, v100
	v_rcp_f32_e32 v100, v107
	s_nop 0
	v_mul_f32_e32 v107, v103, v100
.LBB0_1288:
	v_mov_b32_e32 v117, v129
	v_cvt_pk_bf16_f32 v100, v104, v105
	v_cvt_pk_bf16_f32 v101, v106, v107
	v_lshl_add_u64 v[102:103], v[108:109], 0, v[116:117]
	s_and_b64 vcc, exec, s[2:3]
	s_mov_b64 s[4:5], -1
	global_store_dwordx2 v[102:103], v[100:101], off
	s_cbranch_vccnz .LBB0_1292
	s_cmpk_gt_u32 s38, 0xbff
	v_mov_b32_e32 v103, v99
	v_mov_b32_e32 v102, v98
	v_mov_b32_e32 v101, v97
	v_mov_b32_e32 v100, v96
	s_cbranch_scc1 .LBB0_1291
	v_mov_b32_e32 v143, v129
	v_lshl_add_u64 v[100:101], v[142:143], 2, s[68:69]
	v_add_co_u32_e32 v100, vcc, 0x14103000, v100
	v_mul_f32_e32 v104, 0xbfb8aa3b, v96
	s_nop 0
	v_addc_co_u32_e32 v101, vcc, 0, v101, vcc
	global_load_dwordx4 v[100:103], v[100:101], off offset:192
	v_mul_f32_e32 v105, 0xbfb8aa3b, v97
	v_exp_f32_e32 v104, v104
	v_mul_f32_e32 v106, 0xbfb8aa3b, v98
	v_exp_f32_e32 v105, v105
	v_mul_f32_e32 v107, 0xbfb8aa3b, v99
	v_exp_f32_e32 v106, v106
	v_exp_f32_e32 v107, v107
	v_add_f32_e32 v104, 1.0, v104
	v_add_f32_e32 v105, 1.0, v105
	v_add_f32_e32 v106, 1.0, v106
	v_add_f32_e32 v107, 1.0, v107
	s_waitcnt vmcnt(0)
	v_sub_f32_e32 v110, 1.0, v100
	v_sub_f32_e32 v111, 1.0, v101
	v_sub_f32_e32 v113, 1.0, v102
	v_sub_f32_e32 v114, 1.0, v103
	s_mov_b64 vcc, s[4:5]
	v_rcp_f32_e32 v115, v104
	s_nop 0
	v_mul_f32_e32 v104, v110, v115
	s_mov_b64 vcc, s[6:7]
	v_add_f32_e32 v100, v100, v104
	v_rcp_f32_e32 v110, v105
	s_nop 0
	v_mul_f32_e32 v104, v111, v110
	s_mov_b64 vcc, s[8:9]
	v_add_f32_e32 v101, v101, v104
	v_rcp_f32_e32 v105, v106
	s_nop 0
	v_mul_f32_e32 v104, v113, v105
	v_add_f32_e32 v102, v102, v104
	v_rcp_f32_e32 v105, v107
	s_nop 0
	v_mul_f32_e32 v104, v114, v105
	v_add_f32_e32 v103, v103, v104
	v_log_f32_e32 v100, v100
	v_log_f32_e32 v101, v101
	v_log_f32_e32 v102, v102
	v_log_f32_e32 v103, v103

.LBB0_1292:
	s_andn2_b64 vcc, exec, s[4:5]
	s_cbranch_vccnz .LBB0_1294
	v_mul_f32_e32 v100, 0xbfb8aa3b, v96
	v_mul_f32_e32 v101, 0xbfb8aa3b, v97
	v_exp_f32_e32 v100, v100
	v_exp_f32_e32 v101, v101
	v_mul_f32_e32 v102, 0xbfb8aa3b, v98
	v_mul_f32_e32 v103, 0xbfb8aa3b, v99
	v_exp_f32_e32 v102, v102
	v_pk_add_f32 v[100:101], v[100:101], 1.0 op_sel_hi:[1,0]
	v_exp_f32_e32 v103, v103
	s_nop 0
	v_pk_add_f32 v[102:103], v[102:103], 1.0 op_sel_hi:[1,0]
	v_rcp_f32_e32 v104, v100
	s_nop 0
	v_mul_f32_e32 v100, v96, v104
	v_rcp_f32_e32 v96, v101
	s_nop 0
	v_mul_f32_e32 v101, v97, v96
	v_rcp_f32_e32 v96, v102
	s_nop 0
	v_mul_f32_e32 v102, v98, v96
	v_rcp_f32_e32 v96, v103
	s_nop 0
	v_mul_f32_e32 v103, v99, v96
.LBB0_1294:
	v_mov_b32_e32 v113, v129
	v_cvt_pk_bf16_f32 v96, v100, v101
	v_cvt_pk_bf16_f32 v97, v102, v103
	v_lshl_add_u64 v[98:99], v[108:109], 0, v[112:113]
	s_and_b64 vcc, exec, s[2:3]
	s_mov_b64 s[4:5], -1
	global_store_dwordx2 v[98:99], v[96:97], off
	s_cbranch_vccnz .LBB0_1298
	s_cmpk_gt_u32 s38, 0xbff
	v_mov_b32_e32 v99, v95
	v_mov_b32_e32 v98, v94
	v_mov_b32_e32 v97, v93
	v_mov_b32_e32 v96, v92
	s_cbranch_scc1 .LBB0_1297
	v_mov_b32_e32 v143, v129
	v_lshl_add_u64 v[96:97], v[142:143], 2, s[68:69]
	v_add_co_u32_e32 v96, vcc, 0x14103000, v96
	v_mul_f32_e32 v100, 0xbfb8aa3b, v92
	s_nop 0
	v_addc_co_u32_e32 v97, vcc, 0, v97, vcc
	global_load_dwordx4 v[96:99], v[96:97], off
	v_mul_f32_e32 v101, 0xbfb8aa3b, v93
	v_exp_f32_e32 v100, v100
	v_mul_f32_e32 v102, 0xbfb8aa3b, v94
	v_exp_f32_e32 v101, v101
	v_mul_f32_e32 v103, 0xbfb8aa3b, v95
	v_exp_f32_e32 v102, v102
	v_exp_f32_e32 v103, v103
	v_add_f32_e32 v100, 1.0, v100
	v_add_f32_e32 v101, 1.0, v101
	v_add_f32_e32 v102, 1.0, v102
	v_add_f32_e32 v103, 1.0, v103
	s_waitcnt vmcnt(0)
	v_sub_f32_e32 v104, 1.0, v96
	v_sub_f32_e32 v105, 1.0, v97
	v_sub_f32_e32 v106, 1.0, v98
	v_sub_f32_e32 v107, 1.0, v99
	s_mov_b64 vcc, s[4:5]
	v_rcp_f32_e32 v108, v100
	s_nop 0
	v_mul_f32_e32 v100, v104, v108
	s_mov_b64 vcc, s[6:7]
	v_add_f32_e32 v96, v96, v100
	v_rcp_f32_e32 v104, v101
	s_nop 0
	v_mul_f32_e32 v100, v105, v104
	s_mov_b64 vcc, s[8:9]
	v_add_f32_e32 v97, v97, v100
	v_rcp_f32_e32 v101, v102
	s_nop 0
	v_mul_f32_e32 v100, v106, v101
	v_add_f32_e32 v98, v98, v100
	v_rcp_f32_e32 v101, v103
	s_nop 0
	v_mul_f32_e32 v100, v107, v101
	v_add_f32_e32 v99, v99, v100
	v_log_f32_e32 v96, v96
	v_log_f32_e32 v97, v97
	v_log_f32_e32 v98, v98
	v_log_f32_e32 v99, v99

.LBB0_1298:
	s_andn2_b64 vcc, exec, s[4:5]
	s_cbranch_vccnz .LBB0_1300
	v_mul_f32_e32 v96, 0xbfb8aa3b, v92
	v_mul_f32_e32 v97, 0xbfb8aa3b, v93
	v_exp_f32_e32 v96, v96
	v_exp_f32_e32 v97, v97
	v_mul_f32_e32 v98, 0xbfb8aa3b, v94
	v_mul_f32_e32 v99, 0xbfb8aa3b, v95
	v_exp_f32_e32 v98, v98
	v_pk_add_f32 v[96:97], v[96:97], 1.0 op_sel_hi:[1,0]
	v_exp_f32_e32 v99, v99
	s_nop 0
	v_pk_add_f32 v[98:99], v[98:99], 1.0 op_sel_hi:[1,0]
	v_rcp_f32_e32 v100, v96
	s_nop 0
	v_mul_f32_e32 v96, v92, v100
	v_rcp_f32_e32 v92, v97
	s_nop 0
	v_mul_f32_e32 v97, v93, v92
	v_rcp_f32_e32 v92, v98
	s_nop 0
	v_mul_f32_e32 v98, v94, v92
	v_rcp_f32_e32 v92, v99
	s_nop 0
	v_mul_f32_e32 v99, v95, v92
.LBB0_1300:
	v_or_b32_e32 v92, 32, v124
	v_ashrrev_i32_e32 v93, 31, v92
	v_lshlrev_b64 v[92:93], 11, v[92:93]
	v_lshl_add_u64 v[92:93], s[40:41], 0, v[92:93]
	v_cvt_pk_bf16_f32 v94, v96, v97
	v_cvt_pk_bf16_f32 v95, v98, v99
	v_lshl_add_u64 v[96:97], v[92:93], 0, v[128:129]
	s_and_b64 vcc, exec, s[2:3]
	s_mov_b64 s[4:5], -1
	global_store_dwordx2 v[96:97], v[94:95], off
	s_cbranch_vccnz .LBB0_1304
	s_cmpk_gt_u32 s38, 0xbff
	v_mov_b32_e32 v97, v91
	v_mov_b32_e32 v96, v90
	v_mov_b32_e32 v95, v89
	v_mov_b32_e32 v94, v88
	s_cbranch_scc1 .LBB0_1303
	v_mov_b32_e32 v143, v129
	v_lshl_add_u64 v[94:95], v[142:143], 2, s[68:69]
	v_add_co_u32_e32 v94, vcc, 0x14103000, v94
	v_mul_f32_e32 v98, 0xbfb8aa3b, v88
	s_nop 0
	v_addc_co_u32_e32 v95, vcc, 0, v95, vcc
	global_load_dwordx4 v[94:97], v[94:95], off offset:64
	v_mul_f32_e32 v99, 0xbfb8aa3b, v89
	v_exp_f32_e32 v98, v98
	v_mul_f32_e32 v100, 0xbfb8aa3b, v90
	v_exp_f32_e32 v99, v99
	v_mul_f32_e32 v101, 0xbfb8aa3b, v91
	v_exp_f32_e32 v100, v100
	v_exp_f32_e32 v101, v101
	v_add_f32_e32 v98, 1.0, v98
	v_add_f32_e32 v99, 1.0, v99
	v_add_f32_e32 v100, 1.0, v100
	v_add_f32_e32 v101, 1.0, v101
	s_waitcnt vmcnt(0)
	v_sub_f32_e32 v102, 1.0, v94
	v_sub_f32_e32 v103, 1.0, v95
	v_sub_f32_e32 v104, 1.0, v96
	v_sub_f32_e32 v105, 1.0, v97
	s_mov_b64 vcc, s[4:5]
	v_rcp_f32_e32 v106, v98
	s_nop 0
	v_mul_f32_e32 v98, v102, v106
	s_mov_b64 vcc, s[6:7]
	v_add_f32_e32 v94, v94, v98
	v_rcp_f32_e32 v102, v99
	s_nop 0
	v_mul_f32_e32 v98, v103, v102
	s_mov_b64 vcc, s[8:9]
	v_add_f32_e32 v95, v95, v98
	v_rcp_f32_e32 v99, v100
	s_nop 0
	v_mul_f32_e32 v98, v104, v99
	v_add_f32_e32 v96, v96, v98
	v_rcp_f32_e32 v99, v101
	s_nop 0
	v_mul_f32_e32 v98, v105, v99
	v_add_f32_e32 v97, v97, v98
	v_log_f32_e32 v94, v94
	v_log_f32_e32 v95, v95
	v_log_f32_e32 v96, v96
	v_log_f32_e32 v97, v97

.LBB0_1304:
	s_andn2_b64 vcc, exec, s[4:5]
	s_cbranch_vccnz .LBB0_1306
	v_mul_f32_e32 v94, 0xbfb8aa3b, v88
	v_mul_f32_e32 v95, 0xbfb8aa3b, v89
	v_exp_f32_e32 v94, v94
	v_exp_f32_e32 v95, v95
	v_mul_f32_e32 v96, 0xbfb8aa3b, v90
	v_mul_f32_e32 v97, 0xbfb8aa3b, v91
	v_exp_f32_e32 v96, v96
	v_pk_add_f32 v[94:95], v[94:95], 1.0 op_sel_hi:[1,0]
	v_exp_f32_e32 v97, v97
	s_nop 0
	v_pk_add_f32 v[96:97], v[96:97], 1.0 op_sel_hi:[1,0]
	v_rcp_f32_e32 v98, v94
	s_nop 0
	v_mul_f32_e32 v94, v88, v98
	v_rcp_f32_e32 v88, v95
	s_nop 0
	v_mul_f32_e32 v95, v89, v88
	v_rcp_f32_e32 v88, v96
	s_nop 0
	v_mul_f32_e32 v96, v90, v88
	v_rcp_f32_e32 v88, v97
	s_nop 0
	v_mul_f32_e32 v97, v91, v88
.LBB0_1306:
	v_mov_b32_e32 v121, v129
	v_cvt_pk_bf16_f32 v88, v94, v95
	v_cvt_pk_bf16_f32 v89, v96, v97
	v_lshl_add_u64 v[90:91], v[92:93], 0, v[120:121]
	s_and_b64 vcc, exec, s[2:3]
	s_mov_b64 s[4:5], -1
	global_store_dwordx2 v[90:91], v[88:89], off
	s_cbranch_vccnz .LBB0_1310
	s_cmpk_gt_u32 s38, 0xbff
	v_mov_b32_e32 v91, v87
	v_mov_b32_e32 v90, v86
	v_mov_b32_e32 v89, v85
	v_mov_b32_e32 v88, v84
	s_cbranch_scc1 .LBB0_1309
	v_mov_b32_e32 v143, v129
	v_lshl_add_u64 v[88:89], v[142:143], 2, s[68:69]
	v_add_co_u32_e32 v88, vcc, 0x14103000, v88
	v_mul_f32_e32 v94, 0xbfb8aa3b, v84
	s_nop 0
	v_addc_co_u32_e32 v89, vcc, 0, v89, vcc
	global_load_dwordx4 v[88:91], v[88:89], off offset:128
	v_mul_f32_e32 v95, 0xbfb8aa3b, v85
	v_exp_f32_e32 v94, v94
	v_mul_f32_e32 v96, 0xbfb8aa3b, v86
	v_exp_f32_e32 v95, v95
	v_mul_f32_e32 v97, 0xbfb8aa3b, v87
	v_exp_f32_e32 v96, v96
	v_exp_f32_e32 v97, v97
	v_add_f32_e32 v94, 1.0, v94
	v_add_f32_e32 v95, 1.0, v95
	v_add_f32_e32 v96, 1.0, v96
	v_add_f32_e32 v97, 1.0, v97
	s_waitcnt vmcnt(0)
	v_sub_f32_e32 v98, 1.0, v88
	v_sub_f32_e32 v99, 1.0, v89
	v_sub_f32_e32 v100, 1.0, v90
	v_sub_f32_e32 v101, 1.0, v91
	s_mov_b64 vcc, s[4:5]
	v_rcp_f32_e32 v102, v94
	s_nop 0
	v_mul_f32_e32 v94, v98, v102
	s_mov_b64 vcc, s[6:7]
	v_add_f32_e32 v88, v88, v94
	v_rcp_f32_e32 v98, v95
	s_nop 0
	v_mul_f32_e32 v94, v99, v98
	s_mov_b64 vcc, s[8:9]
	v_add_f32_e32 v89, v89, v94
	v_rcp_f32_e32 v95, v96
	s_nop 0
	v_mul_f32_e32 v94, v100, v95
	v_add_f32_e32 v90, v90, v94
	v_rcp_f32_e32 v95, v97
	s_nop 0
	v_mul_f32_e32 v94, v101, v95
	v_add_f32_e32 v91, v91, v94
	v_log_f32_e32 v88, v88
	v_log_f32_e32 v89, v89
	v_log_f32_e32 v90, v90
	v_log_f32_e32 v91, v91

.LBB0_1310:
	s_andn2_b64 vcc, exec, s[4:5]
	s_cbranch_vccnz .LBB0_1312
	v_mul_f32_e32 v88, 0xbfb8aa3b, v84
	v_mul_f32_e32 v89, 0xbfb8aa3b, v85
	v_exp_f32_e32 v88, v88
	v_exp_f32_e32 v89, v89
	v_mul_f32_e32 v90, 0xbfb8aa3b, v86
	v_mul_f32_e32 v91, 0xbfb8aa3b, v87
	v_exp_f32_e32 v90, v90
	v_pk_add_f32 v[88:89], v[88:89], 1.0 op_sel_hi:[1,0]
	v_exp_f32_e32 v91, v91
	s_nop 0
	v_pk_add_f32 v[90:91], v[90:91], 1.0 op_sel_hi:[1,0]
	v_rcp_f32_e32 v94, v88
	s_nop 0
	v_mul_f32_e32 v88, v84, v94
	v_rcp_f32_e32 v84, v89
	s_nop 0
	v_mul_f32_e32 v89, v85, v84
	v_rcp_f32_e32 v84, v90
	s_nop 0
	v_mul_f32_e32 v90, v86, v84
	v_rcp_f32_e32 v84, v91
	s_nop 0
	v_mul_f32_e32 v91, v87, v84
.LBB0_1312:
	v_mov_b32_e32 v117, v129
	v_cvt_pk_bf16_f32 v84, v88, v89
	v_cvt_pk_bf16_f32 v85, v90, v91
	v_lshl_add_u64 v[86:87], v[92:93], 0, v[116:117]
	s_and_b64 vcc, exec, s[2:3]
	s_mov_b64 s[4:5], -1
	global_store_dwordx2 v[86:87], v[84:85], off
	s_cbranch_vccnz .LBB0_1316
	s_cmpk_gt_u32 s38, 0xbff
	v_mov_b32_e32 v87, v83
	v_mov_b32_e32 v86, v82
	v_mov_b32_e32 v85, v81
	v_mov_b32_e32 v84, v80
	s_cbranch_scc1 .LBB0_1315
	v_mov_b32_e32 v143, v129
	v_lshl_add_u64 v[84:85], v[142:143], 2, s[68:69]
	v_add_co_u32_e32 v84, vcc, 0x14103000, v84
	v_mul_f32_e32 v88, 0xbfb8aa3b, v80
	s_nop 0
	v_addc_co_u32_e32 v85, vcc, 0, v85, vcc
	global_load_dwordx4 v[84:87], v[84:85], off offset:192
	v_mul_f32_e32 v89, 0xbfb8aa3b, v81
	v_exp_f32_e32 v88, v88
	v_mul_f32_e32 v90, 0xbfb8aa3b, v82
	v_exp_f32_e32 v89, v89
	v_mul_f32_e32 v91, 0xbfb8aa3b, v83
	v_exp_f32_e32 v90, v90
	v_exp_f32_e32 v91, v91
	v_add_f32_e32 v88, 1.0, v88
	v_add_f32_e32 v89, 1.0, v89
	v_add_f32_e32 v90, 1.0, v90
	v_add_f32_e32 v91, 1.0, v91
	s_waitcnt vmcnt(0)
	v_sub_f32_e32 v94, 1.0, v84
	v_sub_f32_e32 v95, 1.0, v85
	v_sub_f32_e32 v96, 1.0, v86
	v_sub_f32_e32 v97, 1.0, v87
	s_mov_b64 vcc, s[4:5]
	v_rcp_f32_e32 v98, v88
	s_nop 0
	v_mul_f32_e32 v88, v94, v98
	s_mov_b64 vcc, s[6:7]
	v_add_f32_e32 v84, v84, v88
	v_rcp_f32_e32 v94, v89
	s_nop 0
	v_mul_f32_e32 v88, v95, v94
	s_mov_b64 vcc, s[8:9]
	v_add_f32_e32 v85, v85, v88
	v_rcp_f32_e32 v89, v90
	s_nop 0
	v_mul_f32_e32 v88, v96, v89
	v_add_f32_e32 v86, v86, v88
	v_rcp_f32_e32 v89, v91
	s_nop 0
	v_mul_f32_e32 v88, v97, v89
	v_add_f32_e32 v87, v87, v88
	v_log_f32_e32 v84, v84
	v_log_f32_e32 v85, v85
	v_log_f32_e32 v86, v86
	v_log_f32_e32 v87, v87

.LBB0_1316:
	s_andn2_b64 vcc, exec, s[4:5]
	s_cbranch_vccnz .LBB0_1318
	v_mul_f32_e32 v84, 0xbfb8aa3b, v80
	v_mul_f32_e32 v85, 0xbfb8aa3b, v81
	v_exp_f32_e32 v84, v84
	v_exp_f32_e32 v85, v85
	v_mul_f32_e32 v86, 0xbfb8aa3b, v82
	v_mul_f32_e32 v87, 0xbfb8aa3b, v83
	v_exp_f32_e32 v86, v86
	v_pk_add_f32 v[84:85], v[84:85], 1.0 op_sel_hi:[1,0]
	v_exp_f32_e32 v87, v87
	s_nop 0
	v_pk_add_f32 v[86:87], v[86:87], 1.0 op_sel_hi:[1,0]
	v_rcp_f32_e32 v88, v84
	s_nop 0
	v_mul_f32_e32 v84, v80, v88
	v_rcp_f32_e32 v80, v85
	s_nop 0
	v_mul_f32_e32 v85, v81, v80
	v_rcp_f32_e32 v80, v86
	s_nop 0
	v_mul_f32_e32 v86, v82, v80
	v_rcp_f32_e32 v80, v87
	s_nop 0
	v_mul_f32_e32 v87, v83, v80
.LBB0_1318:
	v_mov_b32_e32 v113, v129
	v_cvt_pk_bf16_f32 v80, v84, v85
	v_cvt_pk_bf16_f32 v81, v86, v87
	v_lshl_add_u64 v[82:83], v[92:93], 0, v[112:113]
	s_and_b64 vcc, exec, s[2:3]
	s_mov_b64 s[4:5], -1
	global_store_dwordx2 v[82:83], v[80:81], off
	s_cbranch_vccnz .LBB0_1322
	s_cmpk_gt_u32 s38, 0xbff
	v_mov_b32_e32 v83, v79
	v_mov_b32_e32 v82, v78
	v_mov_b32_e32 v81, v77
	v_mov_b32_e32 v80, v76
	s_cbranch_scc1 .LBB0_1321
	v_mov_b32_e32 v143, v129
	v_lshl_add_u64 v[80:81], v[142:143], 2, s[68:69]
	v_add_co_u32_e32 v80, vcc, 0x14103000, v80
	v_mul_f32_e32 v84, 0xbfb8aa3b, v76
	s_nop 0
	v_addc_co_u32_e32 v81, vcc, 0, v81, vcc
	global_load_dwordx4 v[80:83], v[80:81], off
	v_mul_f32_e32 v85, 0xbfb8aa3b, v77
	v_exp_f32_e32 v84, v84
	v_mul_f32_e32 v86, 0xbfb8aa3b, v78
	v_exp_f32_e32 v85, v85
	v_mul_f32_e32 v87, 0xbfb8aa3b, v79
	v_exp_f32_e32 v86, v86
	v_exp_f32_e32 v87, v87
	v_add_f32_e32 v84, 1.0, v84
	v_add_f32_e32 v85, 1.0, v85
	v_add_f32_e32 v86, 1.0, v86
	v_add_f32_e32 v87, 1.0, v87
	s_waitcnt vmcnt(0)
	v_sub_f32_e32 v88, 1.0, v80
	v_sub_f32_e32 v89, 1.0, v81
	v_sub_f32_e32 v90, 1.0, v82
	v_sub_f32_e32 v91, 1.0, v83
	s_mov_b64 vcc, s[4:5]
	v_rcp_f32_e32 v92, v84
	s_nop 0
	v_mul_f32_e32 v84, v88, v92
	s_mov_b64 vcc, s[6:7]
	v_add_f32_e32 v80, v80, v84
	v_rcp_f32_e32 v88, v85
	s_nop 0
	v_mul_f32_e32 v84, v89, v88
	s_mov_b64 vcc, s[8:9]
	v_add_f32_e32 v81, v81, v84
	v_rcp_f32_e32 v85, v86
	s_nop 0
	v_mul_f32_e32 v84, v90, v85
	v_add_f32_e32 v82, v82, v84
	v_rcp_f32_e32 v85, v87
	s_nop 0
	v_mul_f32_e32 v84, v91, v85
	v_add_f32_e32 v83, v83, v84
	v_log_f32_e32 v80, v80
	v_log_f32_e32 v81, v81
	v_log_f32_e32 v82, v82
	v_log_f32_e32 v83, v83

.LBB0_1322:
	s_andn2_b64 vcc, exec, s[4:5]
	s_cbranch_vccnz .LBB0_1324
	v_mul_f32_e32 v80, 0xbfb8aa3b, v76
	v_mul_f32_e32 v81, 0xbfb8aa3b, v77
	v_exp_f32_e32 v80, v80
	v_exp_f32_e32 v81, v81
	v_mul_f32_e32 v82, 0xbfb8aa3b, v78
	v_mul_f32_e32 v83, 0xbfb8aa3b, v79
	v_exp_f32_e32 v82, v82
	v_pk_add_f32 v[80:81], v[80:81], 1.0 op_sel_hi:[1,0]
	v_exp_f32_e32 v83, v83
	s_nop 0
	v_pk_add_f32 v[82:83], v[82:83], 1.0 op_sel_hi:[1,0]
	v_rcp_f32_e32 v84, v80
	s_nop 0
	v_mul_f32_e32 v80, v76, v84
	v_rcp_f32_e32 v76, v81
	s_nop 0
	v_mul_f32_e32 v81, v77, v76
	v_rcp_f32_e32 v76, v82
	s_nop 0
	v_mul_f32_e32 v82, v78, v76
	v_rcp_f32_e32 v76, v83
	s_nop 0
	v_mul_f32_e32 v83, v79, v76
.LBB0_1324:
	v_or_b32_e32 v76, 48, v124
	v_ashrrev_i32_e32 v77, 31, v76
	v_lshlrev_b64 v[76:77], 11, v[76:77]
	v_lshl_add_u64 v[76:77], s[40:41], 0, v[76:77]
	v_cvt_pk_bf16_f32 v78, v80, v81
	v_cvt_pk_bf16_f32 v79, v82, v83
	v_lshl_add_u64 v[80:81], v[76:77], 0, v[128:129]
	s_and_b64 vcc, exec, s[2:3]
	s_mov_b64 s[4:5], -1
	global_store_dwordx2 v[80:81], v[78:79], off
	s_cbranch_vccnz .LBB0_1328
	s_cmpk_gt_u32 s38, 0xbff
	v_mov_b32_e32 v81, v75
	v_mov_b32_e32 v80, v74
	v_mov_b32_e32 v79, v73
	v_mov_b32_e32 v78, v72
	s_cbranch_scc1 .LBB0_1327
	v_mov_b32_e32 v143, v129
	v_lshl_add_u64 v[78:79], v[142:143], 2, s[68:69]
	v_add_co_u32_e32 v78, vcc, 0x14103000, v78
	v_mul_f32_e32 v82, 0xbfb8aa3b, v72
	s_nop 0
	v_addc_co_u32_e32 v79, vcc, 0, v79, vcc
	global_load_dwordx4 v[78:81], v[78:79], off offset:64
	v_mul_f32_e32 v83, 0xbfb8aa3b, v73
	v_exp_f32_e32 v82, v82
	v_mul_f32_e32 v84, 0xbfb8aa3b, v74
	v_exp_f32_e32 v83, v83
	v_mul_f32_e32 v85, 0xbfb8aa3b, v75
	v_exp_f32_e32 v84, v84
	v_exp_f32_e32 v85, v85
	v_add_f32_e32 v82, 1.0, v82
	v_add_f32_e32 v83, 1.0, v83
	v_add_f32_e32 v84, 1.0, v84
	v_add_f32_e32 v85, 1.0, v85
	s_waitcnt vmcnt(0)
	v_sub_f32_e32 v86, 1.0, v78
	v_sub_f32_e32 v87, 1.0, v79
	v_sub_f32_e32 v88, 1.0, v80
	v_sub_f32_e32 v89, 1.0, v81
	s_mov_b64 vcc, s[4:5]
	v_rcp_f32_e32 v90, v82
	s_nop 0
	v_mul_f32_e32 v82, v86, v90
	s_mov_b64 vcc, s[6:7]
	v_add_f32_e32 v78, v78, v82
	v_rcp_f32_e32 v86, v83
	s_nop 0
	v_mul_f32_e32 v82, v87, v86
	s_mov_b64 vcc, s[8:9]
	v_add_f32_e32 v79, v79, v82
	v_rcp_f32_e32 v83, v84
	s_nop 0
	v_mul_f32_e32 v82, v88, v83
	v_add_f32_e32 v80, v80, v82
	v_rcp_f32_e32 v83, v85
	s_nop 0
	v_mul_f32_e32 v82, v89, v83
	v_add_f32_e32 v81, v81, v82
	v_log_f32_e32 v78, v78
	v_log_f32_e32 v79, v79
	v_log_f32_e32 v80, v80
	v_log_f32_e32 v81, v81

.LBB0_1328:
	s_andn2_b64 vcc, exec, s[4:5]
	s_cbranch_vccnz .LBB0_1330
	v_mul_f32_e32 v78, 0xbfb8aa3b, v72
	v_mul_f32_e32 v79, 0xbfb8aa3b, v73
	v_exp_f32_e32 v78, v78
	v_exp_f32_e32 v79, v79
	v_mul_f32_e32 v80, 0xbfb8aa3b, v74
	v_mul_f32_e32 v81, 0xbfb8aa3b, v75
	v_exp_f32_e32 v80, v80
	v_pk_add_f32 v[78:79], v[78:79], 1.0 op_sel_hi:[1,0]
	v_exp_f32_e32 v81, v81
	s_nop 0
	v_pk_add_f32 v[80:81], v[80:81], 1.0 op_sel_hi:[1,0]
	v_rcp_f32_e32 v82, v78
	s_nop 0
	v_mul_f32_e32 v78, v72, v82
	v_rcp_f32_e32 v72, v79
	s_nop 0
	v_mul_f32_e32 v79, v73, v72
	v_rcp_f32_e32 v72, v80
	s_nop 0
	v_mul_f32_e32 v80, v74, v72
	v_rcp_f32_e32 v72, v81
	s_nop 0
	v_mul_f32_e32 v81, v75, v72
.LBB0_1330:
	v_mov_b32_e32 v121, v129
	v_cvt_pk_bf16_f32 v72, v78, v79
	v_cvt_pk_bf16_f32 v73, v80, v81
	v_lshl_add_u64 v[74:75], v[76:77], 0, v[120:121]
	s_and_b64 vcc, exec, s[2:3]
	s_mov_b64 s[4:5], -1
	global_store_dwordx2 v[74:75], v[72:73], off
	s_cbranch_vccnz .LBB0_1334
	s_cmpk_gt_u32 s38, 0xbff
	v_mov_b32_e32 v75, v71
	v_mov_b32_e32 v74, v70
	v_mov_b32_e32 v73, v69
	v_mov_b32_e32 v72, v68
	s_cbranch_scc1 .LBB0_1333
	v_mov_b32_e32 v143, v129
	v_lshl_add_u64 v[72:73], v[142:143], 2, s[68:69]
	v_add_co_u32_e32 v72, vcc, 0x14103000, v72
	v_mul_f32_e32 v78, 0xbfb8aa3b, v68
	s_nop 0
	v_addc_co_u32_e32 v73, vcc, 0, v73, vcc
	global_load_dwordx4 v[72:75], v[72:73], off offset:128
	v_mul_f32_e32 v79, 0xbfb8aa3b, v69
	v_exp_f32_e32 v78, v78
	v_mul_f32_e32 v80, 0xbfb8aa3b, v70
	v_exp_f32_e32 v79, v79
	v_mul_f32_e32 v81, 0xbfb8aa3b, v71
	v_exp_f32_e32 v80, v80
	v_exp_f32_e32 v81, v81
	v_add_f32_e32 v78, 1.0, v78
	v_add_f32_e32 v79, 1.0, v79
	v_add_f32_e32 v80, 1.0, v80
	v_add_f32_e32 v81, 1.0, v81
	s_waitcnt vmcnt(0)
	v_sub_f32_e32 v82, 1.0, v72
	v_sub_f32_e32 v83, 1.0, v73
	v_sub_f32_e32 v84, 1.0, v74
	v_sub_f32_e32 v85, 1.0, v75
	s_mov_b64 vcc, s[4:5]
	v_rcp_f32_e32 v86, v78
	s_nop 0
	v_mul_f32_e32 v78, v82, v86
	s_mov_b64 vcc, s[6:7]
	v_add_f32_e32 v72, v72, v78
	v_rcp_f32_e32 v82, v79
	s_nop 0
	v_mul_f32_e32 v78, v83, v82
	s_mov_b64 vcc, s[8:9]
	v_add_f32_e32 v73, v73, v78
	v_rcp_f32_e32 v79, v80
	s_nop 0
	v_mul_f32_e32 v78, v84, v79
	v_add_f32_e32 v74, v74, v78
	v_rcp_f32_e32 v79, v81
	s_nop 0
	v_mul_f32_e32 v78, v85, v79
	v_add_f32_e32 v75, v75, v78
	v_log_f32_e32 v72, v72
	v_log_f32_e32 v73, v73
	v_log_f32_e32 v74, v74
	v_log_f32_e32 v75, v75

.LBB0_1334:
	s_andn2_b64 vcc, exec, s[4:5]
	s_cbranch_vccnz .LBB0_1336
	v_mul_f32_e32 v72, 0xbfb8aa3b, v68
	v_mul_f32_e32 v73, 0xbfb8aa3b, v69
	v_exp_f32_e32 v72, v72
	v_exp_f32_e32 v73, v73
	v_mul_f32_e32 v74, 0xbfb8aa3b, v70
	v_mul_f32_e32 v75, 0xbfb8aa3b, v71
	v_exp_f32_e32 v74, v74
	v_pk_add_f32 v[72:73], v[72:73], 1.0 op_sel_hi:[1,0]
	v_exp_f32_e32 v75, v75
	s_nop 0
	v_pk_add_f32 v[74:75], v[74:75], 1.0 op_sel_hi:[1,0]
	v_rcp_f32_e32 v78, v72
	s_nop 0
	v_mul_f32_e32 v72, v68, v78
	v_rcp_f32_e32 v68, v73
	s_nop 0
	v_mul_f32_e32 v73, v69, v68
	v_rcp_f32_e32 v68, v74
	s_nop 0
	v_mul_f32_e32 v74, v70, v68
	v_rcp_f32_e32 v68, v75
	s_nop 0
	v_mul_f32_e32 v75, v71, v68
.LBB0_1336:
	v_mov_b32_e32 v117, v129
	v_cvt_pk_bf16_f32 v68, v72, v73
	v_cvt_pk_bf16_f32 v69, v74, v75
	v_lshl_add_u64 v[70:71], v[76:77], 0, v[116:117]
	s_and_b64 vcc, exec, s[2:3]
	s_mov_b64 s[4:5], -1
	global_store_dwordx2 v[70:71], v[68:69], off
	s_cbranch_vccnz .LBB0_1340
	s_cmpk_gt_u32 s38, 0xbff
	v_mov_b32_e32 v71, v67
	v_mov_b32_e32 v70, v66
	v_mov_b32_e32 v69, v65
	v_mov_b32_e32 v68, v64
	s_cbranch_scc1 .LBB0_1339
	v_mov_b32_e32 v143, v129
	v_lshl_add_u64 v[68:69], v[142:143], 2, s[68:69]
	v_add_co_u32_e32 v68, vcc, 0x14103000, v68
	v_mul_f32_e32 v72, 0xbfb8aa3b, v64
	s_nop 0
	v_addc_co_u32_e32 v69, vcc, 0, v69, vcc
	global_load_dwordx4 v[68:71], v[68:69], off offset:192
	v_mul_f32_e32 v73, 0xbfb8aa3b, v65
	v_exp_f32_e32 v72, v72
	v_mul_f32_e32 v74, 0xbfb8aa3b, v66
	v_exp_f32_e32 v73, v73
	v_mul_f32_e32 v75, 0xbfb8aa3b, v67
	v_exp_f32_e32 v74, v74
	v_exp_f32_e32 v75, v75
	v_add_f32_e32 v72, 1.0, v72
	v_add_f32_e32 v73, 1.0, v73
	v_add_f32_e32 v74, 1.0, v74
	v_add_f32_e32 v75, 1.0, v75
	s_waitcnt vmcnt(0)
	v_sub_f32_e32 v78, 1.0, v68
	v_sub_f32_e32 v79, 1.0, v69
	v_sub_f32_e32 v80, 1.0, v70
	v_sub_f32_e32 v81, 1.0, v71
	s_mov_b64 vcc, s[4:5]
	v_rcp_f32_e32 v82, v72
	s_nop 0
	v_mul_f32_e32 v72, v78, v82
	s_mov_b64 vcc, s[6:7]
	v_add_f32_e32 v68, v68, v72
	v_rcp_f32_e32 v78, v73
	s_nop 0
	v_mul_f32_e32 v72, v79, v78
	s_mov_b64 vcc, s[8:9]
	v_add_f32_e32 v69, v69, v72
	v_rcp_f32_e32 v73, v74
	s_nop 0
	v_mul_f32_e32 v72, v80, v73
	v_add_f32_e32 v70, v70, v72
	v_rcp_f32_e32 v73, v75
	s_nop 0
	v_mul_f32_e32 v72, v81, v73
	v_add_f32_e32 v71, v71, v72
	v_log_f32_e32 v68, v68
	v_log_f32_e32 v69, v69
	v_log_f32_e32 v70, v70
	v_log_f32_e32 v71, v71

.LBB0_1340:
	s_andn2_b64 vcc, exec, s[4:5]
	s_cbranch_vccnz .LBB0_1342
	v_mul_f32_e32 v68, 0xbfb8aa3b, v64
	v_mul_f32_e32 v69, 0xbfb8aa3b, v65
	v_exp_f32_e32 v68, v68
	v_exp_f32_e32 v69, v69
	v_mul_f32_e32 v70, 0xbfb8aa3b, v66
	v_mul_f32_e32 v71, 0xbfb8aa3b, v67
	v_exp_f32_e32 v70, v70
	v_pk_add_f32 v[68:69], v[68:69], 1.0 op_sel_hi:[1,0]
	v_exp_f32_e32 v71, v71
	s_nop 0
	v_pk_add_f32 v[70:71], v[70:71], 1.0 op_sel_hi:[1,0]
	v_rcp_f32_e32 v72, v68
	s_nop 0
	v_mul_f32_e32 v68, v64, v72
	v_rcp_f32_e32 v64, v69
	s_nop 0
	v_mul_f32_e32 v69, v65, v64
	v_rcp_f32_e32 v64, v70
	s_nop 0
	v_mul_f32_e32 v70, v66, v64
	v_rcp_f32_e32 v64, v71
	s_nop 0
	v_mul_f32_e32 v71, v67, v64
.LBB0_1342:
	v_mov_b32_e32 v113, v129
	v_cvt_pk_bf16_f32 v64, v68, v69
	v_cvt_pk_bf16_f32 v65, v70, v71
	v_lshl_add_u64 v[66:67], v[76:77], 0, v[112:113]
	s_and_b64 vcc, exec, s[2:3]
	s_mov_b64 s[4:5], -1
	global_store_dwordx2 v[66:67], v[64:65], off
	s_cbranch_vccnz .LBB0_1346
	s_cmpk_gt_u32 s38, 0xbff
	v_mov_b32_e32 v67, v63
	v_mov_b32_e32 v66, v62
	v_mov_b32_e32 v65, v61
	v_mov_b32_e32 v64, v60
	s_cbranch_scc1 .LBB0_1345
	v_mov_b32_e32 v143, v129
	v_lshl_add_u64 v[64:65], v[142:143], 2, s[68:69]
	v_add_co_u32_e32 v64, vcc, 0x14103000, v64
	v_mul_f32_e32 v68, 0xbfb8aa3b, v60
	s_nop 0
	v_addc_co_u32_e32 v65, vcc, 0, v65, vcc
	global_load_dwordx4 v[64:67], v[64:65], off
	v_mul_f32_e32 v69, 0xbfb8aa3b, v61
	v_exp_f32_e32 v68, v68
	v_mul_f32_e32 v70, 0xbfb8aa3b, v62
	v_exp_f32_e32 v69, v69
	v_mul_f32_e32 v71, 0xbfb8aa3b, v63
	v_exp_f32_e32 v70, v70
	v_exp_f32_e32 v71, v71
	v_add_f32_e32 v68, 1.0, v68
	v_add_f32_e32 v69, 1.0, v69
	v_add_f32_e32 v70, 1.0, v70
	v_add_f32_e32 v71, 1.0, v71
	s_waitcnt vmcnt(0)
	v_sub_f32_e32 v72, 1.0, v64
	v_sub_f32_e32 v73, 1.0, v65
	v_sub_f32_e32 v74, 1.0, v66
	v_sub_f32_e32 v75, 1.0, v67
	s_mov_b64 vcc, s[4:5]
	v_rcp_f32_e32 v76, v68
	s_nop 0
	v_mul_f32_e32 v68, v72, v76
	s_mov_b64 vcc, s[6:7]
	v_add_f32_e32 v64, v64, v68
	v_rcp_f32_e32 v72, v69
	s_nop 0
	v_mul_f32_e32 v68, v73, v72
	s_mov_b64 vcc, s[8:9]
	v_add_f32_e32 v65, v65, v68
	v_rcp_f32_e32 v69, v70
	s_nop 0
	v_mul_f32_e32 v68, v74, v69
	v_add_f32_e32 v66, v66, v68
	v_rcp_f32_e32 v69, v71
	s_nop 0
	v_mul_f32_e32 v68, v75, v69
	v_add_f32_e32 v67, v67, v68
	v_log_f32_e32 v64, v64
	v_log_f32_e32 v65, v65
	v_log_f32_e32 v66, v66
	v_log_f32_e32 v67, v67

.LBB0_1346:
	s_andn2_b64 vcc, exec, s[4:5]
	s_cbranch_vccnz .LBB0_1348
	v_mul_f32_e32 v64, 0xbfb8aa3b, v60
	v_mul_f32_e32 v65, 0xbfb8aa3b, v61
	v_exp_f32_e32 v64, v64
	v_exp_f32_e32 v65, v65
	v_mul_f32_e32 v66, 0xbfb8aa3b, v62
	v_mul_f32_e32 v67, 0xbfb8aa3b, v63
	v_exp_f32_e32 v66, v66
	v_pk_add_f32 v[64:65], v[64:65], 1.0 op_sel_hi:[1,0]
	v_exp_f32_e32 v67, v67
	s_nop 0
	v_pk_add_f32 v[66:67], v[66:67], 1.0 op_sel_hi:[1,0]
	v_rcp_f32_e32 v68, v64
	s_nop 0
	v_mul_f32_e32 v64, v60, v68
	v_rcp_f32_e32 v60, v65
	s_nop 0
	v_mul_f32_e32 v65, v61, v60
	v_rcp_f32_e32 v60, v66
	s_nop 0
	v_mul_f32_e32 v66, v62, v60
	v_rcp_f32_e32 v60, v67
	s_nop 0
	v_mul_f32_e32 v67, v63, v60
.LBB0_1348:
	v_or_b32_e32 v60, 64, v124
	v_ashrrev_i32_e32 v61, 31, v60
	v_lshlrev_b64 v[60:61], 11, v[60:61]
	v_lshl_add_u64 v[60:61], s[40:41], 0, v[60:61]
	v_cvt_pk_bf16_f32 v62, v64, v65
	v_cvt_pk_bf16_f32 v63, v66, v67
	v_lshl_add_u64 v[64:65], v[60:61], 0, v[128:129]
	s_and_b64 vcc, exec, s[2:3]
	s_mov_b64 s[4:5], -1
	global_store_dwordx2 v[64:65], v[62:63], off
	s_cbranch_vccnz .LBB0_1352
	s_cmpk_gt_u32 s38, 0xbff
	v_mov_b32_e32 v65, v59
	v_mov_b32_e32 v64, v58
	v_mov_b32_e32 v63, v57
	v_mov_b32_e32 v62, v56
	s_cbranch_scc1 .LBB0_1351
	v_mov_b32_e32 v143, v129
	v_lshl_add_u64 v[62:63], v[142:143], 2, s[68:69]
	v_add_co_u32_e32 v62, vcc, 0x14103000, v62
	v_mul_f32_e32 v66, 0xbfb8aa3b, v56
	s_nop 0
	v_addc_co_u32_e32 v63, vcc, 0, v63, vcc
	global_load_dwordx4 v[62:65], v[62:63], off offset:64
	v_mul_f32_e32 v67, 0xbfb8aa3b, v57
	v_exp_f32_e32 v66, v66
	v_mul_f32_e32 v68, 0xbfb8aa3b, v58
	v_exp_f32_e32 v67, v67
	v_mul_f32_e32 v69, 0xbfb8aa3b, v59
	v_exp_f32_e32 v68, v68
	v_exp_f32_e32 v69, v69
	v_add_f32_e32 v66, 1.0, v66
	v_add_f32_e32 v67, 1.0, v67
	v_add_f32_e32 v68, 1.0, v68
	v_add_f32_e32 v69, 1.0, v69
	s_waitcnt vmcnt(0)
	v_sub_f32_e32 v70, 1.0, v62
	v_sub_f32_e32 v71, 1.0, v63
	v_sub_f32_e32 v72, 1.0, v64
	v_sub_f32_e32 v73, 1.0, v65
	s_mov_b64 vcc, s[4:5]
	v_rcp_f32_e32 v74, v66
	s_nop 0
	v_mul_f32_e32 v66, v70, v74
	s_mov_b64 vcc, s[6:7]
	v_add_f32_e32 v62, v62, v66
	v_rcp_f32_e32 v70, v67
	s_nop 0
	v_mul_f32_e32 v66, v71, v70
	s_mov_b64 vcc, s[8:9]
	v_add_f32_e32 v63, v63, v66
	v_rcp_f32_e32 v67, v68
	s_nop 0
	v_mul_f32_e32 v66, v72, v67
	v_add_f32_e32 v64, v64, v66
	v_rcp_f32_e32 v67, v69
	s_nop 0
	v_mul_f32_e32 v66, v73, v67
	v_add_f32_e32 v65, v65, v66
	v_log_f32_e32 v62, v62
	v_log_f32_e32 v63, v63
	v_log_f32_e32 v64, v64
	v_log_f32_e32 v65, v65

.LBB0_1352:
	s_andn2_b64 vcc, exec, s[4:5]
	s_cbranch_vccnz .LBB0_1354
	v_mul_f32_e32 v62, 0xbfb8aa3b, v56
	v_mul_f32_e32 v63, 0xbfb8aa3b, v57
	v_exp_f32_e32 v62, v62
	v_exp_f32_e32 v63, v63
	v_mul_f32_e32 v64, 0xbfb8aa3b, v58
	v_mul_f32_e32 v65, 0xbfb8aa3b, v59
	v_exp_f32_e32 v64, v64
	v_pk_add_f32 v[62:63], v[62:63], 1.0 op_sel_hi:[1,0]
	v_exp_f32_e32 v65, v65
	s_nop 0
	v_pk_add_f32 v[64:65], v[64:65], 1.0 op_sel_hi:[1,0]
	v_rcp_f32_e32 v66, v62
	s_nop 0
	v_mul_f32_e32 v62, v56, v66
	v_rcp_f32_e32 v56, v63
	s_nop 0
	v_mul_f32_e32 v63, v57, v56
	v_rcp_f32_e32 v56, v64
	s_nop 0
	v_mul_f32_e32 v64, v58, v56
	v_rcp_f32_e32 v56, v65
	s_nop 0
	v_mul_f32_e32 v65, v59, v56
.LBB0_1354:
	v_mov_b32_e32 v121, v129
	v_cvt_pk_bf16_f32 v56, v62, v63
	v_cvt_pk_bf16_f32 v57, v64, v65
	v_lshl_add_u64 v[58:59], v[60:61], 0, v[120:121]
	s_and_b64 vcc, exec, s[2:3]
	s_mov_b64 s[4:5], -1
	global_store_dwordx2 v[58:59], v[56:57], off
	s_cbranch_vccnz .LBB0_1358
	s_cmpk_gt_u32 s38, 0xbff
	v_mov_b32_e32 v59, v55
	v_mov_b32_e32 v58, v54
	v_mov_b32_e32 v57, v53
	v_mov_b32_e32 v56, v52
	s_cbranch_scc1 .LBB0_1357
	v_mov_b32_e32 v143, v129
	v_lshl_add_u64 v[56:57], v[142:143], 2, s[68:69]
	v_add_co_u32_e32 v56, vcc, 0x14103000, v56
	v_mul_f32_e32 v62, 0xbfb8aa3b, v52
	s_nop 0
	v_addc_co_u32_e32 v57, vcc, 0, v57, vcc
	global_load_dwordx4 v[56:59], v[56:57], off offset:128
	v_mul_f32_e32 v63, 0xbfb8aa3b, v53
	v_exp_f32_e32 v62, v62
	v_mul_f32_e32 v64, 0xbfb8aa3b, v54
	v_exp_f32_e32 v63, v63
	v_mul_f32_e32 v65, 0xbfb8aa3b, v55
	v_exp_f32_e32 v64, v64
	v_exp_f32_e32 v65, v65
	v_add_f32_e32 v62, 1.0, v62
	v_add_f32_e32 v63, 1.0, v63
	v_add_f32_e32 v64, 1.0, v64
	v_add_f32_e32 v65, 1.0, v65
	s_waitcnt vmcnt(0)
	v_sub_f32_e32 v66, 1.0, v56
	v_sub_f32_e32 v67, 1.0, v57
	v_sub_f32_e32 v68, 1.0, v58
	v_sub_f32_e32 v69, 1.0, v59
	s_mov_b64 vcc, s[4:5]
	v_rcp_f32_e32 v70, v62
	s_nop 0
	v_mul_f32_e32 v62, v66, v70
	s_mov_b64 vcc, s[6:7]
	v_add_f32_e32 v56, v56, v62
	v_rcp_f32_e32 v66, v63
	s_nop 0
	v_mul_f32_e32 v62, v67, v66
	s_mov_b64 vcc, s[8:9]
	v_add_f32_e32 v57, v57, v62
	v_rcp_f32_e32 v63, v64
	s_nop 0
	v_mul_f32_e32 v62, v68, v63
	v_add_f32_e32 v58, v58, v62
	v_rcp_f32_e32 v63, v65
	s_nop 0
	v_mul_f32_e32 v62, v69, v63
	v_add_f32_e32 v59, v59, v62
	v_log_f32_e32 v56, v56
	v_log_f32_e32 v57, v57
	v_log_f32_e32 v58, v58
	v_log_f32_e32 v59, v59

.LBB0_1358:
	s_andn2_b64 vcc, exec, s[4:5]
	s_cbranch_vccnz .LBB0_1360
	v_mul_f32_e32 v56, 0xbfb8aa3b, v52
	v_mul_f32_e32 v57, 0xbfb8aa3b, v53
	v_exp_f32_e32 v56, v56
	v_exp_f32_e32 v57, v57
	v_mul_f32_e32 v58, 0xbfb8aa3b, v54
	v_mul_f32_e32 v59, 0xbfb8aa3b, v55
	v_exp_f32_e32 v58, v58
	v_pk_add_f32 v[56:57], v[56:57], 1.0 op_sel_hi:[1,0]
	v_exp_f32_e32 v59, v59
	s_nop 0
	v_pk_add_f32 v[58:59], v[58:59], 1.0 op_sel_hi:[1,0]
	v_rcp_f32_e32 v62, v56
	s_nop 0
	v_mul_f32_e32 v56, v52, v62
	v_rcp_f32_e32 v52, v57
	s_nop 0
	v_mul_f32_e32 v57, v53, v52
	v_rcp_f32_e32 v52, v58
	s_nop 0
	v_mul_f32_e32 v58, v54, v52
	v_rcp_f32_e32 v52, v59
	s_nop 0
	v_mul_f32_e32 v59, v55, v52
.LBB0_1360:
	v_mov_b32_e32 v117, v129
	v_cvt_pk_bf16_f32 v52, v56, v57
	v_cvt_pk_bf16_f32 v53, v58, v59
	v_lshl_add_u64 v[54:55], v[60:61], 0, v[116:117]
	s_and_b64 vcc, exec, s[2:3]
	s_mov_b64 s[4:5], -1
	global_store_dwordx2 v[54:55], v[52:53], off
	s_cbranch_vccnz .LBB0_1364
	s_cmpk_gt_u32 s38, 0xbff
	v_mov_b32_e32 v55, v51
	v_mov_b32_e32 v54, v50
	v_mov_b32_e32 v53, v49
	v_mov_b32_e32 v52, v48
	s_cbranch_scc1 .LBB0_1363
	v_mov_b32_e32 v143, v129
	v_lshl_add_u64 v[52:53], v[142:143], 2, s[68:69]
	v_add_co_u32_e32 v52, vcc, 0x14103000, v52
	v_mul_f32_e32 v56, 0xbfb8aa3b, v48
	s_nop 0
	v_addc_co_u32_e32 v53, vcc, 0, v53, vcc
	global_load_dwordx4 v[52:55], v[52:53], off offset:192
	v_mul_f32_e32 v57, 0xbfb8aa3b, v49
	v_exp_f32_e32 v56, v56
	v_mul_f32_e32 v58, 0xbfb8aa3b, v50
	v_exp_f32_e32 v57, v57
	v_mul_f32_e32 v59, 0xbfb8aa3b, v51
	v_exp_f32_e32 v58, v58
	v_exp_f32_e32 v59, v59
	v_add_f32_e32 v56, 1.0, v56
	v_add_f32_e32 v57, 1.0, v57
	v_add_f32_e32 v58, 1.0, v58
	v_add_f32_e32 v59, 1.0, v59
	s_waitcnt vmcnt(0)
	v_sub_f32_e32 v62, 1.0, v52
	v_sub_f32_e32 v63, 1.0, v53
	v_sub_f32_e32 v64, 1.0, v54
	v_sub_f32_e32 v65, 1.0, v55
	s_mov_b64 vcc, s[4:5]
	v_rcp_f32_e32 v66, v56
	s_nop 0
	v_mul_f32_e32 v56, v62, v66
	s_mov_b64 vcc, s[6:7]
	v_add_f32_e32 v52, v52, v56
	v_rcp_f32_e32 v62, v57
	s_nop 0
	v_mul_f32_e32 v56, v63, v62
	s_mov_b64 vcc, s[8:9]
	v_add_f32_e32 v53, v53, v56
	v_rcp_f32_e32 v57, v58
	s_nop 0
	v_mul_f32_e32 v56, v64, v57
	v_add_f32_e32 v54, v54, v56
	v_rcp_f32_e32 v57, v59
	s_nop 0
	v_mul_f32_e32 v56, v65, v57
	v_add_f32_e32 v55, v55, v56
	v_log_f32_e32 v52, v52
	v_log_f32_e32 v53, v53
	v_log_f32_e32 v54, v54
	v_log_f32_e32 v55, v55

.LBB0_1364:
	s_andn2_b64 vcc, exec, s[4:5]
	s_cbranch_vccnz .LBB0_1366
	v_mul_f32_e32 v52, 0xbfb8aa3b, v48
	v_mul_f32_e32 v53, 0xbfb8aa3b, v49
	v_exp_f32_e32 v52, v52
	v_exp_f32_e32 v53, v53
	v_mul_f32_e32 v54, 0xbfb8aa3b, v50
	v_mul_f32_e32 v55, 0xbfb8aa3b, v51
	v_exp_f32_e32 v54, v54
	v_pk_add_f32 v[52:53], v[52:53], 1.0 op_sel_hi:[1,0]
	v_exp_f32_e32 v55, v55
	s_nop 0
	v_pk_add_f32 v[54:55], v[54:55], 1.0 op_sel_hi:[1,0]
	v_rcp_f32_e32 v56, v52
	s_nop 0
	v_mul_f32_e32 v52, v48, v56
	v_rcp_f32_e32 v48, v53
	s_nop 0
	v_mul_f32_e32 v53, v49, v48
	v_rcp_f32_e32 v48, v54
	s_nop 0
	v_mul_f32_e32 v54, v50, v48
	v_rcp_f32_e32 v48, v55
	s_nop 0
	v_mul_f32_e32 v55, v51, v48
.LBB0_1366:
	v_mov_b32_e32 v113, v129
	v_cvt_pk_bf16_f32 v48, v52, v53
	v_cvt_pk_bf16_f32 v49, v54, v55
	v_lshl_add_u64 v[50:51], v[60:61], 0, v[112:113]
	s_and_b64 vcc, exec, s[2:3]
	s_mov_b64 s[4:5], -1
	global_store_dwordx2 v[50:51], v[48:49], off
	s_cbranch_vccnz .LBB0_1370
	s_cmpk_gt_u32 s38, 0xbff
	v_mov_b32_e32 v51, v47
	v_mov_b32_e32 v50, v46
	v_mov_b32_e32 v49, v45
	v_mov_b32_e32 v48, v44
	s_cbranch_scc1 .LBB0_1369
	v_mov_b32_e32 v143, v129
	v_lshl_add_u64 v[48:49], v[142:143], 2, s[68:69]
	v_add_co_u32_e32 v48, vcc, 0x14103000, v48
	v_mul_f32_e32 v52, 0xbfb8aa3b, v44
	s_nop 0
	v_addc_co_u32_e32 v49, vcc, 0, v49, vcc
	global_load_dwordx4 v[48:51], v[48:49], off
	v_mul_f32_e32 v53, 0xbfb8aa3b, v45
	v_exp_f32_e32 v52, v52
	v_mul_f32_e32 v54, 0xbfb8aa3b, v46
	v_exp_f32_e32 v53, v53
	v_mul_f32_e32 v55, 0xbfb8aa3b, v47
	v_exp_f32_e32 v54, v54
	v_exp_f32_e32 v55, v55
	v_add_f32_e32 v52, 1.0, v52
	v_add_f32_e32 v53, 1.0, v53
	v_add_f32_e32 v54, 1.0, v54
	v_add_f32_e32 v55, 1.0, v55
	s_waitcnt vmcnt(0)
	v_sub_f32_e32 v56, 1.0, v48
	v_sub_f32_e32 v57, 1.0, v49
	v_sub_f32_e32 v58, 1.0, v50
	v_sub_f32_e32 v59, 1.0, v51
	s_mov_b64 vcc, s[4:5]
	v_rcp_f32_e32 v60, v52
	s_nop 0
	v_mul_f32_e32 v52, v56, v60
	s_mov_b64 vcc, s[6:7]
	v_add_f32_e32 v48, v48, v52
	v_rcp_f32_e32 v56, v53
	s_nop 0
	v_mul_f32_e32 v52, v57, v56
	s_mov_b64 vcc, s[8:9]
	v_add_f32_e32 v49, v49, v52
	v_rcp_f32_e32 v53, v54
	s_nop 0
	v_mul_f32_e32 v52, v58, v53
	v_add_f32_e32 v50, v50, v52
	v_rcp_f32_e32 v53, v55
	s_nop 0
	v_mul_f32_e32 v52, v59, v53
	v_add_f32_e32 v51, v51, v52
	v_log_f32_e32 v48, v48
	v_log_f32_e32 v49, v49
	v_log_f32_e32 v50, v50
	v_log_f32_e32 v51, v51

.LBB0_1370:
	s_andn2_b64 vcc, exec, s[4:5]
	s_cbranch_vccnz .LBB0_1372
	v_mul_f32_e32 v48, 0xbfb8aa3b, v44
	v_mul_f32_e32 v49, 0xbfb8aa3b, v45
	v_exp_f32_e32 v48, v48
	v_exp_f32_e32 v49, v49
	v_mul_f32_e32 v50, 0xbfb8aa3b, v46
	v_mul_f32_e32 v51, 0xbfb8aa3b, v47
	v_exp_f32_e32 v50, v50
	v_pk_add_f32 v[48:49], v[48:49], 1.0 op_sel_hi:[1,0]
	v_exp_f32_e32 v51, v51
	s_nop 0
	v_pk_add_f32 v[50:51], v[50:51], 1.0 op_sel_hi:[1,0]
	v_rcp_f32_e32 v52, v48
	s_nop 0
	v_mul_f32_e32 v48, v44, v52
	v_rcp_f32_e32 v44, v49
	s_nop 0
	v_mul_f32_e32 v49, v45, v44
	v_rcp_f32_e32 v44, v50
	s_nop 0
	v_mul_f32_e32 v50, v46, v44
	v_rcp_f32_e32 v44, v51
	s_nop 0
	v_mul_f32_e32 v51, v47, v44
.LBB0_1372:
	v_or_b32_e32 v44, 0x50, v124
	v_ashrrev_i32_e32 v45, 31, v44
	v_lshlrev_b64 v[44:45], 11, v[44:45]
	v_lshl_add_u64 v[44:45], s[40:41], 0, v[44:45]
	v_cvt_pk_bf16_f32 v46, v48, v49
	v_cvt_pk_bf16_f32 v47, v50, v51
	v_lshl_add_u64 v[48:49], v[44:45], 0, v[128:129]
	s_and_b64 vcc, exec, s[2:3]
	s_mov_b64 s[4:5], -1
	global_store_dwordx2 v[48:49], v[46:47], off
	s_cbranch_vccnz .LBB0_1376
	s_cmpk_gt_u32 s38, 0xbff
	v_mov_b32_e32 v49, v43
	v_mov_b32_e32 v48, v42
	v_mov_b32_e32 v47, v41
	v_mov_b32_e32 v46, v40
	s_cbranch_scc1 .LBB0_1375
	v_mov_b32_e32 v143, v129
	v_lshl_add_u64 v[46:47], v[142:143], 2, s[68:69]
	v_add_co_u32_e32 v46, vcc, 0x14103000, v46
	v_mul_f32_e32 v50, 0xbfb8aa3b, v40
	s_nop 0
	v_addc_co_u32_e32 v47, vcc, 0, v47, vcc
	global_load_dwordx4 v[46:49], v[46:47], off offset:64
	v_mul_f32_e32 v51, 0xbfb8aa3b, v41
	v_exp_f32_e32 v50, v50
	v_mul_f32_e32 v52, 0xbfb8aa3b, v42
	v_exp_f32_e32 v51, v51
	v_mul_f32_e32 v53, 0xbfb8aa3b, v43
	v_exp_f32_e32 v52, v52
	v_exp_f32_e32 v53, v53
	v_add_f32_e32 v50, 1.0, v50
	v_add_f32_e32 v51, 1.0, v51
	v_add_f32_e32 v52, 1.0, v52
	v_add_f32_e32 v53, 1.0, v53
	s_waitcnt vmcnt(0)
	v_sub_f32_e32 v54, 1.0, v46
	v_sub_f32_e32 v55, 1.0, v47
	v_sub_f32_e32 v56, 1.0, v48
	v_sub_f32_e32 v57, 1.0, v49
	s_mov_b64 vcc, s[4:5]
	v_rcp_f32_e32 v58, v50
	s_nop 0
	v_mul_f32_e32 v50, v54, v58
	s_mov_b64 vcc, s[6:7]
	v_add_f32_e32 v46, v46, v50
	v_rcp_f32_e32 v54, v51
	s_nop 0
	v_mul_f32_e32 v50, v55, v54
	s_mov_b64 vcc, s[8:9]
	v_add_f32_e32 v47, v47, v50
	v_rcp_f32_e32 v51, v52
	s_nop 0
	v_mul_f32_e32 v50, v56, v51
	v_add_f32_e32 v48, v48, v50
	v_rcp_f32_e32 v51, v53
	s_nop 0
	v_mul_f32_e32 v50, v57, v51
	v_add_f32_e32 v49, v49, v50
	v_log_f32_e32 v46, v46
	v_log_f32_e32 v47, v47
	v_log_f32_e32 v48, v48
	v_log_f32_e32 v49, v49

.LBB0_1376:
	s_andn2_b64 vcc, exec, s[4:5]
	s_cbranch_vccnz .LBB0_1378
	v_mul_f32_e32 v46, 0xbfb8aa3b, v40
	v_mul_f32_e32 v47, 0xbfb8aa3b, v41
	v_exp_f32_e32 v46, v46
	v_exp_f32_e32 v47, v47
	v_mul_f32_e32 v48, 0xbfb8aa3b, v42
	v_mul_f32_e32 v49, 0xbfb8aa3b, v43
	v_exp_f32_e32 v48, v48
	v_pk_add_f32 v[46:47], v[46:47], 1.0 op_sel_hi:[1,0]
	v_exp_f32_e32 v49, v49
	s_nop 0
	v_pk_add_f32 v[48:49], v[48:49], 1.0 op_sel_hi:[1,0]
	v_rcp_f32_e32 v50, v46
	s_nop 0
	v_mul_f32_e32 v46, v40, v50
	v_rcp_f32_e32 v40, v47
	s_nop 0
	v_mul_f32_e32 v47, v41, v40
	v_rcp_f32_e32 v40, v48
	s_nop 0
	v_mul_f32_e32 v48, v42, v40
	v_rcp_f32_e32 v40, v49
	s_nop 0
	v_mul_f32_e32 v49, v43, v40
.LBB0_1378:
	v_mov_b32_e32 v121, v129
	v_cvt_pk_bf16_f32 v40, v46, v47
	v_cvt_pk_bf16_f32 v41, v48, v49
	v_lshl_add_u64 v[42:43], v[44:45], 0, v[120:121]
	s_and_b64 vcc, exec, s[2:3]
	s_mov_b64 s[4:5], -1
	global_store_dwordx2 v[42:43], v[40:41], off
	s_cbranch_vccnz .LBB0_1382
	s_cmpk_gt_u32 s38, 0xbff
	v_mov_b32_e32 v43, v39
	v_mov_b32_e32 v42, v38
	v_mov_b32_e32 v41, v37
	v_mov_b32_e32 v40, v36
	s_cbranch_scc1 .LBB0_1381
	v_mov_b32_e32 v143, v129
	v_lshl_add_u64 v[40:41], v[142:143], 2, s[68:69]
	v_add_co_u32_e32 v40, vcc, 0x14103000, v40
	v_mul_f32_e32 v46, 0xbfb8aa3b, v36
	s_nop 0
	v_addc_co_u32_e32 v41, vcc, 0, v41, vcc
	global_load_dwordx4 v[40:43], v[40:41], off offset:128
	v_mul_f32_e32 v47, 0xbfb8aa3b, v37
	v_exp_f32_e32 v46, v46
	v_mul_f32_e32 v48, 0xbfb8aa3b, v38
	v_exp_f32_e32 v47, v47
	v_mul_f32_e32 v49, 0xbfb8aa3b, v39
	v_exp_f32_e32 v48, v48
	v_exp_f32_e32 v49, v49
	v_add_f32_e32 v46, 1.0, v46
	v_add_f32_e32 v47, 1.0, v47
	v_add_f32_e32 v48, 1.0, v48
	v_add_f32_e32 v49, 1.0, v49
	s_waitcnt vmcnt(0)
	v_sub_f32_e32 v50, 1.0, v40
	v_sub_f32_e32 v51, 1.0, v41
	v_sub_f32_e32 v52, 1.0, v42
	v_sub_f32_e32 v53, 1.0, v43
	s_mov_b64 vcc, s[4:5]
	v_rcp_f32_e32 v54, v46
	s_nop 0
	v_mul_f32_e32 v46, v50, v54
	s_mov_b64 vcc, s[6:7]
	v_add_f32_e32 v40, v40, v46
	v_rcp_f32_e32 v50, v47
	s_nop 0
	v_mul_f32_e32 v46, v51, v50
	s_mov_b64 vcc, s[8:9]
	v_add_f32_e32 v41, v41, v46
	v_rcp_f32_e32 v47, v48
	s_nop 0
	v_mul_f32_e32 v46, v52, v47
	v_add_f32_e32 v42, v42, v46
	v_rcp_f32_e32 v47, v49
	s_nop 0
	v_mul_f32_e32 v46, v53, v47
	v_add_f32_e32 v43, v43, v46
	v_log_f32_e32 v40, v40
	v_log_f32_e32 v41, v41
	v_log_f32_e32 v42, v42
	v_log_f32_e32 v43, v43

.LBB0_1382:
	s_andn2_b64 vcc, exec, s[4:5]
	s_cbranch_vccnz .LBB0_1384
	v_mul_f32_e32 v40, 0xbfb8aa3b, v36
	v_mul_f32_e32 v41, 0xbfb8aa3b, v37
	v_exp_f32_e32 v40, v40
	v_exp_f32_e32 v41, v41
	v_mul_f32_e32 v42, 0xbfb8aa3b, v38
	v_mul_f32_e32 v43, 0xbfb8aa3b, v39
	v_exp_f32_e32 v42, v42
	v_pk_add_f32 v[40:41], v[40:41], 1.0 op_sel_hi:[1,0]
	v_exp_f32_e32 v43, v43
	s_nop 0
	v_pk_add_f32 v[42:43], v[42:43], 1.0 op_sel_hi:[1,0]
	v_rcp_f32_e32 v46, v40
	s_nop 0
	v_mul_f32_e32 v40, v36, v46
	v_rcp_f32_e32 v36, v41
	s_nop 0
	v_mul_f32_e32 v41, v37, v36
	v_rcp_f32_e32 v36, v42
	s_nop 0
	v_mul_f32_e32 v42, v38, v36
	v_rcp_f32_e32 v36, v43
	s_nop 0
	v_mul_f32_e32 v43, v39, v36
.LBB0_1384:
	v_mov_b32_e32 v117, v129
	v_cvt_pk_bf16_f32 v36, v40, v41
	v_cvt_pk_bf16_f32 v37, v42, v43
	v_lshl_add_u64 v[38:39], v[44:45], 0, v[116:117]
	s_and_b64 vcc, exec, s[2:3]
	s_mov_b64 s[4:5], -1
	global_store_dwordx2 v[38:39], v[36:37], off
	s_cbranch_vccnz .LBB0_1388
	s_cmpk_gt_u32 s38, 0xbff
	v_mov_b32_e32 v39, v35
	v_mov_b32_e32 v38, v34
	v_mov_b32_e32 v37, v33
	v_mov_b32_e32 v36, v32
	s_cbranch_scc1 .LBB0_1387
	v_mov_b32_e32 v143, v129
	v_lshl_add_u64 v[36:37], v[142:143], 2, s[68:69]
	v_add_co_u32_e32 v36, vcc, 0x14103000, v36
	v_mul_f32_e32 v40, 0xbfb8aa3b, v32
	s_nop 0
	v_addc_co_u32_e32 v37, vcc, 0, v37, vcc
	global_load_dwordx4 v[36:39], v[36:37], off offset:192
	v_mul_f32_e32 v41, 0xbfb8aa3b, v33
	v_exp_f32_e32 v40, v40
	v_mul_f32_e32 v42, 0xbfb8aa3b, v34
	v_exp_f32_e32 v41, v41
	v_mul_f32_e32 v43, 0xbfb8aa3b, v35
	v_exp_f32_e32 v42, v42
	v_exp_f32_e32 v43, v43
	v_add_f32_e32 v40, 1.0, v40
	v_add_f32_e32 v41, 1.0, v41
	v_add_f32_e32 v42, 1.0, v42
	v_add_f32_e32 v43, 1.0, v43
	s_waitcnt vmcnt(0)
	v_sub_f32_e32 v46, 1.0, v36
	v_sub_f32_e32 v47, 1.0, v37
	v_sub_f32_e32 v48, 1.0, v38
	v_sub_f32_e32 v49, 1.0, v39
	s_mov_b64 vcc, s[4:5]
	v_rcp_f32_e32 v50, v40
	s_nop 0
	v_mul_f32_e32 v40, v46, v50
	s_mov_b64 vcc, s[6:7]
	v_add_f32_e32 v36, v36, v40
	v_rcp_f32_e32 v46, v41
	s_nop 0
	v_mul_f32_e32 v40, v47, v46
	s_mov_b64 vcc, s[8:9]
	v_add_f32_e32 v37, v37, v40
	v_rcp_f32_e32 v41, v42
	s_nop 0
	v_mul_f32_e32 v40, v48, v41
	v_add_f32_e32 v38, v38, v40
	v_rcp_f32_e32 v41, v43
	s_nop 0
	v_mul_f32_e32 v40, v49, v41
	v_add_f32_e32 v39, v39, v40
	v_log_f32_e32 v36, v36
	v_log_f32_e32 v37, v37
	v_log_f32_e32 v38, v38
	v_log_f32_e32 v39, v39

.LBB0_1388:
	s_andn2_b64 vcc, exec, s[4:5]
	s_cbranch_vccnz .LBB0_1390
	v_mul_f32_e32 v36, 0xbfb8aa3b, v32
	v_mul_f32_e32 v37, 0xbfb8aa3b, v33
	v_exp_f32_e32 v36, v36
	v_exp_f32_e32 v37, v37
	v_mul_f32_e32 v38, 0xbfb8aa3b, v34
	v_mul_f32_e32 v39, 0xbfb8aa3b, v35
	v_exp_f32_e32 v38, v38
	v_pk_add_f32 v[36:37], v[36:37], 1.0 op_sel_hi:[1,0]
	v_exp_f32_e32 v39, v39
	s_nop 0
	v_pk_add_f32 v[38:39], v[38:39], 1.0 op_sel_hi:[1,0]
	v_rcp_f32_e32 v40, v36
	s_nop 0
	v_mul_f32_e32 v36, v32, v40
	v_rcp_f32_e32 v32, v37
	s_nop 0
	v_mul_f32_e32 v37, v33, v32
	v_rcp_f32_e32 v32, v38
	s_nop 0
	v_mul_f32_e32 v38, v34, v32
	v_rcp_f32_e32 v32, v39
	s_nop 0
	v_mul_f32_e32 v39, v35, v32
.LBB0_1390:
	v_mov_b32_e32 v113, v129
	v_cvt_pk_bf16_f32 v32, v36, v37
	v_cvt_pk_bf16_f32 v33, v38, v39
	v_lshl_add_u64 v[34:35], v[44:45], 0, v[112:113]
	s_and_b64 vcc, exec, s[2:3]
	s_mov_b64 s[4:5], -1
	global_store_dwordx2 v[34:35], v[32:33], off
	s_cbranch_vccnz .LBB0_1394
	s_cmpk_gt_u32 s38, 0xbff
	v_mov_b32_e32 v35, v31
	v_mov_b32_e32 v34, v30
	v_mov_b32_e32 v33, v29
	v_mov_b32_e32 v32, v28
	s_cbranch_scc1 .LBB0_1393
	v_mov_b32_e32 v143, v129
	v_lshl_add_u64 v[32:33], v[142:143], 2, s[68:69]
	v_add_co_u32_e32 v32, vcc, 0x14103000, v32
	v_mul_f32_e32 v36, 0xbfb8aa3b, v28
	s_nop 0
	v_addc_co_u32_e32 v33, vcc, 0, v33, vcc
	global_load_dwordx4 v[32:35], v[32:33], off
	v_mul_f32_e32 v37, 0xbfb8aa3b, v29
	v_exp_f32_e32 v36, v36
	v_mul_f32_e32 v38, 0xbfb8aa3b, v30
	v_exp_f32_e32 v37, v37
	v_mul_f32_e32 v39, 0xbfb8aa3b, v31
	v_exp_f32_e32 v38, v38
	v_exp_f32_e32 v39, v39
	v_add_f32_e32 v36, 1.0, v36
	v_add_f32_e32 v37, 1.0, v37
	v_add_f32_e32 v38, 1.0, v38
	v_add_f32_e32 v39, 1.0, v39
	s_waitcnt vmcnt(0)
	v_sub_f32_e32 v40, 1.0, v32
	v_sub_f32_e32 v41, 1.0, v33
	v_sub_f32_e32 v42, 1.0, v34
	v_sub_f32_e32 v43, 1.0, v35
	s_mov_b64 vcc, s[4:5]
	v_rcp_f32_e32 v44, v36
	s_nop 0
	v_mul_f32_e32 v36, v40, v44
	s_mov_b64 vcc, s[6:7]
	v_add_f32_e32 v32, v32, v36
	v_rcp_f32_e32 v40, v37
	s_nop 0
	v_mul_f32_e32 v36, v41, v40
	s_mov_b64 vcc, s[8:9]
	v_add_f32_e32 v33, v33, v36
	v_rcp_f32_e32 v37, v38
	s_nop 0
	v_mul_f32_e32 v36, v42, v37
	v_add_f32_e32 v34, v34, v36
	v_rcp_f32_e32 v37, v39
	s_nop 0
	v_mul_f32_e32 v36, v43, v37
	v_add_f32_e32 v35, v35, v36
	v_log_f32_e32 v32, v32
	v_log_f32_e32 v33, v33
	v_log_f32_e32 v34, v34
	v_log_f32_e32 v35, v35

.LBB0_1394:
	s_andn2_b64 vcc, exec, s[4:5]
	s_cbranch_vccnz .LBB0_1396
	v_mul_f32_e32 v32, 0xbfb8aa3b, v28
	v_mul_f32_e32 v33, 0xbfb8aa3b, v29
	v_exp_f32_e32 v32, v32
	v_exp_f32_e32 v33, v33
	v_mul_f32_e32 v34, 0xbfb8aa3b, v30
	v_mul_f32_e32 v35, 0xbfb8aa3b, v31
	v_exp_f32_e32 v34, v34
	v_pk_add_f32 v[32:33], v[32:33], 1.0 op_sel_hi:[1,0]
	v_exp_f32_e32 v35, v35
	s_nop 0
	v_pk_add_f32 v[34:35], v[34:35], 1.0 op_sel_hi:[1,0]
	v_rcp_f32_e32 v36, v32
	s_nop 0
	v_mul_f32_e32 v32, v28, v36
	v_rcp_f32_e32 v28, v33
	s_nop 0
	v_mul_f32_e32 v33, v29, v28
	v_rcp_f32_e32 v28, v34
	s_nop 0
	v_mul_f32_e32 v34, v30, v28
	v_rcp_f32_e32 v28, v35
	s_nop 0
	v_mul_f32_e32 v35, v31, v28
.LBB0_1396:
	v_or_b32_e32 v28, 0x60, v124
	v_ashrrev_i32_e32 v29, 31, v28
	v_lshlrev_b64 v[28:29], 11, v[28:29]
	v_lshl_add_u64 v[28:29], s[40:41], 0, v[28:29]
	v_cvt_pk_bf16_f32 v30, v32, v33
	v_cvt_pk_bf16_f32 v31, v34, v35
	v_lshl_add_u64 v[32:33], v[28:29], 0, v[128:129]
	s_and_b64 vcc, exec, s[2:3]
	s_mov_b64 s[4:5], -1
	global_store_dwordx2 v[32:33], v[30:31], off
	s_cbranch_vccnz .LBB0_1400
	s_cmpk_gt_u32 s38, 0xbff
	v_mov_b32_e32 v33, v27
	v_mov_b32_e32 v32, v26
	v_mov_b32_e32 v31, v25
	v_mov_b32_e32 v30, v24
	s_cbranch_scc1 .LBB0_1399
	v_mov_b32_e32 v143, v129
	v_lshl_add_u64 v[30:31], v[142:143], 2, s[68:69]
	v_add_co_u32_e32 v30, vcc, 0x14103000, v30
	v_mul_f32_e32 v34, 0xbfb8aa3b, v24
	s_nop 0
	v_addc_co_u32_e32 v31, vcc, 0, v31, vcc
	global_load_dwordx4 v[30:33], v[30:31], off offset:64
	v_mul_f32_e32 v35, 0xbfb8aa3b, v25
	v_exp_f32_e32 v34, v34
	v_mul_f32_e32 v36, 0xbfb8aa3b, v26
	v_exp_f32_e32 v35, v35
	v_mul_f32_e32 v37, 0xbfb8aa3b, v27
	v_exp_f32_e32 v36, v36
	v_exp_f32_e32 v37, v37
	v_add_f32_e32 v34, 1.0, v34
	v_add_f32_e32 v35, 1.0, v35
	v_add_f32_e32 v36, 1.0, v36
	v_add_f32_e32 v37, 1.0, v37
	s_waitcnt vmcnt(0)
	v_sub_f32_e32 v38, 1.0, v30
	v_sub_f32_e32 v39, 1.0, v31
	v_sub_f32_e32 v40, 1.0, v32
	v_sub_f32_e32 v41, 1.0, v33
	s_mov_b64 vcc, s[4:5]
	v_rcp_f32_e32 v42, v34
	s_nop 0
	v_mul_f32_e32 v34, v38, v42
	s_mov_b64 vcc, s[6:7]
	v_add_f32_e32 v30, v30, v34
	v_rcp_f32_e32 v38, v35
	s_nop 0
	v_mul_f32_e32 v34, v39, v38
	s_mov_b64 vcc, s[8:9]
	v_add_f32_e32 v31, v31, v34
	v_rcp_f32_e32 v35, v36
	s_nop 0
	v_mul_f32_e32 v34, v40, v35
	v_add_f32_e32 v32, v32, v34
	v_rcp_f32_e32 v35, v37
	s_nop 0
	v_mul_f32_e32 v34, v41, v35
	v_add_f32_e32 v33, v33, v34
	v_log_f32_e32 v30, v30
	v_log_f32_e32 v31, v31
	v_log_f32_e32 v32, v32
	v_log_f32_e32 v33, v33

.LBB0_1400:
	s_andn2_b64 vcc, exec, s[4:5]
	s_cbranch_vccnz .LBB0_1402
	v_mul_f32_e32 v30, 0xbfb8aa3b, v24
	v_mul_f32_e32 v31, 0xbfb8aa3b, v25
	v_exp_f32_e32 v30, v30
	v_exp_f32_e32 v31, v31
	v_mul_f32_e32 v32, 0xbfb8aa3b, v26
	v_mul_f32_e32 v33, 0xbfb8aa3b, v27
	v_exp_f32_e32 v32, v32
	v_pk_add_f32 v[30:31], v[30:31], 1.0 op_sel_hi:[1,0]
	v_exp_f32_e32 v33, v33
	s_nop 0
	v_pk_add_f32 v[32:33], v[32:33], 1.0 op_sel_hi:[1,0]
	v_rcp_f32_e32 v34, v30
	s_nop 0
	v_mul_f32_e32 v30, v24, v34
	v_rcp_f32_e32 v24, v31
	s_nop 0
	v_mul_f32_e32 v31, v25, v24
	v_rcp_f32_e32 v24, v32
	s_nop 0
	v_mul_f32_e32 v32, v26, v24
	v_rcp_f32_e32 v24, v33
	s_nop 0
	v_mul_f32_e32 v33, v27, v24
.LBB0_1402:
	v_mov_b32_e32 v121, v129
	v_cvt_pk_bf16_f32 v24, v30, v31
	v_cvt_pk_bf16_f32 v25, v32, v33
	v_lshl_add_u64 v[26:27], v[28:29], 0, v[120:121]
	s_and_b64 vcc, exec, s[2:3]
	s_mov_b64 s[4:5], -1
	global_store_dwordx2 v[26:27], v[24:25], off
	s_cbranch_vccnz .LBB0_1406
	s_cmpk_gt_u32 s38, 0xbff
	v_mov_b32_e32 v27, v23
	v_mov_b32_e32 v26, v22
	v_mov_b32_e32 v25, v21
	v_mov_b32_e32 v24, v20
	s_cbranch_scc1 .LBB0_1405
	v_mov_b32_e32 v143, v129
	v_lshl_add_u64 v[24:25], v[142:143], 2, s[68:69]
	v_add_co_u32_e32 v24, vcc, 0x14103000, v24
	v_mul_f32_e32 v30, 0xbfb8aa3b, v20
	s_nop 0
	v_addc_co_u32_e32 v25, vcc, 0, v25, vcc
	global_load_dwordx4 v[24:27], v[24:25], off offset:128
	v_mul_f32_e32 v31, 0xbfb8aa3b, v21
	v_exp_f32_e32 v30, v30
	v_mul_f32_e32 v32, 0xbfb8aa3b, v22
	v_exp_f32_e32 v31, v31
	v_mul_f32_e32 v33, 0xbfb8aa3b, v23
	v_exp_f32_e32 v32, v32
	v_exp_f32_e32 v33, v33
	v_add_f32_e32 v30, 1.0, v30
	v_add_f32_e32 v31, 1.0, v31
	v_add_f32_e32 v32, 1.0, v32
	v_add_f32_e32 v33, 1.0, v33
	s_waitcnt vmcnt(0)
	v_sub_f32_e32 v34, 1.0, v24
	v_sub_f32_e32 v35, 1.0, v25
	v_sub_f32_e32 v36, 1.0, v26
	v_sub_f32_e32 v37, 1.0, v27
	s_mov_b64 vcc, s[4:5]
	v_rcp_f32_e32 v38, v30
	s_nop 0
	v_mul_f32_e32 v30, v34, v38
	s_mov_b64 vcc, s[6:7]
	v_add_f32_e32 v24, v24, v30
	v_rcp_f32_e32 v34, v31
	s_nop 0
	v_mul_f32_e32 v30, v35, v34
	s_mov_b64 vcc, s[8:9]
	v_add_f32_e32 v25, v25, v30
	v_rcp_f32_e32 v31, v32
	s_nop 0
	v_mul_f32_e32 v30, v36, v31
	v_add_f32_e32 v26, v26, v30
	v_rcp_f32_e32 v31, v33
	s_nop 0
	v_mul_f32_e32 v30, v37, v31
	v_add_f32_e32 v27, v27, v30
	v_log_f32_e32 v24, v24
	v_log_f32_e32 v25, v25
	v_log_f32_e32 v26, v26
	v_log_f32_e32 v27, v27

.LBB0_1406:
	s_andn2_b64 vcc, exec, s[4:5]
	s_cbranch_vccnz .LBB0_1408
	v_mul_f32_e32 v24, 0xbfb8aa3b, v20
	v_mul_f32_e32 v25, 0xbfb8aa3b, v21
	v_exp_f32_e32 v24, v24
	v_exp_f32_e32 v25, v25
	v_mul_f32_e32 v26, 0xbfb8aa3b, v22
	v_mul_f32_e32 v27, 0xbfb8aa3b, v23
	v_exp_f32_e32 v26, v26
	v_pk_add_f32 v[24:25], v[24:25], 1.0 op_sel_hi:[1,0]
	v_exp_f32_e32 v27, v27
	s_nop 0
	v_pk_add_f32 v[26:27], v[26:27], 1.0 op_sel_hi:[1,0]
	v_rcp_f32_e32 v30, v24
	s_nop 0
	v_mul_f32_e32 v24, v20, v30
	v_rcp_f32_e32 v20, v25
	s_nop 0
	v_mul_f32_e32 v25, v21, v20
	v_rcp_f32_e32 v20, v26
	s_nop 0
	v_mul_f32_e32 v26, v22, v20
	v_rcp_f32_e32 v20, v27
	s_nop 0
	v_mul_f32_e32 v27, v23, v20
.LBB0_1408:
	v_mov_b32_e32 v117, v129
	v_cvt_pk_bf16_f32 v20, v24, v25
	v_cvt_pk_bf16_f32 v21, v26, v27
	v_lshl_add_u64 v[22:23], v[28:29], 0, v[116:117]
	s_and_b64 vcc, exec, s[2:3]
	s_mov_b64 s[4:5], -1
	global_store_dwordx2 v[22:23], v[20:21], off
	s_cbranch_vccnz .LBB0_1412
	s_cmpk_gt_u32 s38, 0xbff
	v_mov_b32_e32 v23, v19
	v_mov_b32_e32 v22, v18
	v_mov_b32_e32 v21, v17
	v_mov_b32_e32 v20, v16
	s_cbranch_scc1 .LBB0_1411
	v_mov_b32_e32 v143, v129
	v_lshl_add_u64 v[20:21], v[142:143], 2, s[68:69]
	v_add_co_u32_e32 v20, vcc, 0x14103000, v20
	v_mul_f32_e32 v24, 0xbfb8aa3b, v16
	s_nop 0
	v_addc_co_u32_e32 v21, vcc, 0, v21, vcc
	global_load_dwordx4 v[20:23], v[20:21], off offset:192
	v_mul_f32_e32 v25, 0xbfb8aa3b, v17
	v_exp_f32_e32 v24, v24
	v_mul_f32_e32 v26, 0xbfb8aa3b, v18
	v_exp_f32_e32 v25, v25
	v_mul_f32_e32 v27, 0xbfb8aa3b, v19
	v_exp_f32_e32 v26, v26
	v_exp_f32_e32 v27, v27
	v_add_f32_e32 v24, 1.0, v24
	v_add_f32_e32 v25, 1.0, v25
	v_add_f32_e32 v26, 1.0, v26
	v_add_f32_e32 v27, 1.0, v27
	s_waitcnt vmcnt(0)
	v_sub_f32_e32 v30, 1.0, v20
	v_sub_f32_e32 v31, 1.0, v21
	v_sub_f32_e32 v32, 1.0, v22
	v_sub_f32_e32 v33, 1.0, v23
	s_mov_b64 vcc, s[4:5]
	v_rcp_f32_e32 v34, v24
	s_nop 0
	v_mul_f32_e32 v24, v30, v34
	s_mov_b64 vcc, s[6:7]
	v_add_f32_e32 v20, v20, v24
	v_rcp_f32_e32 v30, v25
	s_nop 0
	v_mul_f32_e32 v24, v31, v30
	s_mov_b64 vcc, s[8:9]
	v_add_f32_e32 v21, v21, v24
	v_rcp_f32_e32 v25, v26
	s_nop 0
	v_mul_f32_e32 v24, v32, v25
	v_add_f32_e32 v22, v22, v24
	v_rcp_f32_e32 v25, v27
	s_nop 0
	v_mul_f32_e32 v24, v33, v25
	v_add_f32_e32 v23, v23, v24
	v_log_f32_e32 v20, v20
	v_log_f32_e32 v21, v21
	v_log_f32_e32 v22, v22
	v_log_f32_e32 v23, v23

.LBB0_1412:
	s_andn2_b64 vcc, exec, s[4:5]
	s_cbranch_vccnz .LBB0_1414
	v_mul_f32_e32 v20, 0xbfb8aa3b, v16
	v_mul_f32_e32 v21, 0xbfb8aa3b, v17
	v_exp_f32_e32 v20, v20
	v_exp_f32_e32 v21, v21
	v_mul_f32_e32 v22, 0xbfb8aa3b, v18
	v_mul_f32_e32 v23, 0xbfb8aa3b, v19
	v_exp_f32_e32 v22, v22
	v_pk_add_f32 v[20:21], v[20:21], 1.0 op_sel_hi:[1,0]
	v_exp_f32_e32 v23, v23
	s_nop 0
	v_pk_add_f32 v[22:23], v[22:23], 1.0 op_sel_hi:[1,0]
	v_rcp_f32_e32 v24, v20
	s_nop 0
	v_mul_f32_e32 v20, v16, v24
	v_rcp_f32_e32 v16, v21
	s_nop 0
	v_mul_f32_e32 v21, v17, v16
	v_rcp_f32_e32 v16, v22
	s_nop 0
	v_mul_f32_e32 v22, v18, v16
	v_rcp_f32_e32 v16, v23
	s_nop 0
	v_mul_f32_e32 v23, v19, v16
.LBB0_1414:
	v_mov_b32_e32 v113, v129
	v_cvt_pk_bf16_f32 v16, v20, v21
	v_cvt_pk_bf16_f32 v17, v22, v23
	v_lshl_add_u64 v[18:19], v[28:29], 0, v[112:113]
	s_and_b64 vcc, exec, s[2:3]
	s_mov_b64 s[2:3], -1
	global_store_dwordx2 v[18:19], v[16:17], off
	s_cbranch_vccnz .LBB0_1418
	s_cmpk_gt_u32 s38, 0xbff
	v_mov_b32_e32 v19, v15
	v_mov_b32_e32 v18, v14
	v_mov_b32_e32 v17, v13
	v_mov_b32_e32 v16, v12
	s_cbranch_scc1 .LBB0_1417
	v_mov_b32_e32 v143, v129
	v_lshl_add_u64 v[16:17], v[142:143], 2, s[68:69]
	v_add_co_u32_e32 v16, vcc, 0x14103000, v16
	v_mul_f32_e32 v20, 0xbfb8aa3b, v12
	s_nop 0
	v_addc_co_u32_e32 v17, vcc, 0, v17, vcc
	global_load_dwordx4 v[16:19], v[16:17], off
	v_mul_f32_e32 v21, 0xbfb8aa3b, v13
	v_exp_f32_e32 v20, v20
	v_mul_f32_e32 v22, 0xbfb8aa3b, v14
	v_exp_f32_e32 v21, v21
	v_mul_f32_e32 v23, 0xbfb8aa3b, v15
	v_exp_f32_e32 v22, v22
	v_exp_f32_e32 v23, v23
	v_add_f32_e32 v20, 1.0, v20
	v_add_f32_e32 v21, 1.0, v21
	v_add_f32_e32 v22, 1.0, v22
	v_add_f32_e32 v23, 1.0, v23
	s_waitcnt vmcnt(0)
	v_sub_f32_e32 v24, 1.0, v16
	v_sub_f32_e32 v25, 1.0, v17
	v_sub_f32_e32 v26, 1.0, v18
	v_sub_f32_e32 v27, 1.0, v19
	s_mov_b64 vcc, s[2:3]
	v_rcp_f32_e32 v28, v20
	s_nop 0
	v_mul_f32_e32 v20, v24, v28
	s_mov_b64 vcc, s[4:5]
	v_add_f32_e32 v16, v16, v20
	v_rcp_f32_e32 v24, v21
	s_nop 0
	v_mul_f32_e32 v20, v25, v24
	s_mov_b64 vcc, s[6:7]
	v_add_f32_e32 v17, v17, v20
	v_rcp_f32_e32 v21, v22
	s_nop 0
	v_mul_f32_e32 v20, v26, v21
	v_add_f32_e32 v18, v18, v20
	v_rcp_f32_e32 v21, v23
	s_nop 0
	v_mul_f32_e32 v20, v27, v21
	v_add_f32_e32 v19, v19, v20
	v_log_f32_e32 v16, v16
	v_log_f32_e32 v17, v17
	v_log_f32_e32 v18, v18
	v_log_f32_e32 v19, v19

.LBB0_1418:
	s_andn2_b64 vcc, exec, s[2:3]
	s_cbranch_vccnz .LBB0_1420
	v_mul_f32_e32 v16, 0xbfb8aa3b, v12
	v_mul_f32_e32 v17, 0xbfb8aa3b, v13
	v_exp_f32_e32 v16, v16
	v_exp_f32_e32 v17, v17
	v_mul_f32_e32 v18, 0xbfb8aa3b, v14
	v_mul_f32_e32 v19, 0xbfb8aa3b, v15
	v_exp_f32_e32 v18, v18
	v_pk_add_f32 v[16:17], v[16:17], 1.0 op_sel_hi:[1,0]
	v_exp_f32_e32 v19, v19
	s_nop 0
	v_pk_add_f32 v[18:19], v[18:19], 1.0 op_sel_hi:[1,0]
	v_rcp_f32_e32 v20, v16
	s_nop 0
	v_mul_f32_e32 v16, v12, v20
	v_rcp_f32_e32 v12, v17
	s_nop 0
	v_mul_f32_e32 v17, v13, v12
	v_rcp_f32_e32 v12, v18
	s_nop 0
	v_mul_f32_e32 v18, v14, v12
	v_rcp_f32_e32 v12, v19
	s_nop 0
	v_mul_f32_e32 v19, v15, v12
.LBB0_1420:
	v_or_b32_e32 v12, 0x70, v124
	v_ashrrev_i32_e32 v13, 31, v12
	v_lshlrev_b64 v[12:13], 11, v[12:13]
	v_lshl_add_u64 v[12:13], s[40:41], 0, v[12:13]
	v_cvt_pk_bf16_f32 v14, v16, v17
	v_cvt_pk_bf16_f32 v15, v18, v19
	v_lshl_add_u64 v[16:17], v[12:13], 0, v[128:129]
	global_store_dwordx2 v[16:17], v[14:15], off
	v_add_u32_e32 v14, 0xfffff010, v142
	v_cmp_lt_u32_e32 vcc, s63, v14
	s_and_saveexec_b64 s[2:3], vcc
	s_xor_b64 s[8:9], exec, s[2:3]
	s_cbranch_execz .LBB0_1423
	s_cmpk_gt_u32 s38, 0xbff
	s_cbranch_scc1 .LBB0_1423
	v_mov_b32_e32 v143, v129
	v_lshl_add_u64 v[14:15], v[142:143], 2, s[68:69]
	v_add_co_u32_e32 v14, vcc, 0x14103000, v14
	v_mul_f32_e32 v8, 0xbfb8aa3b, v8
	s_nop 0
	v_addc_co_u32_e32 v15, vcc, 0, v15, vcc
	global_load_dwordx4 v[14:17], v[14:15], off offset:64
	v_mul_f32_e32 v9, 0xbfb8aa3b, v9
	v_exp_f32_e32 v8, v8
	v_mul_f32_e32 v10, 0xbfb8aa3b, v10
	v_exp_f32_e32 v9, v9
	v_mul_f32_e32 v11, 0xbfb8aa3b, v11
	v_exp_f32_e32 v10, v10
	v_exp_f32_e32 v11, v11
	v_add_f32_e32 v8, 1.0, v8
	v_add_f32_e32 v9, 1.0, v9
	v_add_f32_e32 v10, 1.0, v10
	v_add_f32_e32 v11, 1.0, v11
	s_waitcnt vmcnt(0)
	v_sub_f32_e32 v18, 1.0, v14
	v_sub_f32_e32 v19, 1.0, v15
	v_sub_f32_e32 v20, 1.0, v16
	v_sub_f32_e32 v21, 1.0, v17
	s_mov_b64 vcc, s[2:3]
	v_rcp_f32_e32 v22, v8
	s_nop 0
	v_mul_f32_e32 v8, v18, v22
	s_mov_b64 vcc, s[4:5]
	v_add_f32_e32 v8, v14, v8
	s_mov_b64 vcc, s[6:7]
	v_rcp_f32_e32 v14, v10
	s_nop 0
	v_mul_f32_e32 v10, v20, v14
	v_rcp_f32_e32 v18, v9
	s_nop 0
	v_mul_f32_e32 v9, v19, v18
	v_rcp_f32_e32 v14, v11
	s_nop 0
	v_mul_f32_e32 v11, v21, v14
	v_add_f32_e32 v9, v15, v9
	v_add_f32_e32 v10, v16, v10
	v_add_f32_e32 v11, v17, v11
	v_log_f32_e32 v8, v8
	v_log_f32_e32 v9, v9
	v_log_f32_e32 v10, v10
	v_log_f32_e32 v11, v11
.LBB0_1423:
	s_andn2_saveexec_b64 s[2:3], s[8:9]
	s_cbranch_execz .LBB0_1425
	v_mul_f32_e32 v14, 0xbfb8aa3b, v8
	v_mul_f32_e32 v15, 0xbfb8aa3b, v9
	v_exp_f32_e32 v14, v14
	v_exp_f32_e32 v15, v15
	v_mul_f32_e32 v16, 0xbfb8aa3b, v10
	v_mul_f32_e32 v17, 0xbfb8aa3b, v11
	v_exp_f32_e32 v16, v16
	v_pk_add_f32 v[14:15], v[14:15], 1.0 op_sel_hi:[1,0]
	v_exp_f32_e32 v17, v17
	s_nop 0
	v_pk_add_f32 v[16:17], v[16:17], 1.0 op_sel_hi:[1,0]
	v_rcp_f32_e32 v18, v14
	s_nop 0
	v_mul_f32_e32 v8, v8, v18
	v_rcp_f32_e32 v14, v15
	s_nop 0
	v_mul_f32_e32 v9, v9, v14
	v_rcp_f32_e32 v14, v16
	s_nop 0
	v_mul_f32_e32 v10, v10, v14
	v_rcp_f32_e32 v14, v17
	s_nop 0
	v_mul_f32_e32 v11, v11, v14
.LBB0_1425:
	s_or_b64 exec, exec, s[2:3]
	v_mov_b32_e32 v121, v129
	v_cvt_pk_bf16_f32 v8, v8, v9
	v_cvt_pk_bf16_f32 v9, v10, v11
	v_lshl_add_u64 v[10:11], v[12:13], 0, v[120:121]
	global_store_dwordx2 v[10:11], v[8:9], off
	v_add_u32_e32 v8, 0xfffff020, v142
	v_cmp_lt_u32_e32 vcc, s63, v8
	s_and_saveexec_b64 s[2:3], vcc
	s_xor_b64 s[8:9], exec, s[2:3]
	s_cbranch_execz .LBB0_1428
	s_cmpk_gt_u32 s38, 0xbff
	s_cbranch_scc1 .LBB0_1428
	v_mov_b32_e32 v143, v129
	v_lshl_add_u64 v[8:9], v[142:143], 2, s[68:69]
	v_add_co_u32_e32 v8, vcc, 0x14103000, v8
	v_mul_f32_e32 v4, 0xbfb8aa3b, v4
	s_nop 0
	v_addc_co_u32_e32 v9, vcc, 0, v9, vcc
	global_load_dwordx4 v[8:11], v[8:9], off offset:128
	v_mul_f32_e32 v5, 0xbfb8aa3b, v5
	v_exp_f32_e32 v4, v4
	v_mul_f32_e32 v6, 0xbfb8aa3b, v6
	v_exp_f32_e32 v5, v5
	v_mul_f32_e32 v7, 0xbfb8aa3b, v7
	v_exp_f32_e32 v6, v6
	v_exp_f32_e32 v7, v7
	v_add_f32_e32 v4, 1.0, v4
	v_add_f32_e32 v5, 1.0, v5
	v_add_f32_e32 v6, 1.0, v6
	v_add_f32_e32 v7, 1.0, v7
	s_waitcnt vmcnt(0)
	v_sub_f32_e32 v14, 1.0, v8
	v_sub_f32_e32 v15, 1.0, v9
	v_sub_f32_e32 v16, 1.0, v10
	v_sub_f32_e32 v17, 1.0, v11
	s_mov_b64 vcc, s[2:3]
	v_rcp_f32_e32 v18, v4
	s_nop 0
	v_mul_f32_e32 v4, v14, v18
	s_mov_b64 vcc, s[4:5]
	v_add_f32_e32 v4, v8, v4
	s_mov_b64 vcc, s[6:7]
	v_rcp_f32_e32 v8, v6
	s_nop 0
	v_mul_f32_e32 v6, v16, v8
	v_rcp_f32_e32 v14, v5
	s_nop 0
	v_mul_f32_e32 v5, v15, v14
	v_rcp_f32_e32 v8, v7
	s_nop 0
	v_mul_f32_e32 v7, v17, v8
	v_add_f32_e32 v5, v9, v5
	v_add_f32_e32 v6, v10, v6
	v_add_f32_e32 v7, v11, v7
	v_log_f32_e32 v4, v4
	v_log_f32_e32 v5, v5
	v_log_f32_e32 v6, v6
	v_log_f32_e32 v7, v7
.LBB0_1428:
	s_andn2_saveexec_b64 s[2:3], s[8:9]
	s_cbranch_execz .LBB0_1430
	v_mul_f32_e32 v8, 0xbfb8aa3b, v4
	v_mul_f32_e32 v9, 0xbfb8aa3b, v5
	v_exp_f32_e32 v8, v8
	v_exp_f32_e32 v9, v9
	v_mul_f32_e32 v10, 0xbfb8aa3b, v6
	v_mul_f32_e32 v11, 0xbfb8aa3b, v7
	v_exp_f32_e32 v10, v10
	v_pk_add_f32 v[8:9], v[8:9], 1.0 op_sel_hi:[1,0]
	v_exp_f32_e32 v11, v11
	s_nop 0
	v_pk_add_f32 v[10:11], v[10:11], 1.0 op_sel_hi:[1,0]
	v_rcp_f32_e32 v14, v8
	s_nop 0
	v_mul_f32_e32 v4, v4, v14
	v_rcp_f32_e32 v8, v9
	s_nop 0
	v_mul_f32_e32 v5, v5, v8
	v_rcp_f32_e32 v8, v10
	s_nop 0
	v_mul_f32_e32 v6, v6, v8
	v_rcp_f32_e32 v8, v11
	s_nop 0
	v_mul_f32_e32 v7, v7, v8
.LBB0_1430:
	s_or_b64 exec, exec, s[2:3]
	v_mov_b32_e32 v117, v129
	v_cvt_pk_bf16_f32 v4, v4, v5
	v_cvt_pk_bf16_f32 v5, v6, v7
	v_lshl_add_u64 v[6:7], v[12:13], 0, v[116:117]
	global_store_dwordx2 v[6:7], v[4:5], off
	v_add_u32_e32 v4, 0xfffff030, v142
	v_cmp_lt_u32_e32 vcc, s63, v4
	s_and_saveexec_b64 s[2:3], vcc
	s_xor_b64 s[8:9], exec, s[2:3]
	s_cbranch_execz .LBB0_1433
	s_cmpk_gt_u32 s38, 0xbff
	s_cbranch_scc1 .LBB0_1433
	v_mov_b32_e32 v143, v129
	v_lshl_add_u64 v[4:5], v[142:143], 2, s[68:69]
	v_add_co_u32_e32 v4, vcc, 0x14103000, v4
	v_mul_f32_e32 v0, 0xbfb8aa3b, v0
	s_nop 0
	v_addc_co_u32_e32 v5, vcc, 0, v5, vcc
	global_load_dwordx4 v[4:7], v[4:5], off offset:192
	v_mul_f32_e32 v1, 0xbfb8aa3b, v1
	v_exp_f32_e32 v0, v0
	v_mul_f32_e32 v2, 0xbfb8aa3b, v2
	v_exp_f32_e32 v1, v1
	v_mul_f32_e32 v3, 0xbfb8aa3b, v3
	v_exp_f32_e32 v2, v2
	v_exp_f32_e32 v3, v3
	v_add_f32_e32 v0, 1.0, v0
	v_add_f32_e32 v1, 1.0, v1
	v_add_f32_e32 v2, 1.0, v2
	v_add_f32_e32 v3, 1.0, v3
	s_waitcnt vmcnt(0)
	v_sub_f32_e32 v8, 1.0, v4
	v_sub_f32_e32 v9, 1.0, v5
	v_sub_f32_e32 v10, 1.0, v6
	v_sub_f32_e32 v11, 1.0, v7
	s_mov_b64 vcc, s[2:3]
	v_rcp_f32_e32 v14, v0
	s_nop 0
	v_mul_f32_e32 v0, v8, v14
	s_mov_b64 vcc, s[4:5]
	v_add_f32_e32 v0, v4, v0
	s_mov_b64 vcc, s[6:7]
	v_rcp_f32_e32 v4, v2
	s_nop 0
	v_mul_f32_e32 v2, v10, v4
	v_rcp_f32_e32 v8, v1
	s_nop 0
	v_mul_f32_e32 v1, v9, v8
	v_rcp_f32_e32 v4, v3
	s_nop 0
	v_mul_f32_e32 v3, v11, v4
	v_add_f32_e32 v1, v5, v1
	v_add_f32_e32 v2, v6, v2
	v_add_f32_e32 v3, v7, v3
	v_log_f32_e32 v0, v0
	v_log_f32_e32 v1, v1
	v_log_f32_e32 v2, v2
	v_log_f32_e32 v3, v3
.LBB0_1433:
	s_andn2_saveexec_b64 s[2:3], s[8:9]
	s_cbranch_execz .LBB0_1231
	v_mul_f32_e32 v4, 0xbfb8aa3b, v0
	v_mul_f32_e32 v5, 0xbfb8aa3b, v1
	v_exp_f32_e32 v4, v4
	v_exp_f32_e32 v5, v5
	v_mul_f32_e32 v6, 0xbfb8aa3b, v2
	v_mul_f32_e32 v7, 0xbfb8aa3b, v3
	v_exp_f32_e32 v6, v6
	v_pk_add_f32 v[4:5], v[4:5], 1.0 op_sel_hi:[1,0]
	v_exp_f32_e32 v7, v7
	s_nop 0
	v_pk_add_f32 v[6:7], v[6:7], 1.0 op_sel_hi:[1,0]
	v_rcp_f32_e32 v8, v4
	s_nop 0
	v_mul_f32_e32 v0, v0, v8
	v_rcp_f32_e32 v4, v5
	s_nop 0
	v_mul_f32_e32 v1, v1, v4
	v_rcp_f32_e32 v4, v6
	s_nop 0
	v_mul_f32_e32 v2, v2, v4
	v_rcp_f32_e32 v4, v7
	s_nop 0
	v_mul_f32_e32 v3, v3, v4
	s_branch .LBB0_1231

.LBB0_1617:
	v_add_u32_e32 v128, s36, v157
	v_or_b32_e32 v144, v128, v154
	v_ashrrev_i32_e32 v145, 31, v144
	v_or_b32_e32 v142, s58, v159
	v_lshlrev_b64 v[146:147], 11, v[144:145]
	v_cmp_gt_i32_e64 s[8:9], s96, v144
	v_cmp_lt_i32_e64 s[10:11], s30, v144
	v_cmp_lt_i32_e64 s[0:1], s31, v142
	s_and_saveexec_b64 s[2:3], s[0:1]
	s_xor_b64 s[2:3], exec, s[2:3]
	s_cbranch_execz .LBB0_1619
	v_mul_f32_e32 v139, 0xbfb8aa3b, v124
	v_exp_f32_e32 v148, v139
	v_mul_f32_e32 v139, 0xbfb8aa3b, v125
	v_exp_f32_e32 v149, v139
	s_nop 0
	v_pk_add_f32 v[148:149], v[148:149], 1.0 op_sel_hi:[1,0]
	s_nop 0
	s_nop 0
	v_rcp_f32_e32 v139, v149
	s_nop 0
	v_mul_f32_e32 v125, v125, v139
	s_nop 0
	v_rcp_f32_e32 v139, v148
	s_nop 0
	v_mul_f32_e32 v124, v124, v139
	v_cvt_pk_bf16_f32 v124, v124, v125
	v_mul_f32_e32 v125, 0xbfb8aa3b, v126
	v_exp_f32_e32 v148, v125
	v_mul_f32_e32 v125, 0xbfb8aa3b, v127
	v_exp_f32_e32 v149, v125
	s_nop 0
	v_pk_add_f32 v[148:149], v[148:149], 1.0 op_sel_hi:[1,0]
	s_nop 0
	s_nop 0
	v_rcp_f32_e32 v125, v149
	s_nop 0
	v_mul_f32_e32 v125, v127, v125
	s_nop 0
	v_rcp_f32_e32 v127, v148
	s_nop 0
	v_mul_f32_e32 v126, v126, v127
	v_cvt_pk_bf16_f32 v125, v126, v125
	v_lshl_add_u64 v[126:127], s[68:69], 0, v[146:147]
	v_mov_b32_e32 v143, v129
	v_lshl_add_u64 v[126:127], v[142:143], 1, v[126:127]
	v_add_co_u32_e32 v126, vcc, 0x9ffe000, v126
	s_nop 1
	v_addc_co_u32_e32 v127, vcc, 0, v127, vcc
	global_store_dwordx2 v[126:127], v[124:125], off offset:2048

.LBB0_1631:
	s_or_b64 exec, exec, s[2:3]
	v_mul_hi_u32_u24_e32 v125, 0xa00, v139
	v_mul_u32_u24_e32 v124, 0xa00, v139
	v_or_b32_e32 v139, 16, v142
	v_cmp_lt_i32_e64 s[6:7], s31, v139
	s_and_saveexec_b64 s[2:3], s[6:7]
	s_xor_b64 s[2:3], exec, s[2:3]
	s_cbranch_execz .LBB0_1633
	v_mul_f32_e32 v126, 0xbfb8aa3b, v120
	v_mul_f32_e32 v127, 0xbfb8aa3b, v121
	v_exp_f32_e32 v126, v126
	v_exp_f32_e32 v127, v127
	s_nop 0
	v_pk_add_f32 v[126:127], v[126:127], 1.0 op_sel_hi:[1,0]
	s_nop 0
	s_nop 0
	v_rcp_f32_e32 v128, v127
	s_nop 0
	v_mul_f32_e32 v121, v121, v128
	s_nop 0
	v_rcp_f32_e32 v127, v126
	s_nop 0
	v_mul_f32_e32 v120, v120, v127
	v_cvt_pk_bf16_f32 v120, v120, v121
	v_mul_f32_e32 v121, 0xbfb8aa3b, v122
	v_exp_f32_e32 v126, v121
	v_mul_f32_e32 v121, 0xbfb8aa3b, v123
	v_exp_f32_e32 v127, v121
	s_nop 0
	v_pk_add_f32 v[126:127], v[126:127], 1.0 op_sel_hi:[1,0]
	s_nop 0
	s_nop 0
	v_rcp_f32_e32 v121, v127
	s_nop 0
	v_mul_f32_e32 v121, v123, v121
	s_nop 0
	v_rcp_f32_e32 v123, v126
	s_nop 0
	v_mul_f32_e32 v122, v122, v123
	v_cvt_pk_bf16_f32 v121, v122, v121
	v_lshl_add_u64 v[122:123], s[68:69], 0, v[146:147]
	v_mov_b32_e32 v143, v129
	v_lshl_add_u64 v[122:123], v[142:143], 1, v[122:123]
	v_add_co_u32_e32 v122, vcc, 0x9ffe000, v122
	s_nop 1
	v_addc_co_u32_e32 v123, vcc, 0, v123, vcc
	global_store_dwordx2 v[122:123], v[120:121], off offset:2080

.LBB0_1645:
	s_or_b64 exec, exec, s[2:3]
	v_or_b32_e32 v122, 32, v142
	v_cmp_lt_i32_e64 s[4:5], s31, v122
	s_and_saveexec_b64 s[2:3], s[4:5]
	s_xor_b64 s[2:3], exec, s[2:3]
	s_cbranch_execz .LBB0_1647
	v_mul_f32_e32 v120, 0xbfb8aa3b, v116
	v_mul_f32_e32 v121, 0xbfb8aa3b, v117
	v_exp_f32_e32 v120, v120
	v_exp_f32_e32 v121, v121
	s_nop 0
	v_pk_add_f32 v[120:121], v[120:121], 1.0 op_sel_hi:[1,0]
	s_nop 0
	s_nop 0
	v_rcp_f32_e32 v123, v121
	s_nop 0
	v_mul_f32_e32 v117, v117, v123
	v_mov_b32_e32 v143, v129
	v_rcp_f32_e32 v121, v120
	s_nop 0
	v_mul_f32_e32 v116, v116, v121
	v_cvt_pk_bf16_f32 v116, v116, v117
	v_mul_f32_e32 v117, 0xbfb8aa3b, v118
	v_exp_f32_e32 v120, v117
	v_mul_f32_e32 v117, 0xbfb8aa3b, v119
	v_exp_f32_e32 v121, v117
	s_nop 0
	v_pk_add_f32 v[120:121], v[120:121], 1.0 op_sel_hi:[1,0]
	s_nop 0
	s_nop 0
	v_rcp_f32_e32 v117, v121
	s_nop 0
	v_mul_f32_e32 v117, v119, v117
	s_nop 0
	v_rcp_f32_e32 v119, v120
	s_nop 0
	v_mul_f32_e32 v118, v118, v119
	v_cvt_pk_bf16_f32 v117, v118, v117
	v_lshl_add_u64 v[118:119], s[68:69], 0, v[146:147]
	v_lshl_add_u64 v[118:119], v[142:143], 1, v[118:119]
	v_add_co_u32_e32 v118, vcc, 0x9ffe000, v118
	s_nop 1
	v_addc_co_u32_e32 v119, vcc, 0, v119, vcc
	global_store_dwordx2 v[118:119], v[116:117], off offset:2112

.LBB0_1659:
	s_or_b64 exec, exec, s[2:3]
	v_or_b32_e32 v120, 48, v142
	v_cmp_lt_i32_e64 s[2:3], s31, v120
	s_and_saveexec_b64 s[72:73], s[2:3]
	s_xor_b64 s[72:73], exec, s[72:73]
	s_cbranch_execz .LBB0_1661
	v_mul_f32_e32 v116, 0xbfb8aa3b, v112
	v_mul_f32_e32 v117, 0xbfb8aa3b, v113
	v_exp_f32_e32 v116, v116
	v_exp_f32_e32 v117, v117
	v_mov_b32_e32 v143, v129
	v_pk_add_f32 v[116:117], v[116:117], 1.0 op_sel_hi:[1,0]
	s_nop 0
	s_nop 0
	v_rcp_f32_e32 v118, v117
	s_nop 0
	v_mul_f32_e32 v113, v113, v118
	s_nop 0
	v_rcp_f32_e32 v117, v116
	s_nop 0
	v_mul_f32_e32 v112, v112, v117
	v_cvt_pk_bf16_f32 v112, v112, v113
	v_mul_f32_e32 v113, 0xbfb8aa3b, v114
	v_exp_f32_e32 v116, v113
	v_mul_f32_e32 v113, 0xbfb8aa3b, v115
	v_exp_f32_e32 v117, v113
	s_nop 0
	v_pk_add_f32 v[116:117], v[116:117], 1.0 op_sel_hi:[1,0]
	s_nop 0
	s_nop 0
	v_rcp_f32_e32 v113, v117
	s_nop 0
	v_mul_f32_e32 v113, v115, v113
	s_nop 0
	v_rcp_f32_e32 v115, v116
	s_nop 0
	v_mul_f32_e32 v114, v114, v115
	v_cvt_pk_bf16_f32 v113, v114, v113
	v_lshl_add_u64 v[114:115], s[68:69], 0, v[146:147]
	v_lshl_add_u64 v[114:115], v[142:143], 1, v[114:115]
	v_add_co_u32_e32 v114, vcc, 0x9ffe000, v114
	s_nop 1
	v_addc_co_u32_e32 v115, vcc, 0, v115, vcc
	global_store_dwordx2 v[114:115], v[112:113], off offset:2144

.LBB0_1673:
	s_or_b64 exec, exec, s[72:73]
	v_or_b32_e32 v114, 16, v144
	v_ashrrev_i32_e32 v115, 31, v114
	v_lshlrev_b64 v[112:113], 11, v[114:115]
	v_cmp_gt_i32_e64 s[8:9], s96, v114
	v_cmp_lt_i32_e64 s[10:11], s30, v114
	s_and_saveexec_b64 s[72:73], s[0:1]
	s_xor_b64 s[72:73], exec, s[72:73]
	s_cbranch_execz .LBB0_1675
	v_mul_f32_e32 v114, 0xbfb8aa3b, v108
	v_mul_f32_e32 v115, 0xbfb8aa3b, v109
	v_exp_f32_e32 v114, v114
	v_exp_f32_e32 v115, v115
	v_mov_b32_e32 v143, v129
	v_pk_add_f32 v[114:115], v[114:115], 1.0 op_sel_hi:[1,0]
	s_nop 0
	s_nop 0
	v_rcp_f32_e32 v116, v115
	s_nop 0
	v_mul_f32_e32 v109, v109, v116
	s_nop 0
	v_rcp_f32_e32 v115, v114
	s_nop 0
	v_mul_f32_e32 v108, v108, v115
	v_cvt_pk_bf16_f32 v108, v108, v109
	v_mul_f32_e32 v109, 0xbfb8aa3b, v110
	v_exp_f32_e32 v114, v109
	v_mul_f32_e32 v109, 0xbfb8aa3b, v111
	v_exp_f32_e32 v115, v109
	s_nop 0
	v_pk_add_f32 v[114:115], v[114:115], 1.0 op_sel_hi:[1,0]
	s_nop 0
	s_nop 0
	v_rcp_f32_e32 v109, v115
	s_nop 0
	v_mul_f32_e32 v109, v111, v109
	s_nop 0
	v_rcp_f32_e32 v111, v114
	s_nop 0
	v_mul_f32_e32 v110, v110, v111
	v_cvt_pk_bf16_f32 v109, v110, v109
	v_lshl_add_u64 v[110:111], s[68:69], 0, v[112:113]
	v_lshl_add_u64 v[110:111], v[142:143], 1, v[110:111]
	v_add_co_u32_e32 v110, vcc, 0x9ffe000, v110
	s_nop 1
	v_addc_co_u32_e32 v111, vcc, 0, v111, vcc
	global_store_dwordx2 v[110:111], v[108:109], off offset:2048

.LBB0_1729:
	s_or_b64 exec, exec, s[72:73]
	v_or_b32_e32 v98, 32, v144
	v_ashrrev_i32_e32 v99, 31, v98
	v_lshlrev_b64 v[96:97], 11, v[98:99]
	v_cmp_gt_i32_e64 s[8:9], s96, v98
	v_cmp_lt_i32_e64 s[10:11], s30, v98
	s_and_saveexec_b64 s[72:73], s[0:1]
	s_xor_b64 s[72:73], exec, s[72:73]
	s_cbranch_execz .LBB0_1731
	v_mul_f32_e32 v98, 0xbfb8aa3b, v92
	v_mul_f32_e32 v99, 0xbfb8aa3b, v93
	v_exp_f32_e32 v98, v98
	v_exp_f32_e32 v99, v99
	v_mov_b32_e32 v143, v129
	v_pk_add_f32 v[98:99], v[98:99], 1.0 op_sel_hi:[1,0]
	s_nop 0
	s_nop 0
	v_rcp_f32_e32 v100, v99
	s_nop 0
	v_mul_f32_e32 v93, v93, v100
	s_nop 0
	v_rcp_f32_e32 v99, v98
	s_nop 0
	v_mul_f32_e32 v92, v92, v99
	v_cvt_pk_bf16_f32 v92, v92, v93
	v_mul_f32_e32 v93, 0xbfb8aa3b, v94
	v_exp_f32_e32 v98, v93
	v_mul_f32_e32 v93, 0xbfb8aa3b, v95
	v_exp_f32_e32 v99, v93
	s_nop 0
	v_pk_add_f32 v[98:99], v[98:99], 1.0 op_sel_hi:[1,0]
	s_nop 0
	s_nop 0
	v_rcp_f32_e32 v93, v99
	s_nop 0
	v_mul_f32_e32 v93, v95, v93
	s_nop 0
	v_rcp_f32_e32 v95, v98
	s_nop 0
	v_mul_f32_e32 v94, v94, v95
	v_cvt_pk_bf16_f32 v93, v94, v93
	v_lshl_add_u64 v[94:95], s[68:69], 0, v[96:97]
	v_lshl_add_u64 v[94:95], v[142:143], 1, v[94:95]
	v_add_co_u32_e32 v94, vcc, 0x9ffe000, v94
	s_nop 1
	v_addc_co_u32_e32 v95, vcc, 0, v95, vcc
	global_store_dwordx2 v[94:95], v[92:93], off offset:2048

.LBB0_1785:
	s_or_b64 exec, exec, s[72:73]
	v_or_b32_e32 v82, 48, v144
	v_ashrrev_i32_e32 v83, 31, v82
	v_lshlrev_b64 v[80:81], 11, v[82:83]
	v_cmp_gt_i32_e64 s[8:9], s96, v82
	v_cmp_lt_i32_e64 s[10:11], s30, v82
	s_and_saveexec_b64 s[72:73], s[0:1]
	s_xor_b64 s[72:73], exec, s[72:73]
	s_cbranch_execz .LBB0_1787
	v_mul_f32_e32 v82, 0xbfb8aa3b, v76
	v_mul_f32_e32 v83, 0xbfb8aa3b, v77
	v_exp_f32_e32 v82, v82
	v_exp_f32_e32 v83, v83
	v_mov_b32_e32 v143, v129
	v_pk_add_f32 v[82:83], v[82:83], 1.0 op_sel_hi:[1,0]
	s_nop 0
	s_nop 0
	v_rcp_f32_e32 v84, v83
	s_nop 0
	v_mul_f32_e32 v77, v77, v84
	s_nop 0
	v_rcp_f32_e32 v83, v82
	s_nop 0
	v_mul_f32_e32 v76, v76, v83
	v_cvt_pk_bf16_f32 v76, v76, v77
	v_mul_f32_e32 v77, 0xbfb8aa3b, v78
	v_exp_f32_e32 v82, v77
	v_mul_f32_e32 v77, 0xbfb8aa3b, v79
	v_exp_f32_e32 v83, v77
	s_nop 0
	v_pk_add_f32 v[82:83], v[82:83], 1.0 op_sel_hi:[1,0]
	s_nop 0
	s_nop 0
	v_rcp_f32_e32 v77, v83
	s_nop 0
	v_mul_f32_e32 v77, v79, v77
	s_nop 0
	v_rcp_f32_e32 v79, v82
	s_nop 0
	v_mul_f32_e32 v78, v78, v79
	v_cvt_pk_bf16_f32 v77, v78, v77
	v_lshl_add_u64 v[78:79], s[68:69], 0, v[80:81]
	v_lshl_add_u64 v[78:79], v[142:143], 1, v[78:79]
	v_add_co_u32_e32 v78, vcc, 0x9ffe000, v78
	s_nop 1
	v_addc_co_u32_e32 v79, vcc, 0, v79, vcc
	global_store_dwordx2 v[78:79], v[76:77], off offset:2048

.LBB0_1841:
	s_or_b64 exec, exec, s[72:73]
	v_or_b32_e32 v66, 64, v144
	v_ashrrev_i32_e32 v67, 31, v66
	v_lshlrev_b64 v[64:65], 11, v[66:67]
	v_cmp_gt_i32_e64 s[8:9], s96, v66
	v_cmp_lt_i32_e64 s[10:11], s30, v66
	s_and_saveexec_b64 s[72:73], s[0:1]
	s_xor_b64 s[72:73], exec, s[72:73]
	s_cbranch_execz .LBB0_1843
	v_mul_f32_e32 v66, 0xbfb8aa3b, v60
	v_mul_f32_e32 v67, 0xbfb8aa3b, v61
	v_exp_f32_e32 v66, v66
	v_exp_f32_e32 v67, v67
	v_mov_b32_e32 v143, v129
	v_pk_add_f32 v[66:67], v[66:67], 1.0 op_sel_hi:[1,0]
	s_nop 0
	s_nop 0
	v_rcp_f32_e32 v68, v67
	s_nop 0
	v_mul_f32_e32 v61, v61, v68
	s_nop 0
	v_rcp_f32_e32 v67, v66
	s_nop 0
	v_mul_f32_e32 v60, v60, v67
	v_cvt_pk_bf16_f32 v60, v60, v61
	v_mul_f32_e32 v61, 0xbfb8aa3b, v62
	v_exp_f32_e32 v66, v61
	v_mul_f32_e32 v61, 0xbfb8aa3b, v63
	v_exp_f32_e32 v67, v61
	s_nop 0
	v_pk_add_f32 v[66:67], v[66:67], 1.0 op_sel_hi:[1,0]
	s_nop 0
	s_nop 0
	v_rcp_f32_e32 v61, v67
	s_nop 0
	v_mul_f32_e32 v61, v63, v61
	s_nop 0
	v_rcp_f32_e32 v63, v66
	s_nop 0
	v_mul_f32_e32 v62, v62, v63
	v_cvt_pk_bf16_f32 v61, v62, v61
	v_lshl_add_u64 v[62:63], s[68:69], 0, v[64:65]
	v_lshl_add_u64 v[62:63], v[142:143], 1, v[62:63]
	v_add_co_u32_e32 v62, vcc, 0x9ffe000, v62
	s_nop 1
	v_addc_co_u32_e32 v63, vcc, 0, v63, vcc
	global_store_dwordx2 v[62:63], v[60:61], off offset:2048

.LBB0_1897:
	s_or_b64 exec, exec, s[72:73]
	v_or_b32_e32 v50, 0x50, v144
	v_ashrrev_i32_e32 v51, 31, v50
	v_lshlrev_b64 v[48:49], 11, v[50:51]
	v_cmp_gt_i32_e64 s[8:9], s96, v50
	v_cmp_lt_i32_e64 s[10:11], s30, v50
	s_and_saveexec_b64 s[72:73], s[0:1]
	s_xor_b64 s[72:73], exec, s[72:73]
	s_cbranch_execz .LBB0_1899
	v_mul_f32_e32 v50, 0xbfb8aa3b, v44
	v_mul_f32_e32 v51, 0xbfb8aa3b, v45
	v_exp_f32_e32 v50, v50
	v_exp_f32_e32 v51, v51
	v_mov_b32_e32 v143, v129
	v_pk_add_f32 v[50:51], v[50:51], 1.0 op_sel_hi:[1,0]
	s_nop 0
	s_nop 0
	v_rcp_f32_e32 v52, v51
	s_nop 0
	v_mul_f32_e32 v45, v45, v52
	s_nop 0
	v_rcp_f32_e32 v51, v50
	s_nop 0
	v_mul_f32_e32 v44, v44, v51
	v_cvt_pk_bf16_f32 v44, v44, v45
	v_mul_f32_e32 v45, 0xbfb8aa3b, v46
	v_exp_f32_e32 v50, v45
	v_mul_f32_e32 v45, 0xbfb8aa3b, v47
	v_exp_f32_e32 v51, v45
	s_nop 0
	v_pk_add_f32 v[50:51], v[50:51], 1.0 op_sel_hi:[1,0]
	s_nop 0
	s_nop 0
	v_rcp_f32_e32 v45, v51
	s_nop 0
	v_mul_f32_e32 v45, v47, v45
	s_nop 0
	v_rcp_f32_e32 v47, v50
	s_nop 0
	v_mul_f32_e32 v46, v46, v47
	v_cvt_pk_bf16_f32 v45, v46, v45
	v_lshl_add_u64 v[46:47], s[68:69], 0, v[48:49]
	v_lshl_add_u64 v[46:47], v[142:143], 1, v[46:47]
	v_add_co_u32_e32 v46, vcc, 0x9ffe000, v46
	s_nop 1
	v_addc_co_u32_e32 v47, vcc, 0, v47, vcc
	global_store_dwordx2 v[46:47], v[44:45], off offset:2048

.LBB0_1953:
	s_or_b64 exec, exec, s[72:73]
	v_or_b32_e32 v34, 0x60, v144
	v_ashrrev_i32_e32 v35, 31, v34
	v_lshlrev_b64 v[32:33], 11, v[34:35]
	v_cmp_gt_i32_e64 s[8:9], s96, v34
	v_cmp_lt_i32_e64 s[10:11], s30, v34
	s_and_saveexec_b64 s[72:73], s[0:1]
	s_xor_b64 s[72:73], exec, s[72:73]
	s_cbranch_execz .LBB0_1955
	v_mul_f32_e32 v34, 0xbfb8aa3b, v28
	v_mul_f32_e32 v35, 0xbfb8aa3b, v29
	v_exp_f32_e32 v34, v34
	v_exp_f32_e32 v35, v35
	v_mov_b32_e32 v143, v129
	v_pk_add_f32 v[34:35], v[34:35], 1.0 op_sel_hi:[1,0]
	s_nop 0
	s_nop 0
	v_rcp_f32_e32 v36, v35
	s_nop 0
	v_mul_f32_e32 v29, v29, v36
	s_nop 0
	v_rcp_f32_e32 v35, v34
	s_nop 0
	v_mul_f32_e32 v28, v28, v35
	v_cvt_pk_bf16_f32 v28, v28, v29
	v_mul_f32_e32 v29, 0xbfb8aa3b, v30
	v_exp_f32_e32 v34, v29
	v_mul_f32_e32 v29, 0xbfb8aa3b, v31
	v_exp_f32_e32 v35, v29
	s_nop 0
	v_pk_add_f32 v[34:35], v[34:35], 1.0 op_sel_hi:[1,0]
	s_nop 0
	s_nop 0
	v_rcp_f32_e32 v29, v35
	s_nop 0
	v_mul_f32_e32 v29, v31, v29
	s_nop 0
	v_rcp_f32_e32 v31, v34
	s_nop 0
	v_mul_f32_e32 v30, v30, v31
	v_cvt_pk_bf16_f32 v29, v30, v29
	v_lshl_add_u64 v[30:31], s[68:69], 0, v[32:33]
	v_lshl_add_u64 v[30:31], v[142:143], 1, v[30:31]
	v_add_co_u32_e32 v30, vcc, 0x9ffe000, v30
	s_nop 1
	v_addc_co_u32_e32 v31, vcc, 0, v31, vcc
	global_store_dwordx2 v[30:31], v[28:29], off offset:2048

.LBB0_2009:
	s_or_b64 exec, exec, s[72:73]
	v_or_b32_e32 v18, 0x70, v144
	v_ashrrev_i32_e32 v19, 31, v18
	v_lshlrev_b64 v[16:17], 11, v[18:19]
	v_cmp_gt_i32_e64 s[8:9], s96, v18
	v_cmp_lt_i32_e64 s[10:11], s30, v18
	s_and_saveexec_b64 s[72:73], s[0:1]
	s_xor_b64 s[0:1], exec, s[72:73]
	s_cbranch_execz .LBB0_2011
	v_mul_f32_e32 v18, 0xbfb8aa3b, v12
	v_mul_f32_e32 v19, 0xbfb8aa3b, v13
	v_exp_f32_e32 v18, v18
	v_exp_f32_e32 v19, v19
	v_mov_b32_e32 v143, v129
	v_pk_add_f32 v[18:19], v[18:19], 1.0 op_sel_hi:[1,0]
	s_nop 0
	s_nop 0
	v_rcp_f32_e32 v20, v19
	s_nop 0
	v_mul_f32_e32 v13, v13, v20
	s_nop 0
	v_rcp_f32_e32 v19, v18
	s_nop 0
	v_mul_f32_e32 v12, v12, v19
	v_cvt_pk_bf16_f32 v12, v12, v13
	v_mul_f32_e32 v13, 0xbfb8aa3b, v14
	v_exp_f32_e32 v18, v13
	v_mul_f32_e32 v13, 0xbfb8aa3b, v15
	v_exp_f32_e32 v19, v13
	s_nop 0
	v_pk_add_f32 v[18:19], v[18:19], 1.0 op_sel_hi:[1,0]
	s_nop 0
	s_nop 0
	v_rcp_f32_e32 v13, v19
	s_nop 0
	v_mul_f32_e32 v13, v15, v13
	s_nop 0
	v_rcp_f32_e32 v15, v18
	s_nop 0
	v_mul_f32_e32 v14, v14, v15
	v_cvt_pk_bf16_f32 v13, v14, v13
	v_lshl_add_u64 v[14:15], s[68:69], 0, v[16:17]
	v_lshl_add_u64 v[14:15], v[142:143], 1, v[14:15]
	v_add_co_u32_e32 v14, vcc, 0x9ffe000, v14
	s_nop 1
	v_addc_co_u32_e32 v15, vcc, 0, v15, vcc
	global_store_dwordx2 v[14:15], v[12:13], off offset:2048

.LBB0_2029:
	v_mul_f32_e32 v12, 0xbfb8aa3b, v8
	v_mul_f32_e32 v13, 0xbfb8aa3b, v9
	v_exp_f32_e32 v12, v12
	v_exp_f32_e32 v13, v13
	v_mov_b32_e32 v143, v129
	v_pk_add_f32 v[12:13], v[12:13], 1.0 op_sel_hi:[1,0]
	s_nop 0
	s_nop 0
	v_rcp_f32_e32 v14, v13
	s_nop 0
	v_mul_f32_e32 v9, v9, v14
	s_nop 0
	v_rcp_f32_e32 v13, v12
	s_nop 0
	v_mul_f32_e32 v8, v8, v13
	v_cvt_pk_bf16_f32 v8, v8, v9
	v_mul_f32_e32 v9, 0xbfb8aa3b, v10
	v_exp_f32_e32 v12, v9
	v_mul_f32_e32 v9, 0xbfb8aa3b, v11
	v_exp_f32_e32 v13, v9
	s_nop 0
	v_pk_add_f32 v[12:13], v[12:13], 1.0 op_sel_hi:[1,0]
	s_nop 0
	s_nop 0
	v_rcp_f32_e32 v9, v13
	s_nop 0
	v_mul_f32_e32 v9, v11, v9
	s_nop 0
	v_rcp_f32_e32 v11, v12
	s_nop 0
	v_mul_f32_e32 v10, v10, v11
	v_cvt_pk_bf16_f32 v9, v10, v9
	v_lshl_add_u64 v[10:11], s[68:69], 0, v[16:17]
	v_lshl_add_u64 v[10:11], v[142:143], 1, v[10:11]
	v_add_co_u32_e32 v10, vcc, 0x9ffe000, v10
	s_nop 1
	v_addc_co_u32_e32 v11, vcc, 0, v11, vcc
	global_store_dwordx2 v[10:11], v[8:9], off offset:2080
	s_andn2_saveexec_b64 s[0:1], s[0:1]
	s_cbranch_execz .LBB0_2014

.LBB0_2041:
	v_mul_f32_e32 v8, 0xbfb8aa3b, v4
	v_mul_f32_e32 v9, 0xbfb8aa3b, v5
	v_exp_f32_e32 v8, v8
	v_exp_f32_e32 v9, v9
	v_mov_b32_e32 v143, v129
	v_pk_add_f32 v[8:9], v[8:9], 1.0 op_sel_hi:[1,0]
	s_nop 0
	s_nop 0
	v_rcp_f32_e32 v10, v9
	s_nop 0
	v_mul_f32_e32 v5, v5, v10
	s_nop 0
	v_rcp_f32_e32 v9, v8
	s_nop 0
	v_mul_f32_e32 v4, v4, v9
	v_cvt_pk_bf16_f32 v4, v4, v5
	v_mul_f32_e32 v5, 0xbfb8aa3b, v6
	v_exp_f32_e32 v8, v5
	v_mul_f32_e32 v5, 0xbfb8aa3b, v7
	v_exp_f32_e32 v9, v5
	s_nop 0
	v_pk_add_f32 v[8:9], v[8:9], 1.0 op_sel_hi:[1,0]
	s_nop 0
	s_nop 0
	v_rcp_f32_e32 v5, v9
	s_nop 0
	v_mul_f32_e32 v5, v7, v5
	s_nop 0
	v_rcp_f32_e32 v7, v8
	s_nop 0
	v_mul_f32_e32 v6, v6, v7
	v_cvt_pk_bf16_f32 v5, v6, v5
	v_lshl_add_u64 v[6:7], s[68:69], 0, v[16:17]
	v_lshl_add_u64 v[6:7], v[142:143], 1, v[6:7]
	v_add_co_u32_e32 v6, vcc, 0x9ffe000, v6
	s_nop 1
	v_addc_co_u32_e32 v7, vcc, 0, v7, vcc
	global_store_dwordx2 v[6:7], v[4:5], off offset:2112
	s_andn2_saveexec_b64 s[0:1], s[0:1]
	s_cbranch_execz .LBB0_2016

.LBB0_2053:
	v_mul_f32_e32 v4, 0xbfb8aa3b, v0
	v_mul_f32_e32 v5, 0xbfb8aa3b, v1
	v_exp_f32_e32 v4, v4
	v_exp_f32_e32 v5, v5
	v_mov_b32_e32 v143, v129
	v_pk_add_f32 v[4:5], v[4:5], 1.0 op_sel_hi:[1,0]
	s_nop 0
	s_nop 0
	v_rcp_f32_e32 v6, v5
	s_nop 0
	v_mul_f32_e32 v1, v1, v6
	s_nop 0
	v_rcp_f32_e32 v5, v4
	s_nop 0
	v_mul_f32_e32 v0, v0, v5
	v_cvt_pk_bf16_f32 v0, v0, v1
	v_mul_f32_e32 v1, 0xbfb8aa3b, v2
	v_exp_f32_e32 v4, v1
	v_mul_f32_e32 v1, 0xbfb8aa3b, v3
	v_exp_f32_e32 v5, v1
	s_nop 0
	v_pk_add_f32 v[4:5], v[4:5], 1.0 op_sel_hi:[1,0]
	s_nop 0
	s_nop 0
	v_rcp_f32_e32 v1, v5
	s_nop 0
	v_mul_f32_e32 v1, v3, v1
	s_nop 0
	v_rcp_f32_e32 v3, v4
	s_nop 0
	v_mul_f32_e32 v2, v2, v3
	v_cvt_pk_bf16_f32 v1, v2, v1
	v_lshl_add_u64 v[2:3], s[68:69], 0, v[16:17]
	v_lshl_add_u64 v[2:3], v[142:143], 1, v[2:3]
	v_add_co_u32_e32 v2, vcc, 0x9ffe000, v2
	s_nop 1
	v_addc_co_u32_e32 v3, vcc, 0, v3, vcc
	global_store_dwordx2 v[2:3], v[0:1], off offset:2144
	s_andn2_saveexec_b64 s[0:1], s[0:1]
	s_cbranch_execz .LBB0_2065

.LBB0_2224:
	ds_bpermute_b32 v0, v187, v175
	ds_bpermute_b32 v1, v187, v174
	s_lshl_b32 s2, s15, 1
	v_mov_b32_e32 v149, v145
	s_add_i32 s28, s28, s78
	s_waitcnt lgkmcnt(1)
	v_add_f32_e32 v0, v175, v0
	ds_bpermute_b32 v2, v186, v0
	s_waitcnt lgkmcnt(1)
	v_add_f32_e32 v1, v174, v1
	ds_bpermute_b32 v3, v186, v1
	s_cmpk_gt_i32 s28, 0x5ff
	s_waitcnt lgkmcnt(1)
	v_add_f32_e32 v0, v0, v2
	s_waitcnt lgkmcnt(0)
	v_add_f32_e32 v1, v1, v3
	v_rcp_f32_e32 v10, v0
	v_rcp_f32_e32 v0, v1
	s_nop 0
	v_mul_f32_e32 v12, v189, v0
	v_pk_mul_f32 v[2:3], v[78:79], v[12:13] op_sel_hi:[1,0]
	v_pk_mul_f32 v[6:7], v[70:71], v[12:13] op_sel_hi:[1,0]
	v_pk_fma_f32 v[4:5], v[74:75], v[10:11], v[2:3] op_sel_hi:[1,0,1] neg_lo:[0,0,1] neg_hi:[0,0,1]
	v_lshl_add_u64 v[2:3], s[4:5], 0, v[152:153]
	v_lshl_add_u64 v[2:3], v[2:3], 0, s[2:3]
	v_lshl_add_u64 v[2:3], v[2:3], 0, v[148:149]
	global_load_dwordx2 v[74:75], v[2:3], off
	v_pk_fma_f32 v[66:67], v[66:67], v[10:11], v[6:7] op_sel_hi:[1,0,1] neg_lo:[0,0,1] neg_hi:[0,0,1]
	global_load_dwordx4 v[6:9], v[146:147], off offset:512
	v_pk_mul_f32 v[68:69], v[68:69], v[12:13] op_sel_hi:[1,0]
	v_pk_mul_f32 v[0:1], v[76:77], v[12:13] op_sel_hi:[1,0]
	v_pk_fma_f32 v[64:65], v[64:65], v[10:11], v[68:69] op_sel_hi:[1,0,1] neg_lo:[0,0,1] neg_hi:[0,0,1]
	v_pk_mul_f32 v[62:63], v[62:63], v[12:13] op_sel_hi:[1,0]
	v_pk_mul_f32 v[68:69], v[64:65], v[64:65]
	v_pk_mul_f32 v[60:61], v[60:61], v[12:13] op_sel_hi:[1,0]
	v_pk_mul_f32 v[54:55], v[54:55], v[12:13] op_sel_hi:[1,0]
	v_pk_mul_f32 v[52:53], v[52:53], v[12:13] op_sel_hi:[1,0]
	v_pk_mul_f32 v[46:47], v[46:47], v[12:13] op_sel_hi:[1,0]
	v_pk_mul_f32 v[44:45], v[44:45], v[12:13] op_sel_hi:[1,0]
	v_pk_mul_f32 v[38:39], v[38:39], v[12:13] op_sel_hi:[1,0]
	v_pk_mul_f32 v[36:37], v[36:37], v[12:13] op_sel_hi:[1,0]
	v_pk_mul_f32 v[30:31], v[30:31], v[12:13] op_sel_hi:[1,0]
	v_pk_mul_f32 v[28:29], v[28:29], v[12:13] op_sel_hi:[1,0]
	v_pk_mul_f32 v[22:23], v[22:23], v[12:13] op_sel_hi:[1,0]
	v_pk_mul_f32 v[12:13], v[20:21], v[12:13] op_sel_hi:[1,0]
	v_pk_fma_f32 v[0:1], v[72:73], v[10:11], v[0:1] op_sel_hi:[1,0,1] neg_lo:[0,0,1] neg_hi:[0,0,1]
	v_pk_mul_f32 v[70:71], v[66:67], v[66:67]
	v_pk_fma_f32 v[58:59], v[58:59], v[10:11], v[62:63] op_sel_hi:[1,0,1] neg_lo:[0,0,1] neg_hi:[0,0,1]
	v_pk_fma_f32 v[56:57], v[56:57], v[10:11], v[60:61] op_sel_hi:[1,0,1] neg_lo:[0,0,1] neg_hi:[0,0,1]
	v_pk_fma_f32 v[50:51], v[50:51], v[10:11], v[54:55] op_sel_hi:[1,0,1] neg_lo:[0,0,1] neg_hi:[0,0,1]
	v_pk_fma_f32 v[48:49], v[48:49], v[10:11], v[52:53] op_sel_hi:[1,0,1] neg_lo:[0,0,1] neg_hi:[0,0,1]
	v_pk_fma_f32 v[42:43], v[42:43], v[10:11], v[46:47] op_sel_hi:[1,0,1] neg_lo:[0,0,1] neg_hi:[0,0,1]
	v_pk_fma_f32 v[40:41], v[40:41], v[10:11], v[44:45] op_sel_hi:[1,0,1] neg_lo:[0,0,1] neg_hi:[0,0,1]
	v_pk_fma_f32 v[34:35], v[34:35], v[10:11], v[38:39] op_sel_hi:[1,0,1] neg_lo:[0,0,1] neg_hi:[0,0,1]
	v_pk_fma_f32 v[32:33], v[32:33], v[10:11], v[36:37] op_sel_hi:[1,0,1] neg_lo:[0,0,1] neg_hi:[0,0,1]
	v_pk_fma_f32 v[26:27], v[26:27], v[10:11], v[30:31] op_sel_hi:[1,0,1] neg_lo:[0,0,1] neg_hi:[0,0,1]
	v_pk_fma_f32 v[24:25], v[24:25], v[10:11], v[28:29] op_sel_hi:[1,0,1] neg_lo:[0,0,1] neg_hi:[0,0,1]
	v_pk_fma_f32 v[18:19], v[18:19], v[10:11], v[22:23] op_sel_hi:[1,0,1] neg_lo:[0,0,1] neg_hi:[0,0,1]
	v_pk_fma_f32 v[10:11], v[16:17], v[10:11], v[12:13] op_sel_hi:[1,0,1] neg_lo:[0,0,1] neg_hi:[0,0,1]
	v_add_f32_e32 v16, v68, v69
	v_add_f32_e32 v16, v70, v16
	v_pk_mul_f32 v[60:61], v[56:57], v[56:57]
	v_add_f32_e32 v16, v71, v16
	v_add_f32_e32 v16, v60, v16
	v_pk_mul_f32 v[62:63], v[58:59], v[58:59]
	v_add_f32_e32 v16, v61, v16
	v_add_f32_e32 v16, v62, v16
	v_pk_mul_f32 v[52:53], v[48:49], v[48:49]
	v_add_f32_e32 v16, v63, v16
	v_add_f32_e32 v16, v52, v16
	v_pk_mul_f32 v[54:55], v[50:51], v[50:51]
	v_add_f32_e32 v16, v53, v16
	v_add_f32_e32 v16, v54, v16
	v_pk_mul_f32 v[44:45], v[40:41], v[40:41]
	v_add_f32_e32 v16, v55, v16
	v_add_f32_e32 v16, v44, v16
	v_pk_mul_f32 v[46:47], v[42:43], v[42:43]
	v_add_f32_e32 v16, v45, v16
	v_add_f32_e32 v16, v46, v16
	v_pk_mul_f32 v[36:37], v[32:33], v[32:33]
	v_add_f32_e32 v16, v47, v16
	v_add_f32_e32 v16, v36, v16
	v_pk_mul_f32 v[38:39], v[34:35], v[34:35]
	v_add_f32_e32 v16, v37, v16
	v_add_f32_e32 v16, v38, v16
	v_pk_mul_f32 v[28:29], v[24:25], v[24:25]
	v_add_f32_e32 v16, v39, v16
	v_add_f32_e32 v16, v28, v16
	v_pk_mul_f32 v[30:31], v[26:27], v[26:27]
	v_add_f32_e32 v16, v29, v16
	v_add_f32_e32 v16, v30, v16
	v_pk_mul_f32 v[12:13], v[10:11], v[10:11]
	v_add_f32_e32 v16, v31, v16
	v_add_f32_e32 v12, v12, v16
	v_pk_mul_f32 v[22:23], v[18:19], v[18:19]
	v_add_f32_e32 v12, v13, v12
	v_add_f32_e32 v12, v22, v12
	v_pk_mul_f32 v[14:15], v[0:1], v[0:1]
	v_add_f32_e32 v12, v23, v12
	v_add_f32_e32 v12, v14, v12
	v_pk_mul_f32 v[72:73], v[4:5], v[4:5]
	v_add_f32_e32 v12, v15, v12
	v_add_f32_e32 v12, v72, v12
	v_add_f32_e32 v12, v73, v12
	ds_bpermute_b32 v13, v187, v12
	s_waitcnt vmcnt(1)
	v_and_b32_e32 v23, 0xffff0000, v75
	v_lshlrev_b32_e32 v20, 16, v74
	s_waitcnt lgkmcnt(0)
	v_add_f32_e32 v21, v12, v13
	ds_bpermute_b32 v22, v186, v21
	global_load_dwordx2 v[12:13], v[2:3], off offset:32
	global_load_dwordx2 v[14:15], v[2:3], off offset:64
	global_load_dwordx2 v[16:17], v[2:3], off offset:96
	s_waitcnt lgkmcnt(0)
	v_add_f32_e32 v21, v21, v22
	v_fmamk_f32 v21, v21, 0x3c000000, v212
	v_mul_f32_e32 v22, 0x4b800000, v21
	v_cmp_gt_f32_e32 vcc, s27, v21
	s_nop 1
	v_cndmask_b32_e32 v21, v21, v22, vcc
	v_rsq_f32_e32 v28, v21
	v_lshlrev_b32_e32 v22, 16, v75
	v_and_b32_e32 v21, 0xffff0000, v74
	v_mul_f32_e32 v29, 0x45800000, v28
	v_cndmask_b32_e32 v28, v28, v29, vcc
	v_mul_f32_e32 v28, 0x3ee34c56, v28
	v_pk_mul_f32 v[30:31], v[66:67], v[28:29] op_sel_hi:[1,0]
	v_pk_mul_f32 v[10:11], v[10:11], v[28:29] op_sel_hi:[1,0]
	s_waitcnt vmcnt(3)
	v_pk_mul_f32 v[8:9], v[8:9], v[30:31]
	v_pk_mul_f32 v[4:5], v[4:5], v[28:29] op_sel_hi:[1,0]
	v_pk_mul_f32 v[8:9], v[8:9], v[22:23]
	v_pk_mul_f32 v[22:23], v[64:65], v[28:29] op_sel_hi:[1,0]
	v_pk_mul_f32 v[0:1], v[0:1], v[28:29] op_sel_hi:[1,0]
	v_pk_mul_f32 v[6:7], v[6:7], v[22:23]
	v_pk_mul_f32 v[22:23], v[56:57], v[28:29] op_sel_hi:[1,0]
	v_pk_mul_f32 v[6:7], v[6:7], v[20:21]
	v_pk_mul_f32 v[20:21], v[58:59], v[28:29] op_sel_hi:[1,0]
	v_cvt_pk_bf16_f32 v6, v6, v7
	v_cvt_pk_bf16_f32 v7, v8, v9
	global_store_dwordx2 v[2:3], v[6:7], off
	global_load_dwordx4 v[6:9], v[146:147], off offset:576
	s_waitcnt vmcnt(4)
	v_lshlrev_b32_e32 v30, 16, v12
	v_and_b32_e32 v31, 0xffff0000, v12
	v_lshlrev_b32_e32 v12, 16, v13
	v_and_b32_e32 v13, 0xffff0000, v13
	s_waitcnt vmcnt(0)
	v_pk_mul_f32 v[8:9], v[8:9], v[20:21]
	v_pk_mul_f32 v[6:7], v[6:7], v[22:23]
	v_pk_mul_f32 v[8:9], v[8:9], v[12:13]
	v_pk_mul_f32 v[6:7], v[6:7], v[30:31]
	v_pk_mul_f32 v[12:13], v[50:51], v[28:29] op_sel_hi:[1,0]
	v_cvt_pk_bf16_f32 v6, v6, v7
	v_cvt_pk_bf16_f32 v7, v8, v9
	global_store_dwordx2 v[2:3], v[6:7], off offset:32
	global_load_dwordx4 v[6:9], v[146:147], off offset:640
	v_pk_mul_f32 v[20:21], v[48:49], v[28:29] op_sel_hi:[1,0]
	v_lshlrev_b32_e32 v22, 16, v14
	v_and_b32_e32 v23, 0xffff0000, v14
	v_lshlrev_b32_e32 v14, 16, v15
	v_and_b32_e32 v15, 0xffff0000, v15
	v_pk_mul_f32 v[30:31], v[32:33], v[28:29] op_sel_hi:[1,0]
	s_waitcnt vmcnt(0)
	v_pk_mul_f32 v[8:9], v[8:9], v[12:13]
	v_pk_mul_f32 v[6:7], v[6:7], v[20:21]
	v_pk_mul_f32 v[8:9], v[8:9], v[14:15]
	v_pk_mul_f32 v[6:7], v[6:7], v[22:23]
	v_pk_mul_f32 v[14:15], v[42:43], v[28:29] op_sel_hi:[1,0]
	v_cvt_pk_bf16_f32 v6, v6, v7
	v_cvt_pk_bf16_f32 v7, v8, v9
	global_store_dwordx2 v[2:3], v[6:7], off offset:64
	global_load_dwordx4 v[6:9], v[146:147], off offset:704
	s_nop 0
	global_load_dwordx2 v[12:13], v[2:3], off offset:128
	v_pk_mul_f32 v[20:21], v[40:41], v[28:29] op_sel_hi:[1,0]
	v_lshlrev_b32_e32 v22, 16, v16
	v_and_b32_e32 v23, 0xffff0000, v16
	v_lshlrev_b32_e32 v16, 16, v17
	v_and_b32_e32 v17, 0xffff0000, v17
	s_waitcnt vmcnt(1)
	v_pk_mul_f32 v[8:9], v[8:9], v[14:15]
	v_pk_mul_f32 v[6:7], v[6:7], v[20:21]
	v_pk_mul_f32 v[8:9], v[8:9], v[16:17]
	v_pk_mul_f32 v[6:7], v[6:7], v[22:23]
	v_pk_mul_f32 v[22:23], v[34:35], v[28:29] op_sel_hi:[1,0]
	v_cvt_pk_bf16_f32 v6, v6, v7
	v_cvt_pk_bf16_f32 v7, v8, v9
	global_store_dwordx2 v[2:3], v[6:7], off offset:96
	global_load_dwordx4 v[6:9], v[146:147], off offset:768
	s_nop 0
	global_load_dwordx2 v[14:15], v[2:3], off offset:160
	global_load_dwordx2 v[16:17], v[2:3], off offset:192
	global_load_dwordx2 v[20:21], v[2:3], off offset:224
	s_waitcnt vmcnt(5)
	v_lshlrev_b32_e32 v32, 16, v12
	v_and_b32_e32 v33, 0xffff0000, v12
	v_lshlrev_b32_e32 v12, 16, v13
	v_and_b32_e32 v13, 0xffff0000, v13
	s_waitcnt vmcnt(3)
	v_pk_mul_f32 v[8:9], v[8:9], v[22:23]
	v_pk_mul_f32 v[6:7], v[6:7], v[30:31]
	v_pk_mul_f32 v[8:9], v[8:9], v[12:13]
	v_pk_mul_f32 v[6:7], v[6:7], v[32:33]
	v_pk_mul_f32 v[12:13], v[26:27], v[28:29] op_sel_hi:[1,0]
	v_cvt_pk_bf16_f32 v6, v6, v7
	v_cvt_pk_bf16_f32 v7, v8, v9
	global_store_dwordx2 v[2:3], v[6:7], off offset:128
	global_load_dwordx4 v[6:9], v[146:147], off offset:832
	v_pk_mul_f32 v[22:23], v[24:25], v[28:29] op_sel_hi:[1,0]
	s_waitcnt vmcnt(4)
	v_lshlrev_b32_e32 v24, 16, v14
	v_and_b32_e32 v25, 0xffff0000, v14
	v_lshlrev_b32_e32 v14, 16, v15
	v_and_b32_e32 v15, 0xffff0000, v15
	s_waitcnt vmcnt(0)
	v_pk_mul_f32 v[8:9], v[8:9], v[12:13]
	v_pk_mul_f32 v[6:7], v[6:7], v[22:23]
	v_pk_mul_f32 v[8:9], v[8:9], v[14:15]
	v_pk_mul_f32 v[6:7], v[6:7], v[24:25]
	v_pk_mul_f32 v[12:13], v[18:19], v[28:29] op_sel_hi:[1,0]
	v_cvt_pk_bf16_f32 v6, v6, v7
	v_cvt_pk_bf16_f32 v7, v8, v9
	global_store_dwordx2 v[2:3], v[6:7], off offset:160
	global_load_dwordx4 v[6:9], v[146:147], off offset:896
	v_lshlrev_b32_e32 v14, 16, v16
	v_and_b32_e32 v15, 0xffff0000, v16
	v_lshlrev_b32_e32 v16, 16, v17
	v_and_b32_e32 v17, 0xffff0000, v17
	s_waitcnt vmcnt(0)
	v_pk_mul_f32 v[8:9], v[12:13], v[8:9]
	v_pk_mul_f32 v[6:7], v[10:11], v[6:7]
	v_pk_mul_f32 v[8:9], v[8:9], v[16:17]
	v_pk_mul_f32 v[6:7], v[6:7], v[14:15]
	v_lshlrev_b32_e32 v10, 16, v20
	v_cvt_pk_bf16_f32 v6, v6, v7
	v_cvt_pk_bf16_f32 v7, v8, v9
	global_store_dwordx2 v[2:3], v[6:7], off offset:192
	global_load_dwordx4 v[6:9], v[146:147], off offset:960
	v_and_b32_e32 v11, 0xffff0000, v20
	v_lshlrev_b32_e32 v12, 16, v21
	v_and_b32_e32 v13, 0xffff0000, v21
	s_waitcnt vmcnt(0)
	v_pk_mul_f32 v[4:5], v[4:5], v[8:9]
	v_pk_mul_f32 v[0:1], v[0:1], v[6:7]
	v_pk_mul_f32 v[4:5], v[4:5], v[12:13]
	v_pk_mul_f32 v[0:1], v[0:1], v[10:11]
	s_nop 0
	v_cvt_pk_bf16_f32 v0, v0, v1
	v_cvt_pk_bf16_f32 v1, v4, v5
	global_store_dwordx2 v[2:3], v[0:1], off offset:224
	s_cbranch_scc1 .LBB0_2252
